# GEMM K-loops: the s_setprio 0 / s_setprio 1 pair between the two 16-MFMA blocks of every segment removed (priority stays raised across the 32 MFMAs)
# speedup vs baseline: 1.0049x; 1.0049x over previous
.LBB0_111:
	s_cmp_lg_u32 s7, 0
	v_mov_b32_e32 v133, v137
	v_mov_b32_e32 v135, v137
	v_mov_b32_e32 v131, v137
	s_cbranch_scc0 .LBB0_125
	ds_read_b128 v[2:5], v148
	ds_read_b128 v[6:9], v148 offset:1024
	ds_read_b128 v[10:13], v148 offset:2048
	ds_read_b128 v[14:17], v148 offset:3072
	ds_read_b128 v[18:21], v149
	ds_read_b128 v[22:25], v149 offset:1024
	ds_read_b128 v[26:29], v149 offset:2048
	ds_read_b128 v[30:33], v149 offset:3072
	ds_read_b128 v[34:37], v150
	ds_read_b128 v[38:41], v150 offset:1024
	ds_read_b128 v[42:45], v150 offset:2048
	ds_read_b128 v[46:49], v150 offset:3072
	ds_read_b128 v[50:53], v150 offset:4096
	ds_read_b128 v[54:57], v150 offset:5120
	ds_read_b128 v[58:61], v150 offset:6144
	ds_read_b128 v[62:65], v150 offset:7168
	s_waitcnt vmcnt(24)
	s_waitcnt lgkmcnt(0)
	s_barrier
	s_setprio 1
	s_waitcnt lgkmcnt(0)
	v_mfma_f32_16x16x32_bf16 v[66:69], v[2:5], v[34:37], 0
	v_mfma_f32_16x16x32_bf16 v[70:73], v[10:13], v[34:37], 0
	v_mfma_f32_16x16x32_bf16 v[74:77], v[2:5], v[42:45], 0
	v_mfma_f32_16x16x32_bf16 v[78:81], v[10:13], v[42:45], 0
	v_mfma_f32_16x16x32_bf16 v[82:85], v[2:5], v[50:53], 0
	v_mfma_f32_16x16x32_bf16 v[86:89], v[10:13], v[50:53], 0
	v_mfma_f32_16x16x32_bf16 v[90:93], v[2:5], v[58:61], 0
	v_mfma_f32_16x16x32_bf16 v[94:97], v[10:13], v[58:61], 0
	v_mfma_f32_16x16x32_bf16 v[66:69], v[6:9], v[38:41], v[66:69]
	v_mfma_f32_16x16x32_bf16 v[70:73], v[14:17], v[38:41], v[70:73]
	v_mfma_f32_16x16x32_bf16 v[74:77], v[6:9], v[46:49], v[74:77]
	v_mfma_f32_16x16x32_bf16 v[78:81], v[14:17], v[46:49], v[78:81]
	v_mfma_f32_16x16x32_bf16 v[82:85], v[6:9], v[54:57], v[82:85]
	v_mfma_f32_16x16x32_bf16 v[86:89], v[14:17], v[54:57], v[86:89]
	v_mfma_f32_16x16x32_bf16 v[90:93], v[6:9], v[62:65], v[90:93]
	v_mfma_f32_16x16x32_bf16 v[98:101], v[14:17], v[62:65], v[94:97]
	v_mfma_f32_16x16x32_bf16 v[94:97], v[18:21], v[34:37], 0
	v_mfma_f32_16x16x32_bf16 v[34:37], v[26:29], v[34:37], 0
	v_mfma_f32_16x16x32_bf16 v[110:113], v[22:25], v[38:41], v[94:97]
	v_mfma_f32_16x16x32_bf16 v[34:37], v[30:33], v[38:41], v[34:37]
	v_mfma_f32_16x16x32_bf16 v[38:41], v[18:21], v[42:45], 0
	v_mfma_f32_16x16x32_bf16 v[42:45], v[26:29], v[42:45], 0
	v_mfma_f32_16x16x32_bf16 v[38:41], v[22:25], v[46:49], v[38:41]
	v_mfma_f32_16x16x32_bf16 v[46:49], v[30:33], v[46:49], v[42:45]
	v_mfma_f32_16x16x32_bf16 v[42:45], v[18:21], v[50:53], 0
	v_mfma_f32_16x16x32_bf16 v[118:121], v[22:25], v[54:57], v[42:45]
	v_mfma_f32_16x16x32_bf16 v[42:45], v[26:29], v[50:53], 0
	v_mfma_f32_16x16x32_bf16 v[240:243], v[30:33], v[54:57], v[42:45]
	v_mfma_f32_16x16x32_bf16 v[42:45], v[18:21], v[58:61], 0
	v_mfma_f32_16x16x32_bf16 v[122:125], v[22:25], v[62:65], v[42:45]
	v_mfma_f32_16x16x32_bf16 v[42:45], v[26:29], v[58:61], 0
	v_mfma_f32_16x16x32_bf16 v[58:61], v[30:33], v[62:65], v[42:45]
	s_setprio 0
	s_barrier
	v_lshl_add_u64 v[252:253], s[0:1], 0, v[132:133]
	s_add_i32 s7, s75, s59
	v_lshl_add_u64 v[142:143], v[252:253], 0, s[22:23]
	s_mov_b32 m0, s7
	s_nop 0
	ds_read_b128 v[42:45], v150 offset:16384
	ds_read_b128 v[50:53], v150 offset:17408
	ds_read_b128 v[62:65], v150 offset:18432
	ds_read_b128 v[94:97], v150 offset:19456
	ds_read_b128 v[102:105], v150 offset:20480
	ds_read_b128 v[106:109], v150 offset:21504
	ds_read_b128 v[114:117], v150 offset:22528
	ds_read_b128 v[126:129], v150 offset:23552
	global_load_lds_dwordx4 v[142:143], off
	s_add_i32 m0, s7, 0x2000
	v_lshl_add_u64 v[138:139], s[0:1], 0, v[136:137]
	s_add_u32 s44, s0, 0x10100
	v_lshl_add_u64 v[142:143], v[138:139], 0, s[22:23]
	s_addc_u32 s45, s1, 0
	s_add_i32 s7, s76, s59
	global_load_lds_dwordx4 v[142:143], off
	s_mov_b32 m0, s7
	v_lshl_add_u64 v[140:141], s[4:5], 0, v[130:131]
	global_load_lds_dwordx4 v132, s[44:45]
	s_add_i32 m0, s7, 0x2000
	v_lshl_add_u64 v[142:143], v[140:141], 0, s[22:23]
	global_load_lds_dwordx4 v136, s[44:45]
	s_mov_b32 m0, s60
	v_lshl_add_u64 v[54:55], s[4:5], 0, v[134:135]
	global_load_lds_dwordx4 v[142:143], off
	v_lshl_add_u64 v[56:57], v[54:55], 0, s[22:23]
	s_mov_b32 m0, s61
	s_nop 0
	global_load_lds_dwordx4 v[56:57], off
	s_waitcnt vmcnt(24)
	s_waitcnt lgkmcnt(0)
	s_barrier
	s_setprio 1
	s_waitcnt lgkmcnt(0)
	v_mfma_f32_16x16x32_bf16 v[142:145], v[2:5], v[42:45], 0
	v_mfma_f32_16x16x32_bf16 v[156:159], v[2:5], v[62:65], 0
	v_mfma_f32_16x16x32_bf16 v[164:167], v[2:5], v[102:105], 0
	v_mfma_f32_16x16x32_bf16 v[2:5], v[2:5], v[114:117], 0
	v_mfma_f32_16x16x32_bf16 v[172:175], v[6:9], v[126:129], v[2:5]
	v_mfma_f32_16x16x32_bf16 v[2:5], v[10:13], v[114:117], 0
	v_mfma_f32_16x16x32_bf16 v[152:155], v[10:13], v[42:45], 0
	v_mfma_f32_16x16x32_bf16 v[160:163], v[10:13], v[62:65], 0
	v_mfma_f32_16x16x32_bf16 v[168:171], v[10:13], v[102:105], 0
	v_mfma_f32_16x16x32_bf16 v[10:13], v[14:17], v[126:129], v[2:5]
	v_mfma_f32_16x16x32_bf16 v[142:145], v[6:9], v[50:53], v[142:145]
	v_mfma_f32_16x16x32_bf16 v[152:155], v[14:17], v[50:53], v[152:155]
	v_mfma_f32_16x16x32_bf16 v[156:159], v[6:9], v[94:97], v[156:159]
	v_mfma_f32_16x16x32_bf16 v[160:163], v[14:17], v[94:97], v[160:163]
	v_mfma_f32_16x16x32_bf16 v[164:167], v[6:9], v[106:109], v[164:167]
	v_mfma_f32_16x16x32_bf16 v[168:171], v[14:17], v[106:109], v[168:171]
	v_mfma_f32_16x16x32_bf16 v[2:5], v[18:21], v[42:45], 0
	v_mfma_f32_16x16x32_bf16 v[176:179], v[22:25], v[50:53], v[2:5]
	v_mfma_f32_16x16x32_bf16 v[2:5], v[26:29], v[42:45], 0
	v_mfma_f32_16x16x32_bf16 v[180:183], v[30:33], v[50:53], v[2:5]
	v_mfma_f32_16x16x32_bf16 v[2:5], v[18:21], v[62:65], 0
	v_mfma_f32_16x16x32_bf16 v[184:187], v[22:25], v[94:97], v[2:5]
	v_mfma_f32_16x16x32_bf16 v[2:5], v[26:29], v[62:65], 0
	v_mfma_f32_16x16x32_bf16 v[188:191], v[30:33], v[94:97], v[2:5]
	v_mfma_f32_16x16x32_bf16 v[2:5], v[18:21], v[102:105], 0
	v_mfma_f32_16x16x32_bf16 v[192:195], v[22:25], v[106:109], v[2:5]
	v_mfma_f32_16x16x32_bf16 v[2:5], v[26:29], v[102:105], 0
	v_mfma_f32_16x16x32_bf16 v[196:199], v[30:33], v[106:109], v[2:5]
	v_mfma_f32_16x16x32_bf16 v[2:5], v[18:21], v[114:117], 0
	v_mfma_f32_16x16x32_bf16 v[22:25], v[22:25], v[126:129], v[2:5]
	v_mfma_f32_16x16x32_bf16 v[2:5], v[26:29], v[114:117], 0
	v_mfma_f32_16x16x32_bf16 v[200:203], v[30:33], v[126:129], v[2:5]
	s_setprio 0
	s_barrier
	s_add_i32 s7, 0, 0x18000
	s_nop 3
	v_add_u32_e32 v2, s7, v147
	s_add_i32 s14, 0, 0x1c000
	ds_read_b128 v[26:29], v2
	ds_read_b128 v[62:65], v2 offset:1024
	ds_read_b128 v[204:207], v2 offset:2048
	ds_read_b128 v[208:211], v2 offset:3072
	v_add_u32_e32 v2, s14, v147
	ds_read_b128 v[212:215], v2
	ds_read_b128 v[216:219], v2 offset:1024
	ds_read_b128 v[220:223], v2 offset:2048
	ds_read_b128 v[224:227], v2 offset:3072
	s_add_u32 s44, s4, 0x40100
	s_addc_u32 s45, s5, 0
	s_mov_b32 m0, s62
	ds_read_b128 v[2:5], v150 offset:32768
	ds_read_b128 v[6:9], v150 offset:33792
	ds_read_b128 v[14:17], v150 offset:34816
	ds_read_b128 v[18:21], v150 offset:35840
	ds_read_b128 v[126:129], v150 offset:36864
	ds_read_b128 v[228:231], v150 offset:37888
	ds_read_b128 v[232:235], v150 offset:38912
	ds_read_b128 v[236:239], v150 offset:39936
	global_load_lds_dwordx4 v130, s[44:45]
	s_mov_b32 m0, s63
	s_nop 0
	global_load_lds_dwordx4 v134, s[44:45]
	s_waitcnt vmcnt(24)
	s_waitcnt lgkmcnt(0)
	s_barrier
	s_setprio 1
	s_waitcnt lgkmcnt(0)
	v_mfma_f32_16x16x32_bf16 v[30:33], v[26:29], v[2:5], v[66:69]
	v_mfma_f32_16x16x32_bf16 v[114:117], v[62:65], v[6:9], v[30:33]
	v_mfma_f32_16x16x32_bf16 v[30:33], v[204:207], v[2:5], v[70:73]
	v_mfma_f32_16x16x32_bf16 v[106:109], v[208:211], v[6:9], v[30:33]
	v_mfma_f32_16x16x32_bf16 v[30:33], v[26:29], v[14:17], v[74:77]
	v_mfma_f32_16x16x32_bf16 v[102:105], v[62:65], v[18:21], v[30:33]
	v_mfma_f32_16x16x32_bf16 v[30:33], v[204:207], v[14:17], v[78:81]
	v_mfma_f32_16x16x32_bf16 v[94:97], v[208:211], v[18:21], v[30:33]
	v_mfma_f32_16x16x32_bf16 v[30:33], v[26:29], v[126:129], v[82:85]
	v_mfma_f32_16x16x32_bf16 v[82:85], v[62:65], v[228:231], v[30:33]
	v_mfma_f32_16x16x32_bf16 v[30:33], v[204:207], v[126:129], v[86:89]
	v_mfma_f32_16x16x32_bf16 v[74:77], v[208:211], v[228:231], v[30:33]
	v_mfma_f32_16x16x32_bf16 v[30:33], v[26:29], v[232:235], v[90:93]
	v_mfma_f32_16x16x32_bf16 v[70:73], v[62:65], v[236:239], v[30:33]
	v_mfma_f32_16x16x32_bf16 v[30:33], v[204:207], v[232:235], v[98:101]
	v_mfma_f32_16x16x32_bf16 v[66:69], v[208:211], v[236:239], v[30:33]
	v_mfma_f32_16x16x32_bf16 v[30:33], v[212:215], v[2:5], v[110:113]
	v_mfma_f32_16x16x32_bf16 v[2:5], v[220:223], v[2:5], v[34:37]
	v_mfma_f32_16x16x32_bf16 v[42:45], v[224:227], v[6:9], v[2:5]
	v_mfma_f32_16x16x32_bf16 v[2:5], v[212:215], v[14:17], v[38:41]
	v_mfma_f32_16x16x32_bf16 v[38:41], v[216:219], v[18:21], v[2:5]
	v_mfma_f32_16x16x32_bf16 v[2:5], v[220:223], v[14:17], v[46:49]
	v_mfma_f32_16x16x32_bf16 v[50:53], v[216:219], v[6:9], v[30:33]
	v_mfma_f32_16x16x32_bf16 v[30:33], v[224:227], v[18:21], v[2:5]
	v_mfma_f32_16x16x32_bf16 v[2:5], v[212:215], v[126:129], v[118:121]
	v_mfma_f32_16x16x32_bf16 v[18:21], v[216:219], v[228:231], v[2:5]
	v_mfma_f32_16x16x32_bf16 v[2:5], v[220:223], v[126:129], v[240:243]
	v_mfma_f32_16x16x32_bf16 v[14:17], v[224:227], v[228:231], v[2:5]
	v_mfma_f32_16x16x32_bf16 v[2:5], v[212:215], v[232:235], v[122:125]
	v_mfma_f32_16x16x32_bf16 v[6:9], v[216:219], v[236:239], v[2:5]
	v_mfma_f32_16x16x32_bf16 v[2:5], v[220:223], v[232:235], v[58:61]
	v_mfma_f32_16x16x32_bf16 v[2:5], v[224:227], v[236:239], v[2:5]
	s_setprio 0
	s_barrier
	s_add_i32 s7, s7, s59
	v_lshl_add_u64 v[56:57], v[252:253], 0, s[24:25]
	s_mov_b32 m0, s7
	ds_read_b128 v[34:37], v150 offset:49152
	ds_read_b128 v[46:49], v150 offset:50176
	ds_read_b128 v[228:231], v150 offset:51200
	ds_read_b128 v[232:235], v150 offset:52224
	ds_read_b128 v[236:239], v150 offset:53248
	ds_read_b128 v[240:243], v150 offset:54272
	ds_read_b128 v[244:247], v150 offset:55296
	ds_read_b128 v[248:251], v150 offset:56320
	global_load_lds_dwordx4 v[56:57], off
	s_add_i32 m0, s7, 0x2000
	s_add_u32 s44, s0, 0x10180
	v_lshl_add_u64 v[56:57], v[138:139], 0, s[24:25]
	s_addc_u32 s45, s1, 0
	s_add_i32 s7, s14, s59
	global_load_lds_dwordx4 v[56:57], off
	s_mov_b32 m0, s7
	v_lshl_add_u64 v[56:57], v[140:141], 0, s[24:25]
	global_load_lds_dwordx4 v132, s[44:45]
	s_add_i32 m0, s7, 0x2000
	v_lshl_add_u64 v[54:55], v[54:55], 0, s[24:25]
	global_load_lds_dwordx4 v136, s[44:45]
	s_mov_b32 m0, s65
	s_nop 0
	global_load_lds_dwordx4 v[56:57], off
	s_mov_b32 m0, s66
	s_nop 0
	global_load_lds_dwordx4 v[54:55], off
	s_waitcnt vmcnt(8)
	s_waitcnt lgkmcnt(0)
	s_barrier
	s_setprio 1
	s_waitcnt lgkmcnt(0)
	v_mfma_f32_16x16x32_bf16 v[54:57], v[26:29], v[34:37], v[142:145]
	v_mfma_f32_16x16x32_bf16 v[126:129], v[62:65], v[46:49], v[54:57]
	v_mfma_f32_16x16x32_bf16 v[54:57], v[204:207], v[34:37], v[152:155]
	v_mfma_f32_16x16x32_bf16 v[122:125], v[208:211], v[46:49], v[54:57]
	v_mfma_f32_16x16x32_bf16 v[54:57], v[26:29], v[228:231], v[156:159]
	v_mfma_f32_16x16x32_bf16 v[118:121], v[62:65], v[232:235], v[54:57]
	v_mfma_f32_16x16x32_bf16 v[54:57], v[204:207], v[228:231], v[160:163]
	v_mfma_f32_16x16x32_bf16 v[110:113], v[208:211], v[232:235], v[54:57]
	v_mfma_f32_16x16x32_bf16 v[54:57], v[26:29], v[236:239], v[164:167]
	v_mfma_f32_16x16x32_bf16 v[98:101], v[62:65], v[240:243], v[54:57]
	v_mfma_f32_16x16x32_bf16 v[54:57], v[204:207], v[236:239], v[168:171]
	v_mfma_f32_16x16x32_bf16 v[26:29], v[26:29], v[244:247], v[172:175]
	v_mfma_f32_16x16x32_bf16 v[10:13], v[204:207], v[244:247], v[10:13]
	v_mfma_f32_16x16x32_bf16 v[90:93], v[208:211], v[240:243], v[54:57]
	v_mfma_f32_16x16x32_bf16 v[86:89], v[62:65], v[248:251], v[26:29]
	v_mfma_f32_16x16x32_bf16 v[78:81], v[208:211], v[248:251], v[10:13]
	v_mfma_f32_16x16x32_bf16 v[10:13], v[212:215], v[34:37], v[176:179]
	v_mfma_f32_16x16x32_bf16 v[62:65], v[216:219], v[46:49], v[10:13]
	v_mfma_f32_16x16x32_bf16 v[10:13], v[220:223], v[34:37], v[180:183]
	v_mfma_f32_16x16x32_bf16 v[58:61], v[224:227], v[46:49], v[10:13]
	v_mfma_f32_16x16x32_bf16 v[10:13], v[212:215], v[228:231], v[184:187]
	v_mfma_f32_16x16x32_bf16 v[54:57], v[216:219], v[232:235], v[10:13]
	v_mfma_f32_16x16x32_bf16 v[10:13], v[220:223], v[228:231], v[188:191]
	v_mfma_f32_16x16x32_bf16 v[46:49], v[224:227], v[232:235], v[10:13]
	v_mfma_f32_16x16x32_bf16 v[10:13], v[212:215], v[236:239], v[192:195]
	v_mfma_f32_16x16x32_bf16 v[34:37], v[216:219], v[240:243], v[10:13]
	v_mfma_f32_16x16x32_bf16 v[10:13], v[220:223], v[236:239], v[196:199]
	v_mfma_f32_16x16x32_bf16 v[26:29], v[224:227], v[240:243], v[10:13]
	v_mfma_f32_16x16x32_bf16 v[10:13], v[212:215], v[244:247], v[22:25]
	v_mfma_f32_16x16x32_bf16 v[22:25], v[216:219], v[248:251], v[10:13]
	v_mfma_f32_16x16x32_bf16 v[10:13], v[220:223], v[244:247], v[200:203]
	v_mfma_f32_16x16x32_bf16 v[10:13], v[224:227], v[248:251], v[10:13]
	s_setprio 0
	s_barrier
	s_mov_b32 s14, 2
	s_cbranch_execnz .LBB0_114

.LBB0_115:
	ds_read_b128 v[152:155], v148
	ds_read_b128 v[156:159], v148 offset:1024
	ds_read_b128 v[160:163], v148 offset:2048
	ds_read_b128 v[164:167], v148 offset:3072
	ds_read_b128 v[168:171], v149
	ds_read_b128 v[172:175], v149 offset:1024
	ds_read_b128 v[176:179], v149 offset:2048
	ds_read_b128 v[180:183], v149 offset:3072
	s_add_u32 s4, s53, s14
	s_addc_u32 s5, s80, 0
	s_add_u32 s83, s81, s14
	s_addc_u32 s85, s82, 0
	s_cmp_eq_u32 s14, s0
	s_cselect_b32 s51, s7, s5
	s_cselect_b32 s50, s43, s4
	s_cselect_b32 s5, s41, s85
	s_cselect_b32 s4, s49, s83
	s_add_i32 s85, s60, 0xc000
	v_lshl_add_u64 v[138:139], v[142:143], 0, s[14:15]
	s_mov_b32 m0, s85
	s_add_i32 s83, s60, 0xe000
	ds_read_b128 v[184:187], v150
	ds_read_b128 v[188:191], v150 offset:1024
	ds_read_b128 v[192:195], v150 offset:2048
	ds_read_b128 v[196:199], v150 offset:3072
	ds_read_b128 v[200:203], v150 offset:4096
	ds_read_b128 v[204:207], v150 offset:5120
	ds_read_b128 v[208:211], v150 offset:6144
	ds_read_b128 v[212:215], v150 offset:7168
	global_load_lds_dwordx4 v[138:139], off
	v_lshl_add_u64 v[138:139], v[144:145], 0, s[14:15]
	s_mov_b32 m0, s83
	s_nop 0
	global_load_lds_dwordx4 v[138:139], off
	s_waitcnt vmcnt(8)
	s_waitcnt lgkmcnt(0)
	s_barrier
	s_setprio 1
	s_waitcnt lgkmcnt(0)
	v_mfma_f32_16x16x32_bf16 v[114:117], v[152:155], v[184:187], v[114:117]
	v_mfma_f32_16x16x32_bf16 v[106:109], v[160:163], v[184:187], v[106:109]
	v_mfma_f32_16x16x32_bf16 v[102:105], v[152:155], v[192:195], v[102:105]
	v_mfma_f32_16x16x32_bf16 v[94:97], v[160:163], v[192:195], v[94:97]
	v_mfma_f32_16x16x32_bf16 v[82:85], v[152:155], v[200:203], v[82:85]
	v_mfma_f32_16x16x32_bf16 v[74:77], v[160:163], v[200:203], v[74:77]
	v_mfma_f32_16x16x32_bf16 v[70:73], v[152:155], v[208:211], v[70:73]
	v_mfma_f32_16x16x32_bf16 v[66:69], v[160:163], v[208:211], v[66:69]
	v_mfma_f32_16x16x32_bf16 v[114:117], v[156:159], v[188:191], v[114:117]
	v_mfma_f32_16x16x32_bf16 v[106:109], v[164:167], v[188:191], v[106:109]
	v_mfma_f32_16x16x32_bf16 v[102:105], v[156:159], v[196:199], v[102:105]
	v_mfma_f32_16x16x32_bf16 v[94:97], v[164:167], v[196:199], v[94:97]
	v_mfma_f32_16x16x32_bf16 v[82:85], v[156:159], v[204:207], v[82:85]
	v_mfma_f32_16x16x32_bf16 v[74:77], v[164:167], v[204:207], v[74:77]
	v_mfma_f32_16x16x32_bf16 v[70:73], v[156:159], v[212:215], v[70:73]
	v_mfma_f32_16x16x32_bf16 v[66:69], v[164:167], v[212:215], v[66:69]
	v_mfma_f32_16x16x32_bf16 v[50:53], v[168:171], v[184:187], v[50:53]
	v_mfma_f32_16x16x32_bf16 v[42:45], v[176:179], v[184:187], v[42:45]
	v_mfma_f32_16x16x32_bf16 v[38:41], v[168:171], v[192:195], v[38:41]
	v_mfma_f32_16x16x32_bf16 v[30:33], v[176:179], v[192:195], v[30:33]
	v_mfma_f32_16x16x32_bf16 v[18:21], v[168:171], v[200:203], v[18:21]
	v_mfma_f32_16x16x32_bf16 v[14:17], v[176:179], v[200:203], v[14:17]
	v_mfma_f32_16x16x32_bf16 v[6:9], v[168:171], v[208:211], v[6:9]
	v_mfma_f32_16x16x32_bf16 v[2:5], v[176:179], v[208:211], v[2:5]
	v_mfma_f32_16x16x32_bf16 v[50:53], v[172:175], v[188:191], v[50:53]
	v_mfma_f32_16x16x32_bf16 v[42:45], v[180:183], v[188:191], v[42:45]
	v_mfma_f32_16x16x32_bf16 v[38:41], v[172:175], v[196:199], v[38:41]
	v_mfma_f32_16x16x32_bf16 v[30:33], v[180:183], v[196:199], v[30:33]
	v_mfma_f32_16x16x32_bf16 v[18:21], v[172:175], v[204:207], v[18:21]
	v_mfma_f32_16x16x32_bf16 v[14:17], v[180:183], v[204:207], v[14:17]
	v_mfma_f32_16x16x32_bf16 v[6:9], v[172:175], v[212:215], v[6:9]
	v_mfma_f32_16x16x32_bf16 v[2:5], v[180:183], v[212:215], v[2:5]
	s_setprio 0
	s_barrier
	s_add_i32 s86, s75, s59
	v_lshl_add_u64 v[138:139], s[4:5], 0, v[132:133]
	s_mov_b32 m0, s86
	ds_read_b128 v[184:187], v150 offset:16384
	ds_read_b128 v[188:191], v150 offset:17408
	ds_read_b128 v[192:195], v150 offset:18432
	ds_read_b128 v[196:199], v150 offset:19456
	ds_read_b128 v[200:203], v150 offset:20480
	ds_read_b128 v[204:207], v150 offset:21504
	ds_read_b128 v[208:211], v150 offset:22528
	ds_read_b128 v[212:215], v150 offset:23552
	global_load_lds_dwordx4 v[138:139], off
	s_add_i32 m0, s86, 0x2000
	s_add_u32 s86, s4, 0x10000
	v_lshl_add_u64 v[140:141], s[4:5], 0, v[136:137]
	s_addc_u32 s87, s5, 0
	s_add_i32 s88, s76, s59
	global_load_lds_dwordx4 v[140:141], off
	v_lshl_add_u64 v[216:217], s[86:87], 0, v[132:133]
	s_mov_b32 m0, s88
	v_lshl_add_u64 v[218:219], s[50:51], 0, v[134:135]
	global_load_lds_dwordx4 v[216:217], off
	v_lshl_add_u64 v[216:217], s[86:87], 0, v[136:137]
	s_add_i32 m0, s88, 0x2000
	s_nop 0
	global_load_lds_dwordx4 v[216:217], off
	v_lshl_add_u64 v[216:217], s[50:51], 0, v[130:131]
	s_mov_b32 m0, s60
	s_nop 0
	global_load_lds_dwordx4 v[216:217], off
	s_mov_b32 m0, s61
	s_nop 0
	global_load_lds_dwordx4 v[218:219], off
	s_waitcnt vmcnt(8)
	s_waitcnt lgkmcnt(0)
	s_barrier
	s_setprio 1
	s_waitcnt lgkmcnt(0)
	v_mfma_f32_16x16x32_bf16 v[126:129], v[152:155], v[184:187], v[126:129]
	v_mfma_f32_16x16x32_bf16 v[122:125], v[160:163], v[184:187], v[122:125]
	v_mfma_f32_16x16x32_bf16 v[118:121], v[152:155], v[192:195], v[118:121]
	v_mfma_f32_16x16x32_bf16 v[110:113], v[160:163], v[192:195], v[110:113]
	v_mfma_f32_16x16x32_bf16 v[98:101], v[152:155], v[200:203], v[98:101]
	v_mfma_f32_16x16x32_bf16 v[90:93], v[160:163], v[200:203], v[90:93]
	v_mfma_f32_16x16x32_bf16 v[86:89], v[152:155], v[208:211], v[86:89]
	v_mfma_f32_16x16x32_bf16 v[78:81], v[160:163], v[208:211], v[78:81]
	v_mfma_f32_16x16x32_bf16 v[126:129], v[156:159], v[188:191], v[126:129]
	v_mfma_f32_16x16x32_bf16 v[122:125], v[164:167], v[188:191], v[122:125]
	v_mfma_f32_16x16x32_bf16 v[118:121], v[156:159], v[196:199], v[118:121]
	v_mfma_f32_16x16x32_bf16 v[110:113], v[164:167], v[196:199], v[110:113]
	v_mfma_f32_16x16x32_bf16 v[98:101], v[156:159], v[204:207], v[98:101]
	v_mfma_f32_16x16x32_bf16 v[90:93], v[164:167], v[204:207], v[90:93]
	v_mfma_f32_16x16x32_bf16 v[86:89], v[156:159], v[212:215], v[86:89]
	v_mfma_f32_16x16x32_bf16 v[78:81], v[164:167], v[212:215], v[78:81]
	v_mfma_f32_16x16x32_bf16 v[62:65], v[168:171], v[184:187], v[62:65]
	v_mfma_f32_16x16x32_bf16 v[58:61], v[176:179], v[184:187], v[58:61]
	v_mfma_f32_16x16x32_bf16 v[54:57], v[168:171], v[192:195], v[54:57]
	v_mfma_f32_16x16x32_bf16 v[46:49], v[176:179], v[192:195], v[46:49]
	v_mfma_f32_16x16x32_bf16 v[34:37], v[168:171], v[200:203], v[34:37]
	v_mfma_f32_16x16x32_bf16 v[26:29], v[176:179], v[200:203], v[26:29]
	v_mfma_f32_16x16x32_bf16 v[22:25], v[168:171], v[208:211], v[22:25]
	v_mfma_f32_16x16x32_bf16 v[10:13], v[176:179], v[208:211], v[10:13]
	v_mfma_f32_16x16x32_bf16 v[62:65], v[172:175], v[188:191], v[62:65]
	v_mfma_f32_16x16x32_bf16 v[58:61], v[180:183], v[188:191], v[58:61]
	v_mfma_f32_16x16x32_bf16 v[54:57], v[172:175], v[196:199], v[54:57]
	v_mfma_f32_16x16x32_bf16 v[46:49], v[180:183], v[196:199], v[46:49]
	v_mfma_f32_16x16x32_bf16 v[34:37], v[172:175], v[204:207], v[34:37]
	v_mfma_f32_16x16x32_bf16 v[26:29], v[180:183], v[204:207], v[26:29]
	v_mfma_f32_16x16x32_bf16 v[22:25], v[172:175], v[212:215], v[22:25]
	v_mfma_f32_16x16x32_bf16 v[10:13], v[180:183], v[212:215], v[10:13]
	s_setprio 0
	s_barrier
	s_add_i32 s86, 0, 0x18000
	s_add_i32 s87, 0, 0x1c000
	v_add_u32_e32 v164, s86, v147
	v_add_u32_e32 v180, s87, v147
	ds_read_b128 v[152:155], v164
	ds_read_b128 v[156:159], v164 offset:1024
	ds_read_b128 v[160:163], v164 offset:2048
	ds_read_b128 v[164:167], v164 offset:3072
	ds_read_b128 v[168:171], v180
	ds_read_b128 v[172:175], v180 offset:1024
	ds_read_b128 v[176:179], v180 offset:2048
	ds_read_b128 v[180:183], v180 offset:3072
	s_add_u32 s50, s50, 0x40000
	s_addc_u32 s51, s51, 0
	s_mov_b32 m0, s62
	v_lshl_add_u64 v[220:221], s[50:51], 0, v[130:131]
	ds_read_b128 v[184:187], v150 offset:32768
	ds_read_b128 v[188:191], v150 offset:33792
	ds_read_b128 v[192:195], v150 offset:34816
	ds_read_b128 v[196:199], v150 offset:35840
	ds_read_b128 v[200:203], v150 offset:36864
	ds_read_b128 v[204:207], v150 offset:37888
	ds_read_b128 v[208:211], v150 offset:38912
	ds_read_b128 v[212:215], v150 offset:39936
	global_load_lds_dwordx4 v[220:221], off
	v_lshl_add_u64 v[220:221], s[50:51], 0, v[134:135]
	s_mov_b32 m0, s63
	s_nop 0
	global_load_lds_dwordx4 v[220:221], off
	s_waitcnt vmcnt(8)
	s_waitcnt lgkmcnt(0)
	s_barrier
	s_setprio 1
	s_waitcnt lgkmcnt(0)
	v_mfma_f32_16x16x32_bf16 v[114:117], v[152:155], v[184:187], v[114:117]
	v_mfma_f32_16x16x32_bf16 v[106:109], v[160:163], v[184:187], v[106:109]
	v_mfma_f32_16x16x32_bf16 v[102:105], v[152:155], v[192:195], v[102:105]
	v_mfma_f32_16x16x32_bf16 v[94:97], v[160:163], v[192:195], v[94:97]
	v_mfma_f32_16x16x32_bf16 v[82:85], v[152:155], v[200:203], v[82:85]
	v_mfma_f32_16x16x32_bf16 v[74:77], v[160:163], v[200:203], v[74:77]
	v_mfma_f32_16x16x32_bf16 v[70:73], v[152:155], v[208:211], v[70:73]
	v_mfma_f32_16x16x32_bf16 v[66:69], v[160:163], v[208:211], v[66:69]
	v_mfma_f32_16x16x32_bf16 v[114:117], v[156:159], v[188:191], v[114:117]
	v_mfma_f32_16x16x32_bf16 v[106:109], v[164:167], v[188:191], v[106:109]
	v_mfma_f32_16x16x32_bf16 v[102:105], v[156:159], v[196:199], v[102:105]
	v_mfma_f32_16x16x32_bf16 v[94:97], v[164:167], v[196:199], v[94:97]
	v_mfma_f32_16x16x32_bf16 v[82:85], v[156:159], v[204:207], v[82:85]
	v_mfma_f32_16x16x32_bf16 v[74:77], v[164:167], v[204:207], v[74:77]
	v_mfma_f32_16x16x32_bf16 v[70:73], v[156:159], v[212:215], v[70:73]
	v_mfma_f32_16x16x32_bf16 v[66:69], v[164:167], v[212:215], v[66:69]
	v_mfma_f32_16x16x32_bf16 v[50:53], v[168:171], v[184:187], v[50:53]
	v_mfma_f32_16x16x32_bf16 v[42:45], v[176:179], v[184:187], v[42:45]
	v_mfma_f32_16x16x32_bf16 v[38:41], v[168:171], v[192:195], v[38:41]
	v_mfma_f32_16x16x32_bf16 v[30:33], v[176:179], v[192:195], v[30:33]
	v_mfma_f32_16x16x32_bf16 v[18:21], v[168:171], v[200:203], v[18:21]
	v_mfma_f32_16x16x32_bf16 v[14:17], v[176:179], v[200:203], v[14:17]
	v_mfma_f32_16x16x32_bf16 v[6:9], v[168:171], v[208:211], v[6:9]
	v_mfma_f32_16x16x32_bf16 v[2:5], v[176:179], v[208:211], v[2:5]
	v_mfma_f32_16x16x32_bf16 v[50:53], v[172:175], v[188:191], v[50:53]
	v_mfma_f32_16x16x32_bf16 v[42:45], v[180:183], v[188:191], v[42:45]
	v_mfma_f32_16x16x32_bf16 v[38:41], v[172:175], v[196:199], v[38:41]
	v_mfma_f32_16x16x32_bf16 v[30:33], v[180:183], v[196:199], v[30:33]
	v_mfma_f32_16x16x32_bf16 v[18:21], v[172:175], v[204:207], v[18:21]
	v_mfma_f32_16x16x32_bf16 v[14:17], v[180:183], v[204:207], v[14:17]
	v_mfma_f32_16x16x32_bf16 v[6:9], v[172:175], v[212:215], v[6:9]
	v_mfma_f32_16x16x32_bf16 v[2:5], v[180:183], v[212:215], v[2:5]
	s_setprio 0
	s_barrier
	s_add_i32 s50, s86, s59
	v_lshl_add_u64 v[138:139], v[138:139], 0, s[18:19]
	s_mov_b32 m0, s50
	ds_read_b128 v[184:187], v150 offset:49152
	ds_read_b128 v[188:191], v150 offset:50176
	ds_read_b128 v[192:195], v150 offset:51200
	ds_read_b128 v[196:199], v150 offset:52224
	ds_read_b128 v[200:203], v150 offset:53248
	ds_read_b128 v[204:207], v150 offset:54272
	ds_read_b128 v[208:211], v150 offset:55296
	ds_read_b128 v[212:215], v150 offset:56320
	global_load_lds_dwordx4 v[138:139], off
	s_add_i32 m0, s50, 0x2000
	s_add_u32 s4, s4, 0x10080
	v_lshl_add_u64 v[138:139], v[140:141], 0, s[18:19]
	s_addc_u32 s5, s5, 0
	s_add_i32 s50, s87, s59
	global_load_lds_dwordx4 v[138:139], off
	v_lshl_add_u64 v[138:139], s[4:5], 0, v[132:133]
	s_mov_b32 m0, s50
	s_nop 0
	global_load_lds_dwordx4 v[138:139], off
	v_lshl_add_u64 v[138:139], s[4:5], 0, v[136:137]
	s_add_i32 m0, s50, 0x2000
	s_nop 0
	global_load_lds_dwordx4 v[138:139], off
	v_lshl_add_u64 v[138:139], v[216:217], 0, s[18:19]
	s_mov_b32 m0, s65
	s_nop 0
	global_load_lds_dwordx4 v[138:139], off
	v_lshl_add_u64 v[138:139], v[218:219], 0, s[18:19]
	s_mov_b32 m0, s66
	s_nop 0
	global_load_lds_dwordx4 v[138:139], off
	s_waitcnt vmcnt(8)
	s_waitcnt lgkmcnt(0)
	s_barrier
	s_setprio 1
	s_waitcnt lgkmcnt(0)
	v_mfma_f32_16x16x32_bf16 v[126:129], v[152:155], v[184:187], v[126:129]
	v_mfma_f32_16x16x32_bf16 v[122:125], v[160:163], v[184:187], v[122:125]
	v_mfma_f32_16x16x32_bf16 v[118:121], v[152:155], v[192:195], v[118:121]
	v_mfma_f32_16x16x32_bf16 v[110:113], v[160:163], v[192:195], v[110:113]
	v_mfma_f32_16x16x32_bf16 v[98:101], v[152:155], v[200:203], v[98:101]
	v_mfma_f32_16x16x32_bf16 v[90:93], v[160:163], v[200:203], v[90:93]
	v_mfma_f32_16x16x32_bf16 v[86:89], v[152:155], v[208:211], v[86:89]
	v_mfma_f32_16x16x32_bf16 v[78:81], v[160:163], v[208:211], v[78:81]
	v_mfma_f32_16x16x32_bf16 v[126:129], v[156:159], v[188:191], v[126:129]
	v_mfma_f32_16x16x32_bf16 v[122:125], v[164:167], v[188:191], v[122:125]
	v_mfma_f32_16x16x32_bf16 v[118:121], v[156:159], v[196:199], v[118:121]
	v_mfma_f32_16x16x32_bf16 v[110:113], v[164:167], v[196:199], v[110:113]
	v_mfma_f32_16x16x32_bf16 v[98:101], v[156:159], v[204:207], v[98:101]
	v_mfma_f32_16x16x32_bf16 v[90:93], v[164:167], v[204:207], v[90:93]
	v_mfma_f32_16x16x32_bf16 v[86:89], v[156:159], v[212:215], v[86:89]
	v_mfma_f32_16x16x32_bf16 v[78:81], v[164:167], v[212:215], v[78:81]
	v_mfma_f32_16x16x32_bf16 v[62:65], v[168:171], v[184:187], v[62:65]
	v_mfma_f32_16x16x32_bf16 v[58:61], v[176:179], v[184:187], v[58:61]
	v_mfma_f32_16x16x32_bf16 v[54:57], v[168:171], v[192:195], v[54:57]
	v_mfma_f32_16x16x32_bf16 v[46:49], v[176:179], v[192:195], v[46:49]
	v_mfma_f32_16x16x32_bf16 v[34:37], v[168:171], v[200:203], v[34:37]
	v_mfma_f32_16x16x32_bf16 v[26:29], v[176:179], v[200:203], v[26:29]
	v_mfma_f32_16x16x32_bf16 v[22:25], v[168:171], v[208:211], v[22:25]
	v_mfma_f32_16x16x32_bf16 v[10:13], v[176:179], v[208:211], v[10:13]
	v_mfma_f32_16x16x32_bf16 v[62:65], v[172:175], v[188:191], v[62:65]
	v_mfma_f32_16x16x32_bf16 v[58:61], v[180:183], v[188:191], v[58:61]
	v_mfma_f32_16x16x32_bf16 v[54:57], v[172:175], v[196:199], v[54:57]
	v_mfma_f32_16x16x32_bf16 v[46:49], v[180:183], v[196:199], v[46:49]
	v_mfma_f32_16x16x32_bf16 v[34:37], v[172:175], v[204:207], v[34:37]
	v_mfma_f32_16x16x32_bf16 v[26:29], v[180:183], v[204:207], v[26:29]
	v_mfma_f32_16x16x32_bf16 v[22:25], v[172:175], v[212:215], v[22:25]
	v_mfma_f32_16x16x32_bf16 v[10:13], v[180:183], v[212:215], v[10:13]
	s_setprio 0
	s_barrier
	s_add_i32 s52, s52, 2
	s_add_u32 s53, s53, 0x100
	s_addc_u32 s80, s80, 0
	s_add_u32 s81, s81, 0x100
	s_addc_u32 s82, s82, 0
	s_add_u32 s0, s0, 0xffffff00
	s_addc_u32 s1, s1, -1
	v_lshl_add_u64 v[142:143], v[142:143], 0, s[22:23]
	s_cmp_gt_u32 s52, 13
	v_lshl_add_u64 v[144:145], v[144:145], 0, s[22:23]
	s_cbranch_scc0 .LBB0_115
	s_add_u32 s0, s43, 0x40080
	s_addc_u32 s1, s7, 0
	s_mov_b32 m0, s85
	v_lshl_add_u64 v[138:139], s[0:1], 0, v[130:131]
	global_load_lds_dwordx4 v[138:139], off
	v_lshl_add_u64 v[138:139], s[0:1], 0, v[134:135]
	s_mov_b32 m0, s83
	s_and_b64 vcc, exec, s[20:21]
	global_load_lds_dwordx4 v[138:139], off
	s_cbranch_vccz .LBB0_118
	s_barrier

.LBB0_685:
	s_cmp_lg_u32 s5, 0
	v_mov_b32_e32 v137, v141
	v_mov_b32_e32 v139, v141
	v_mov_b32_e32 v135, v141
	s_cbranch_scc0 .LBB0_699
	ds_read_b128 v[2:5], v160
	ds_read_b128 v[6:9], v160 offset:1024
	ds_read_b128 v[10:13], v160 offset:2048
	ds_read_b128 v[14:17], v160 offset:3072
	ds_read_b128 v[18:21], v161
	ds_read_b128 v[22:25], v161 offset:1024
	ds_read_b128 v[26:29], v161 offset:2048
	ds_read_b128 v[30:33], v161 offset:3072
	ds_read_b128 v[34:37], v162
	ds_read_b128 v[38:41], v162 offset:1024
	ds_read_b128 v[42:45], v162 offset:2048
	ds_read_b128 v[46:49], v162 offset:3072
	ds_read_b128 v[50:53], v162 offset:4096
	ds_read_b128 v[54:57], v162 offset:5120
	ds_read_b128 v[58:61], v162 offset:6144
	ds_read_b128 v[62:65], v162 offset:7168
	s_waitcnt vmcnt(24)
	s_waitcnt lgkmcnt(0)
	s_barrier
	s_setprio 1
	s_waitcnt lgkmcnt(0)
	v_mfma_f32_16x16x32_bf16 v[90:93], v[2:5], v[58:61], 0
	v_mfma_f32_16x16x32_bf16 v[66:69], v[2:5], v[34:37], 0
	v_mfma_f32_16x16x32_bf16 v[70:73], v[10:13], v[34:37], 0
	v_mfma_f32_16x16x32_bf16 v[74:77], v[2:5], v[42:45], 0
	v_mfma_f32_16x16x32_bf16 v[78:81], v[10:13], v[42:45], 0
	v_mfma_f32_16x16x32_bf16 v[82:85], v[2:5], v[50:53], 0
	v_mfma_f32_16x16x32_bf16 v[86:89], v[10:13], v[50:53], 0
	v_mfma_f32_16x16x32_bf16 v[98:101], v[6:9], v[62:65], v[90:93]
	v_mfma_f32_16x16x32_bf16 v[90:93], v[10:13], v[58:61], 0
	v_mfma_f32_16x16x32_bf16 v[66:69], v[6:9], v[38:41], v[66:69]
	v_mfma_f32_16x16x32_bf16 v[70:73], v[14:17], v[38:41], v[70:73]
	v_mfma_f32_16x16x32_bf16 v[74:77], v[6:9], v[46:49], v[74:77]
	v_mfma_f32_16x16x32_bf16 v[78:81], v[14:17], v[46:49], v[78:81]
	v_mfma_f32_16x16x32_bf16 v[82:85], v[6:9], v[54:57], v[82:85]
	v_mfma_f32_16x16x32_bf16 v[86:89], v[14:17], v[54:57], v[86:89]
	v_mfma_f32_16x16x32_bf16 v[102:105], v[14:17], v[62:65], v[90:93]
	v_mfma_f32_16x16x32_bf16 v[90:93], v[18:21], v[34:37], 0
	v_mfma_f32_16x16x32_bf16 v[34:37], v[26:29], v[34:37], 0
	v_mfma_f32_16x16x32_bf16 v[114:117], v[22:25], v[38:41], v[90:93]
	v_mfma_f32_16x16x32_bf16 v[34:37], v[30:33], v[38:41], v[34:37]
	v_mfma_f32_16x16x32_bf16 v[38:41], v[18:21], v[42:45], 0
	v_mfma_f32_16x16x32_bf16 v[42:45], v[26:29], v[42:45], 0
	v_mfma_f32_16x16x32_bf16 v[38:41], v[22:25], v[46:49], v[38:41]
	v_mfma_f32_16x16x32_bf16 v[42:45], v[30:33], v[46:49], v[42:45]
	v_mfma_f32_16x16x32_bf16 v[46:49], v[18:21], v[50:53], 0
	v_mfma_f32_16x16x32_bf16 v[50:53], v[26:29], v[50:53], 0
	v_mfma_f32_16x16x32_bf16 v[46:49], v[22:25], v[54:57], v[46:49]
	v_mfma_f32_16x16x32_bf16 v[50:53], v[30:33], v[54:57], v[50:53]
	v_mfma_f32_16x16x32_bf16 v[54:57], v[18:21], v[58:61], 0
	v_mfma_f32_16x16x32_bf16 v[58:61], v[26:29], v[58:61], 0
	v_mfma_f32_16x16x32_bf16 v[54:57], v[22:25], v[62:65], v[54:57]
	v_mfma_f32_16x16x32_bf16 v[58:61], v[30:33], v[62:65], v[58:61]
	s_setprio 0
	s_barrier
	v_lshl_add_u64 v[244:245], s[0:1], 0, v[136:137]
	s_add_i32 s5, s69, s55
	v_lshl_add_u64 v[130:131], v[244:245], 0, s[18:19]
	s_mov_b32 m0, s5
	ds_read_b128 v[62:65], v162 offset:16384
	ds_read_b128 v[90:93], v162 offset:17408
	ds_read_b128 v[94:97], v162 offset:18432
	ds_read_b128 v[106:109], v162 offset:19456
	ds_read_b128 v[110:113], v162 offset:20480
	ds_read_b128 v[118:121], v162 offset:21504
	ds_read_b128 v[122:125], v162 offset:22528
	ds_read_b128 v[126:129], v162 offset:23552
	global_load_lds_dwordx4 v[130:131], off
	s_add_i32 m0, s5, 0x2000
	v_lshl_add_u64 v[246:247], s[0:1], 0, v[140:141]
	s_add_u32 s44, s0, 0x40100
	v_lshl_add_u64 v[130:131], v[246:247], 0, s[18:19]
	s_addc_u32 s45, s1, 0
	s_add_i32 s5, s70, s55
	global_load_lds_dwordx4 v[130:131], off
	s_mov_b32 m0, s5
	v_lshl_add_u64 v[248:249], s[48:49], 0, v[134:135]
	global_load_lds_dwordx4 v136, s[44:45]
	s_add_i32 m0, s5, 0x2000
	v_lshl_add_u64 v[130:131], v[248:249], 0, s[18:19]
	global_load_lds_dwordx4 v140, s[44:45]
	s_mov_b32 m0, s56
	v_lshl_add_u64 v[250:251], s[48:49], 0, v[138:139]
	global_load_lds_dwordx4 v[130:131], off
	v_lshl_add_u64 v[130:131], v[250:251], 0, s[18:19]
	s_mov_b32 m0, s57
	s_nop 0
	global_load_lds_dwordx4 v[130:131], off
	s_waitcnt vmcnt(24)
	s_waitcnt lgkmcnt(0)
	s_barrier
	s_setprio 1
	s_waitcnt lgkmcnt(0)
	v_mfma_f32_16x16x32_bf16 v[130:133], v[2:5], v[62:65], 0
	v_mfma_f32_16x16x32_bf16 v[150:153], v[2:5], v[94:97], 0
	v_mfma_f32_16x16x32_bf16 v[164:167], v[2:5], v[110:113], 0
	v_mfma_f32_16x16x32_bf16 v[2:5], v[2:5], v[122:125], 0
	v_mfma_f32_16x16x32_bf16 v[172:175], v[6:9], v[126:129], v[2:5]
	v_mfma_f32_16x16x32_bf16 v[2:5], v[10:13], v[122:125], 0
	v_mfma_f32_16x16x32_bf16 v[146:149], v[10:13], v[62:65], 0
	v_mfma_f32_16x16x32_bf16 v[154:157], v[10:13], v[94:97], 0
	v_mfma_f32_16x16x32_bf16 v[168:171], v[10:13], v[110:113], 0
	v_mfma_f32_16x16x32_bf16 v[10:13], v[14:17], v[126:129], v[2:5]
	v_mfma_f32_16x16x32_bf16 v[130:133], v[6:9], v[90:93], v[130:133]
	v_mfma_f32_16x16x32_bf16 v[146:149], v[14:17], v[90:93], v[146:149]
	v_mfma_f32_16x16x32_bf16 v[150:153], v[6:9], v[106:109], v[150:153]
	v_mfma_f32_16x16x32_bf16 v[154:157], v[14:17], v[106:109], v[154:157]
	v_mfma_f32_16x16x32_bf16 v[164:167], v[6:9], v[118:121], v[164:167]
	v_mfma_f32_16x16x32_bf16 v[168:171], v[14:17], v[118:121], v[168:171]
	v_mfma_f32_16x16x32_bf16 v[2:5], v[18:21], v[62:65], 0
	v_mfma_f32_16x16x32_bf16 v[14:17], v[22:25], v[90:93], v[2:5]
	v_mfma_f32_16x16x32_bf16 v[2:5], v[26:29], v[62:65], 0
	v_mfma_f32_16x16x32_bf16 v[176:179], v[30:33], v[90:93], v[2:5]
	v_mfma_f32_16x16x32_bf16 v[2:5], v[18:21], v[94:97], 0
	v_mfma_f32_16x16x32_bf16 v[180:183], v[22:25], v[106:109], v[2:5]
	v_mfma_f32_16x16x32_bf16 v[2:5], v[26:29], v[94:97], 0
	v_mfma_f32_16x16x32_bf16 v[184:187], v[30:33], v[106:109], v[2:5]
	v_mfma_f32_16x16x32_bf16 v[2:5], v[18:21], v[110:113], 0
	v_mfma_f32_16x16x32_bf16 v[188:191], v[22:25], v[118:121], v[2:5]
	v_mfma_f32_16x16x32_bf16 v[2:5], v[26:29], v[110:113], 0
	v_mfma_f32_16x16x32_bf16 v[192:195], v[30:33], v[118:121], v[2:5]
	v_mfma_f32_16x16x32_bf16 v[2:5], v[18:21], v[122:125], 0
	v_mfma_f32_16x16x32_bf16 v[196:199], v[22:25], v[126:129], v[2:5]
	v_mfma_f32_16x16x32_bf16 v[2:5], v[26:29], v[122:125], 0
	v_mfma_f32_16x16x32_bf16 v[26:29], v[30:33], v[126:129], v[2:5]
	s_setprio 0
	s_barrier
	s_add_i32 s5, 0, 0x18000
	s_nop 3
	v_add_u32_e32 v2, s5, v159
	s_add_i32 s10, 0, 0x1c000
	ds_read_b128 v[18:21], v2
	ds_read_b128 v[22:25], v2 offset:1024
	ds_read_b128 v[30:33], v2 offset:2048
	ds_read_b128 v[200:203], v2 offset:3072
	v_add_u32_e32 v2, s10, v159
	ds_read_b128 v[204:207], v2
	ds_read_b128 v[208:211], v2 offset:1024
	ds_read_b128 v[212:215], v2 offset:2048
	ds_read_b128 v[216:219], v2 offset:3072
	s_add_u32 s44, s48, 0x40100
	s_addc_u32 s45, s49, 0
	s_mov_b32 m0, s58
	ds_read_b128 v[2:5], v162 offset:32768
	ds_read_b128 v[6:9], v162 offset:33792
	ds_read_b128 v[62:65], v162 offset:34816
	ds_read_b128 v[220:223], v162 offset:35840
	ds_read_b128 v[224:227], v162 offset:36864
	ds_read_b128 v[228:231], v162 offset:37888
	ds_read_b128 v[232:235], v162 offset:38912
	ds_read_b128 v[236:239], v162 offset:39936
	global_load_lds_dwordx4 v134, s[44:45]
	s_mov_b32 m0, s59
	s_nop 0
	global_load_lds_dwordx4 v138, s[44:45]
	s_waitcnt vmcnt(24)
	s_waitcnt lgkmcnt(0)
	s_barrier
	s_setprio 1
	s_waitcnt lgkmcnt(0)
	v_mfma_f32_16x16x32_bf16 v[66:69], v[18:21], v[2:5], v[66:69]
	v_mfma_f32_16x16x32_bf16 v[126:129], v[22:25], v[6:9], v[66:69]
	v_mfma_f32_16x16x32_bf16 v[66:69], v[30:33], v[2:5], v[70:73]
	v_mfma_f32_16x16x32_bf16 v[122:125], v[200:203], v[6:9], v[66:69]
	v_mfma_f32_16x16x32_bf16 v[66:69], v[18:21], v[62:65], v[74:77]
	v_mfma_f32_16x16x32_bf16 v[110:113], v[22:25], v[220:223], v[66:69]
	v_mfma_f32_16x16x32_bf16 v[66:69], v[30:33], v[62:65], v[78:81]
	v_mfma_f32_16x16x32_bf16 v[106:109], v[200:203], v[220:223], v[66:69]
	v_mfma_f32_16x16x32_bf16 v[66:69], v[18:21], v[224:227], v[82:85]
	v_mfma_f32_16x16x32_bf16 v[94:97], v[22:25], v[228:231], v[66:69]
	v_mfma_f32_16x16x32_bf16 v[66:69], v[30:33], v[224:227], v[86:89]
	v_mfma_f32_16x16x32_bf16 v[90:93], v[200:203], v[228:231], v[66:69]
	v_mfma_f32_16x16x32_bf16 v[66:69], v[18:21], v[232:235], v[98:101]
	v_mfma_f32_16x16x32_bf16 v[78:81], v[22:25], v[236:239], v[66:69]
	v_mfma_f32_16x16x32_bf16 v[66:69], v[30:33], v[232:235], v[102:105]
	v_mfma_f32_16x16x32_bf16 v[74:77], v[200:203], v[236:239], v[66:69]
	v_mfma_f32_16x16x32_bf16 v[66:69], v[204:207], v[2:5], v[114:117]
	v_mfma_f32_16x16x32_bf16 v[2:5], v[212:215], v[2:5], v[34:37]
	v_mfma_f32_16x16x32_bf16 v[114:117], v[216:219], v[6:9], v[2:5]
	v_mfma_f32_16x16x32_bf16 v[2:5], v[204:207], v[62:65], v[38:41]
	v_mfma_f32_16x16x32_bf16 v[102:105], v[208:211], v[220:223], v[2:5]
	v_mfma_f32_16x16x32_bf16 v[2:5], v[212:215], v[62:65], v[42:45]
	v_mfma_f32_16x16x32_bf16 v[98:101], v[216:219], v[220:223], v[2:5]
	v_mfma_f32_16x16x32_bf16 v[2:5], v[204:207], v[224:227], v[46:49]
	v_mfma_f32_16x16x32_bf16 v[86:89], v[208:211], v[228:231], v[2:5]
	v_mfma_f32_16x16x32_bf16 v[2:5], v[212:215], v[224:227], v[50:53]
	v_mfma_f32_16x16x32_bf16 v[82:85], v[216:219], v[228:231], v[2:5]
	v_mfma_f32_16x16x32_bf16 v[2:5], v[204:207], v[232:235], v[54:57]
	v_mfma_f32_16x16x32_bf16 v[70:73], v[208:211], v[236:239], v[2:5]
	v_mfma_f32_16x16x32_bf16 v[2:5], v[212:215], v[232:235], v[58:61]
	v_mfma_f32_16x16x32_bf16 v[118:121], v[208:211], v[6:9], v[66:69]
	v_mfma_f32_16x16x32_bf16 v[66:69], v[216:219], v[236:239], v[2:5]
	s_setprio 0
	s_barrier
	s_add_i32 s5, s5, s55
	s_nop 2
	v_lshl_add_u64 v[2:3], v[244:245], 0, s[20:21]
	s_mov_b32 m0, s5
	ds_read_b128 v[34:37], v162 offset:49152
	ds_read_b128 v[38:41], v162 offset:50176
	ds_read_b128 v[220:223], v162 offset:51200
	ds_read_b128 v[224:227], v162 offset:52224
	ds_read_b128 v[228:231], v162 offset:53248
	ds_read_b128 v[232:235], v162 offset:54272
	ds_read_b128 v[236:239], v162 offset:55296
	ds_read_b128 v[240:243], v162 offset:56320
	global_load_lds_dwordx4 v[2:3], off
	s_add_i32 m0, s5, 0x2000
	s_add_u32 s44, s0, 0x40180
	v_lshl_add_u64 v[2:3], v[246:247], 0, s[20:21]
	s_addc_u32 s45, s1, 0
	s_add_i32 s5, s10, s55
	global_load_lds_dwordx4 v[2:3], off
	s_mov_b32 m0, s5
	v_lshl_add_u64 v[2:3], v[248:249], 0, s[20:21]
	global_load_lds_dwordx4 v136, s[44:45]
	s_add_i32 m0, s5, 0x2000
	s_nop 0
	global_load_lds_dwordx4 v140, s[44:45]
	s_mov_b32 m0, s64
	s_nop 0
	global_load_lds_dwordx4 v[2:3], off
	v_lshl_add_u64 v[2:3], v[250:251], 0, s[20:21]
	s_mov_b32 m0, s65
	s_nop 0
	global_load_lds_dwordx4 v[2:3], off
	s_waitcnt vmcnt(8)
	s_waitcnt lgkmcnt(0)
	s_barrier
	s_setprio 1
	s_waitcnt lgkmcnt(0)
	v_mfma_f32_16x16x32_bf16 v[2:5], v[18:21], v[34:37], v[130:133]
	v_mfma_f32_16x16x32_bf16 v[62:65], v[22:25], v[38:41], v[2:5]
	v_mfma_f32_16x16x32_bf16 v[2:5], v[30:33], v[34:37], v[146:149]
	v_mfma_f32_16x16x32_bf16 v[58:61], v[200:203], v[38:41], v[2:5]
	v_mfma_f32_16x16x32_bf16 v[2:5], v[18:21], v[220:223], v[150:153]
	v_mfma_f32_16x16x32_bf16 v[46:49], v[22:25], v[224:227], v[2:5]
	v_mfma_f32_16x16x32_bf16 v[2:5], v[30:33], v[220:223], v[154:157]
	v_mfma_f32_16x16x32_bf16 v[42:45], v[200:203], v[224:227], v[2:5]
	v_mfma_f32_16x16x32_bf16 v[2:5], v[18:21], v[228:231], v[164:167]
	v_mfma_f32_16x16x32_bf16 v[6:9], v[22:25], v[232:235], v[2:5]
	v_mfma_f32_16x16x32_bf16 v[2:5], v[30:33], v[228:231], v[168:171]
	v_mfma_f32_16x16x32_bf16 v[18:21], v[18:21], v[236:239], v[172:175]
	v_mfma_f32_16x16x32_bf16 v[10:13], v[30:33], v[236:239], v[10:13]
	v_mfma_f32_16x16x32_bf16 v[2:5], v[200:203], v[232:235], v[2:5]
	v_mfma_f32_16x16x32_bf16 v[22:25], v[22:25], v[240:243], v[18:21]
	v_mfma_f32_16x16x32_bf16 v[18:21], v[200:203], v[240:243], v[10:13]
	v_mfma_f32_16x16x32_bf16 v[10:13], v[204:207], v[34:37], v[14:17]
	v_mfma_f32_16x16x32_bf16 v[54:57], v[208:211], v[38:41], v[10:13]
	v_mfma_f32_16x16x32_bf16 v[10:13], v[212:215], v[34:37], v[176:179]
	v_mfma_f32_16x16x32_bf16 v[50:53], v[216:219], v[38:41], v[10:13]
	v_mfma_f32_16x16x32_bf16 v[10:13], v[204:207], v[220:223], v[180:183]
	v_mfma_f32_16x16x32_bf16 v[38:41], v[208:211], v[224:227], v[10:13]
	v_mfma_f32_16x16x32_bf16 v[10:13], v[212:215], v[220:223], v[184:187]
	v_mfma_f32_16x16x32_bf16 v[34:37], v[216:219], v[224:227], v[10:13]
	v_mfma_f32_16x16x32_bf16 v[10:13], v[204:207], v[228:231], v[188:191]
	v_mfma_f32_16x16x32_bf16 v[14:17], v[208:211], v[232:235], v[10:13]
	v_mfma_f32_16x16x32_bf16 v[10:13], v[212:215], v[228:231], v[192:195]
	v_mfma_f32_16x16x32_bf16 v[30:33], v[204:207], v[236:239], v[196:199]
	v_mfma_f32_16x16x32_bf16 v[26:29], v[212:215], v[236:239], v[26:29]
	v_mfma_f32_16x16x32_bf16 v[10:13], v[216:219], v[232:235], v[10:13]
	v_mfma_f32_16x16x32_bf16 v[30:33], v[208:211], v[240:243], v[30:33]
	v_mfma_f32_16x16x32_bf16 v[26:29], v[216:219], v[240:243], v[26:29]
	s_setprio 0
	s_barrier
	s_mov_b32 s10, 2
	s_cbranch_execnz .LBB0_688

.LBB0_689:
	ds_read_b128 v[146:149], v160
	ds_read_b128 v[150:153], v160 offset:1024
	ds_read_b128 v[154:157], v160 offset:2048
	ds_read_b128 v[164:167], v160 offset:3072
	ds_read_b128 v[168:171], v161
	ds_read_b128 v[172:175], v161 offset:1024
	ds_read_b128 v[176:179], v161 offset:2048
	ds_read_b128 v[180:183], v161 offset:3072
	s_add_u32 s48, s81, s10
	s_addc_u32 s49, s82, 0
	s_add_u32 s85, s83, s10
	s_addc_u32 s86, s84, 0
	s_cmp_eq_u32 s10, s0
	s_cselect_b32 s51, s5, s49
	s_cselect_b32 s50, s43, s48
	s_cselect_b32 s49, s41, s86
	s_cselect_b32 s48, s79, s85
	s_add_i32 s86, s56, 0xc000
	v_lshl_add_u64 v[216:217], v[130:131], 0, s[10:11]
	s_mov_b32 m0, s86
	s_add_i32 s85, s56, 0xe000
	ds_read_b128 v[184:187], v162
	ds_read_b128 v[188:191], v162 offset:1024
	ds_read_b128 v[192:195], v162 offset:2048
	ds_read_b128 v[196:199], v162 offset:3072
	ds_read_b128 v[200:203], v162 offset:4096
	ds_read_b128 v[204:207], v162 offset:5120
	ds_read_b128 v[208:211], v162 offset:6144
	ds_read_b128 v[212:215], v162 offset:7168
	global_load_lds_dwordx4 v[216:217], off
	v_lshl_add_u64 v[216:217], v[132:133], 0, s[10:11]
	s_mov_b32 m0, s85
	s_nop 0
	global_load_lds_dwordx4 v[216:217], off
	s_waitcnt vmcnt(8)
	s_waitcnt lgkmcnt(0)
	s_barrier
	s_setprio 1
	s_waitcnt lgkmcnt(0)
	v_mfma_f32_16x16x32_bf16 v[126:129], v[146:149], v[184:187], v[126:129]
	v_mfma_f32_16x16x32_bf16 v[122:125], v[154:157], v[184:187], v[122:125]
	v_mfma_f32_16x16x32_bf16 v[110:113], v[146:149], v[192:195], v[110:113]
	v_mfma_f32_16x16x32_bf16 v[106:109], v[154:157], v[192:195], v[106:109]
	v_mfma_f32_16x16x32_bf16 v[94:97], v[146:149], v[200:203], v[94:97]
	v_mfma_f32_16x16x32_bf16 v[90:93], v[154:157], v[200:203], v[90:93]
	v_mfma_f32_16x16x32_bf16 v[78:81], v[146:149], v[208:211], v[78:81]
	v_mfma_f32_16x16x32_bf16 v[74:77], v[154:157], v[208:211], v[74:77]
	v_mfma_f32_16x16x32_bf16 v[126:129], v[150:153], v[188:191], v[126:129]
	v_mfma_f32_16x16x32_bf16 v[122:125], v[164:167], v[188:191], v[122:125]
	v_mfma_f32_16x16x32_bf16 v[110:113], v[150:153], v[196:199], v[110:113]
	v_mfma_f32_16x16x32_bf16 v[106:109], v[164:167], v[196:199], v[106:109]
	v_mfma_f32_16x16x32_bf16 v[94:97], v[150:153], v[204:207], v[94:97]
	v_mfma_f32_16x16x32_bf16 v[90:93], v[164:167], v[204:207], v[90:93]
	v_mfma_f32_16x16x32_bf16 v[78:81], v[150:153], v[212:215], v[78:81]
	v_mfma_f32_16x16x32_bf16 v[74:77], v[164:167], v[212:215], v[74:77]
	v_mfma_f32_16x16x32_bf16 v[118:121], v[168:171], v[184:187], v[118:121]
	v_mfma_f32_16x16x32_bf16 v[114:117], v[176:179], v[184:187], v[114:117]
	v_mfma_f32_16x16x32_bf16 v[102:105], v[168:171], v[192:195], v[102:105]
	v_mfma_f32_16x16x32_bf16 v[98:101], v[176:179], v[192:195], v[98:101]
	v_mfma_f32_16x16x32_bf16 v[86:89], v[168:171], v[200:203], v[86:89]
	v_mfma_f32_16x16x32_bf16 v[82:85], v[176:179], v[200:203], v[82:85]
	v_mfma_f32_16x16x32_bf16 v[70:73], v[168:171], v[208:211], v[70:73]
	v_mfma_f32_16x16x32_bf16 v[66:69], v[176:179], v[208:211], v[66:69]
	v_mfma_f32_16x16x32_bf16 v[118:121], v[172:175], v[188:191], v[118:121]
	v_mfma_f32_16x16x32_bf16 v[114:117], v[180:183], v[188:191], v[114:117]
	v_mfma_f32_16x16x32_bf16 v[102:105], v[172:175], v[196:199], v[102:105]
	v_mfma_f32_16x16x32_bf16 v[98:101], v[180:183], v[196:199], v[98:101]
	v_mfma_f32_16x16x32_bf16 v[86:89], v[172:175], v[204:207], v[86:89]
	v_mfma_f32_16x16x32_bf16 v[82:85], v[180:183], v[204:207], v[82:85]
	v_mfma_f32_16x16x32_bf16 v[70:73], v[172:175], v[212:215], v[70:73]
	v_mfma_f32_16x16x32_bf16 v[66:69], v[180:183], v[212:215], v[66:69]
	s_setprio 0
	s_barrier
	s_add_i32 s87, s69, s55
	v_lshl_add_u64 v[216:217], s[48:49], 0, v[136:137]
	s_mov_b32 m0, s87
	ds_read_b128 v[184:187], v162 offset:16384
	ds_read_b128 v[188:191], v162 offset:17408
	ds_read_b128 v[192:195], v162 offset:18432
	ds_read_b128 v[196:199], v162 offset:19456
	ds_read_b128 v[200:203], v162 offset:20480
	ds_read_b128 v[204:207], v162 offset:21504
	ds_read_b128 v[208:211], v162 offset:22528
	ds_read_b128 v[212:215], v162 offset:23552
	global_load_lds_dwordx4 v[216:217], off
	s_add_i32 m0, s87, 0x2000
	s_add_u32 s88, s48, 0x40000
	v_lshl_add_u64 v[218:219], s[48:49], 0, v[140:141]
	s_addc_u32 s89, s49, 0
	s_add_i32 s87, s70, s55
	global_load_lds_dwordx4 v[218:219], off
	v_lshl_add_u64 v[220:221], s[88:89], 0, v[136:137]
	s_mov_b32 m0, s87
	v_lshl_add_u64 v[222:223], s[50:51], 0, v[138:139]
	global_load_lds_dwordx4 v[220:221], off
	v_lshl_add_u64 v[220:221], s[88:89], 0, v[140:141]
	s_add_i32 m0, s87, 0x2000
	s_nop 0
	global_load_lds_dwordx4 v[220:221], off
	v_lshl_add_u64 v[220:221], s[50:51], 0, v[134:135]
	s_mov_b32 m0, s56
	s_nop 0
	global_load_lds_dwordx4 v[220:221], off
	s_mov_b32 m0, s57
	s_nop 0
	global_load_lds_dwordx4 v[222:223], off
	s_waitcnt vmcnt(8)
	s_waitcnt lgkmcnt(0)
	s_barrier
	s_setprio 1
	s_waitcnt lgkmcnt(0)
	v_mfma_f32_16x16x32_bf16 v[62:65], v[146:149], v[184:187], v[62:65]
	v_mfma_f32_16x16x32_bf16 v[58:61], v[154:157], v[184:187], v[58:61]
	v_mfma_f32_16x16x32_bf16 v[46:49], v[146:149], v[192:195], v[46:49]
	v_mfma_f32_16x16x32_bf16 v[42:45], v[154:157], v[192:195], v[42:45]
	v_mfma_f32_16x16x32_bf16 v[6:9], v[146:149], v[200:203], v[6:9]
	v_mfma_f32_16x16x32_bf16 v[2:5], v[154:157], v[200:203], v[2:5]
	v_mfma_f32_16x16x32_bf16 v[22:25], v[146:149], v[208:211], v[22:25]
	v_mfma_f32_16x16x32_bf16 v[18:21], v[154:157], v[208:211], v[18:21]
	v_mfma_f32_16x16x32_bf16 v[62:65], v[150:153], v[188:191], v[62:65]
	v_mfma_f32_16x16x32_bf16 v[58:61], v[164:167], v[188:191], v[58:61]
	v_mfma_f32_16x16x32_bf16 v[46:49], v[150:153], v[196:199], v[46:49]
	v_mfma_f32_16x16x32_bf16 v[42:45], v[164:167], v[196:199], v[42:45]
	v_mfma_f32_16x16x32_bf16 v[6:9], v[150:153], v[204:207], v[6:9]
	v_mfma_f32_16x16x32_bf16 v[2:5], v[164:167], v[204:207], v[2:5]
	v_mfma_f32_16x16x32_bf16 v[22:25], v[150:153], v[212:215], v[22:25]
	v_mfma_f32_16x16x32_bf16 v[18:21], v[164:167], v[212:215], v[18:21]
	v_mfma_f32_16x16x32_bf16 v[54:57], v[168:171], v[184:187], v[54:57]
	v_mfma_f32_16x16x32_bf16 v[50:53], v[176:179], v[184:187], v[50:53]
	v_mfma_f32_16x16x32_bf16 v[38:41], v[168:171], v[192:195], v[38:41]
	v_mfma_f32_16x16x32_bf16 v[34:37], v[176:179], v[192:195], v[34:37]
	v_mfma_f32_16x16x32_bf16 v[14:17], v[168:171], v[200:203], v[14:17]
	v_mfma_f32_16x16x32_bf16 v[10:13], v[176:179], v[200:203], v[10:13]
	v_mfma_f32_16x16x32_bf16 v[30:33], v[168:171], v[208:211], v[30:33]
	v_mfma_f32_16x16x32_bf16 v[26:29], v[176:179], v[208:211], v[26:29]
	v_mfma_f32_16x16x32_bf16 v[54:57], v[172:175], v[188:191], v[54:57]
	v_mfma_f32_16x16x32_bf16 v[50:53], v[180:183], v[188:191], v[50:53]
	v_mfma_f32_16x16x32_bf16 v[38:41], v[172:175], v[196:199], v[38:41]
	v_mfma_f32_16x16x32_bf16 v[34:37], v[180:183], v[196:199], v[34:37]
	v_mfma_f32_16x16x32_bf16 v[14:17], v[172:175], v[204:207], v[14:17]
	v_mfma_f32_16x16x32_bf16 v[10:13], v[180:183], v[204:207], v[10:13]
	v_mfma_f32_16x16x32_bf16 v[30:33], v[172:175], v[212:215], v[30:33]
	v_mfma_f32_16x16x32_bf16 v[26:29], v[180:183], v[212:215], v[26:29]
	s_setprio 0
	s_barrier
	s_add_i32 s87, 0, 0x18000
	v_add_u32_e32 v163, s87, v159
	s_add_i32 s88, 0, 0x1c000
	ds_read_b128 v[146:149], v163
	ds_read_b128 v[150:153], v163 offset:1024
	ds_read_b128 v[154:157], v163 offset:2048
	ds_read_b128 v[164:167], v163 offset:3072
	v_add_u32_e32 v163, s88, v159
	ds_read_b128 v[168:171], v163
	ds_read_b128 v[172:175], v163 offset:1024
	ds_read_b128 v[176:179], v163 offset:2048
	ds_read_b128 v[180:183], v163 offset:3072
	s_add_u32 s50, s50, 0x40000
	s_addc_u32 s51, s51, 0
	s_mov_b32 m0, s58
	v_lshl_add_u64 v[224:225], s[50:51], 0, v[134:135]
	ds_read_b128 v[184:187], v162 offset:32768
	ds_read_b128 v[188:191], v162 offset:33792
	ds_read_b128 v[192:195], v162 offset:34816
	ds_read_b128 v[196:199], v162 offset:35840
	ds_read_b128 v[200:203], v162 offset:36864
	ds_read_b128 v[204:207], v162 offset:37888
	ds_read_b128 v[208:211], v162 offset:38912
	ds_read_b128 v[212:215], v162 offset:39936
	global_load_lds_dwordx4 v[224:225], off
	v_lshl_add_u64 v[224:225], s[50:51], 0, v[138:139]
	s_mov_b32 m0, s59
	s_nop 0
	global_load_lds_dwordx4 v[224:225], off
	s_waitcnt vmcnt(8)
	s_waitcnt lgkmcnt(0)
	s_barrier
	s_setprio 1
	s_waitcnt lgkmcnt(0)
	v_mfma_f32_16x16x32_bf16 v[126:129], v[146:149], v[184:187], v[126:129]
	v_mfma_f32_16x16x32_bf16 v[122:125], v[154:157], v[184:187], v[122:125]
	v_mfma_f32_16x16x32_bf16 v[110:113], v[146:149], v[192:195], v[110:113]
	v_mfma_f32_16x16x32_bf16 v[106:109], v[154:157], v[192:195], v[106:109]
	v_mfma_f32_16x16x32_bf16 v[94:97], v[146:149], v[200:203], v[94:97]
	v_mfma_f32_16x16x32_bf16 v[90:93], v[154:157], v[200:203], v[90:93]
	v_mfma_f32_16x16x32_bf16 v[78:81], v[146:149], v[208:211], v[78:81]
	v_mfma_f32_16x16x32_bf16 v[74:77], v[154:157], v[208:211], v[74:77]
	v_mfma_f32_16x16x32_bf16 v[126:129], v[150:153], v[188:191], v[126:129]
	v_mfma_f32_16x16x32_bf16 v[122:125], v[164:167], v[188:191], v[122:125]
	v_mfma_f32_16x16x32_bf16 v[110:113], v[150:153], v[196:199], v[110:113]
	v_mfma_f32_16x16x32_bf16 v[106:109], v[164:167], v[196:199], v[106:109]
	v_mfma_f32_16x16x32_bf16 v[94:97], v[150:153], v[204:207], v[94:97]
	v_mfma_f32_16x16x32_bf16 v[90:93], v[164:167], v[204:207], v[90:93]
	v_mfma_f32_16x16x32_bf16 v[78:81], v[150:153], v[212:215], v[78:81]
	v_mfma_f32_16x16x32_bf16 v[74:77], v[164:167], v[212:215], v[74:77]
	v_mfma_f32_16x16x32_bf16 v[118:121], v[168:171], v[184:187], v[118:121]
	v_mfma_f32_16x16x32_bf16 v[114:117], v[176:179], v[184:187], v[114:117]
	v_mfma_f32_16x16x32_bf16 v[102:105], v[168:171], v[192:195], v[102:105]
	v_mfma_f32_16x16x32_bf16 v[98:101], v[176:179], v[192:195], v[98:101]
	v_mfma_f32_16x16x32_bf16 v[86:89], v[168:171], v[200:203], v[86:89]
	v_mfma_f32_16x16x32_bf16 v[82:85], v[176:179], v[200:203], v[82:85]
	v_mfma_f32_16x16x32_bf16 v[70:73], v[168:171], v[208:211], v[70:73]
	v_mfma_f32_16x16x32_bf16 v[66:69], v[176:179], v[208:211], v[66:69]
	v_mfma_f32_16x16x32_bf16 v[118:121], v[172:175], v[188:191], v[118:121]
	v_mfma_f32_16x16x32_bf16 v[114:117], v[180:183], v[188:191], v[114:117]
	v_mfma_f32_16x16x32_bf16 v[102:105], v[172:175], v[196:199], v[102:105]
	v_mfma_f32_16x16x32_bf16 v[98:101], v[180:183], v[196:199], v[98:101]
	v_mfma_f32_16x16x32_bf16 v[86:89], v[172:175], v[204:207], v[86:89]
	v_mfma_f32_16x16x32_bf16 v[82:85], v[180:183], v[204:207], v[82:85]
	v_mfma_f32_16x16x32_bf16 v[70:73], v[172:175], v[212:215], v[70:73]
	v_mfma_f32_16x16x32_bf16 v[66:69], v[180:183], v[212:215], v[66:69]
	s_setprio 0
	s_barrier
	s_add_i32 s50, s87, s55
	v_lshl_add_u64 v[216:217], v[216:217], 0, s[14:15]
	s_mov_b32 m0, s50
	ds_read_b128 v[184:187], v162 offset:49152
	ds_read_b128 v[188:191], v162 offset:50176
	ds_read_b128 v[192:195], v162 offset:51200
	ds_read_b128 v[196:199], v162 offset:52224
	ds_read_b128 v[200:203], v162 offset:53248
	ds_read_b128 v[204:207], v162 offset:54272
	ds_read_b128 v[208:211], v162 offset:55296
	ds_read_b128 v[212:215], v162 offset:56320
	global_load_lds_dwordx4 v[216:217], off
	s_add_i32 m0, s50, 0x2000
	s_add_u32 s48, s48, 0x40080
	v_lshl_add_u64 v[216:217], v[218:219], 0, s[14:15]
	s_addc_u32 s49, s49, 0
	s_add_i32 s50, s88, s55
	global_load_lds_dwordx4 v[216:217], off
	v_lshl_add_u64 v[216:217], s[48:49], 0, v[136:137]
	s_mov_b32 m0, s50
	s_nop 0
	global_load_lds_dwordx4 v[216:217], off
	v_lshl_add_u64 v[216:217], s[48:49], 0, v[140:141]
	s_add_i32 m0, s50, 0x2000
	s_nop 0
	global_load_lds_dwordx4 v[216:217], off
	v_lshl_add_u64 v[216:217], v[220:221], 0, s[14:15]
	s_mov_b32 m0, s64
	s_nop 0
	global_load_lds_dwordx4 v[216:217], off
	v_lshl_add_u64 v[216:217], v[222:223], 0, s[14:15]
	s_mov_b32 m0, s65
	s_nop 0
	global_load_lds_dwordx4 v[216:217], off
	s_waitcnt vmcnt(8)
	s_waitcnt lgkmcnt(0)
	s_barrier
	s_setprio 1
	s_waitcnt lgkmcnt(0)
	v_mfma_f32_16x16x32_bf16 v[62:65], v[146:149], v[184:187], v[62:65]
	v_mfma_f32_16x16x32_bf16 v[58:61], v[154:157], v[184:187], v[58:61]
	v_mfma_f32_16x16x32_bf16 v[46:49], v[146:149], v[192:195], v[46:49]
	v_mfma_f32_16x16x32_bf16 v[42:45], v[154:157], v[192:195], v[42:45]
	v_mfma_f32_16x16x32_bf16 v[6:9], v[146:149], v[200:203], v[6:9]
	v_mfma_f32_16x16x32_bf16 v[2:5], v[154:157], v[200:203], v[2:5]
	v_mfma_f32_16x16x32_bf16 v[22:25], v[146:149], v[208:211], v[22:25]
	v_mfma_f32_16x16x32_bf16 v[18:21], v[154:157], v[208:211], v[18:21]
	v_mfma_f32_16x16x32_bf16 v[62:65], v[150:153], v[188:191], v[62:65]
	v_mfma_f32_16x16x32_bf16 v[58:61], v[164:167], v[188:191], v[58:61]
	v_mfma_f32_16x16x32_bf16 v[46:49], v[150:153], v[196:199], v[46:49]
	v_mfma_f32_16x16x32_bf16 v[42:45], v[164:167], v[196:199], v[42:45]
	v_mfma_f32_16x16x32_bf16 v[6:9], v[150:153], v[204:207], v[6:9]
	v_mfma_f32_16x16x32_bf16 v[2:5], v[164:167], v[204:207], v[2:5]
	v_mfma_f32_16x16x32_bf16 v[22:25], v[150:153], v[212:215], v[22:25]
	v_mfma_f32_16x16x32_bf16 v[18:21], v[164:167], v[212:215], v[18:21]
	v_mfma_f32_16x16x32_bf16 v[54:57], v[168:171], v[184:187], v[54:57]
	v_mfma_f32_16x16x32_bf16 v[50:53], v[176:179], v[184:187], v[50:53]
	v_mfma_f32_16x16x32_bf16 v[38:41], v[168:171], v[192:195], v[38:41]
	v_mfma_f32_16x16x32_bf16 v[34:37], v[176:179], v[192:195], v[34:37]
	v_mfma_f32_16x16x32_bf16 v[14:17], v[168:171], v[200:203], v[14:17]
	v_mfma_f32_16x16x32_bf16 v[10:13], v[176:179], v[200:203], v[10:13]
	v_mfma_f32_16x16x32_bf16 v[30:33], v[168:171], v[208:211], v[30:33]
	v_mfma_f32_16x16x32_bf16 v[26:29], v[176:179], v[208:211], v[26:29]
	v_mfma_f32_16x16x32_bf16 v[54:57], v[172:175], v[188:191], v[54:57]
	v_mfma_f32_16x16x32_bf16 v[50:53], v[180:183], v[188:191], v[50:53]
	v_mfma_f32_16x16x32_bf16 v[38:41], v[172:175], v[196:199], v[38:41]
	v_mfma_f32_16x16x32_bf16 v[34:37], v[180:183], v[196:199], v[34:37]
	v_mfma_f32_16x16x32_bf16 v[14:17], v[172:175], v[204:207], v[14:17]
	v_mfma_f32_16x16x32_bf16 v[10:13], v[180:183], v[204:207], v[10:13]
	v_mfma_f32_16x16x32_bf16 v[30:33], v[172:175], v[212:215], v[30:33]
	v_mfma_f32_16x16x32_bf16 v[26:29], v[180:183], v[212:215], v[26:29]
	s_setprio 0
	s_barrier
	s_add_i32 s80, s80, 2
	s_add_u32 s81, s81, 0x100
	s_addc_u32 s82, s82, 0
	s_add_u32 s83, s83, 0x100
	s_addc_u32 s84, s84, 0
	s_add_u32 s0, s0, 0xffffff00
	s_addc_u32 s1, s1, -1
	v_lshl_add_u64 v[130:131], v[130:131], 0, s[18:19]
	s_cmp_gt_u32 s80, 13
	v_lshl_add_u64 v[132:133], v[132:133], 0, s[18:19]
	s_cbranch_scc0 .LBB0_689
	s_add_u32 s0, s43, 0x40080
	s_addc_u32 s1, s5, 0
	s_mov_b32 m0, s86
	v_lshl_add_u64 v[130:131], s[0:1], 0, v[134:135]
	global_load_lds_dwordx4 v[130:131], off
	v_lshl_add_u64 v[130:131], s[0:1], 0, v[138:139]
	s_mov_b32 m0, s85
	s_and_b64 vcc, exec, s[16:17]
	global_load_lds_dwordx4 v[130:131], off
	s_cbranch_vccz .LBB0_692
	s_barrier

.LBB0_771:
	ds_read_b128 v[130:133], v180
	ds_read_b128 v[134:137], v180 offset:1024
	ds_read_b128 v[138:141], v180 offset:2048
	ds_read_b128 v[142:145], v180 offset:3072
	ds_read_b128 v[146:149], v181
	ds_read_b128 v[166:169], v181 offset:1024
	ds_read_b128 v[170:173], v181 offset:2048
	ds_read_b128 v[174:177], v181 offset:3072
	s_add_u32 s36, s0, 0xfffc0080
	s_addc_u32 s37, s1, -1
	s_cmp_eq_u32 s58, 12
	s_cselect_b32 s39, s27, s37
	s_cselect_b32 s38, s54, s36
	s_cselect_b32 s37, s25, s57
	s_cselect_b32 s36, s55, s56
	v_lshl_add_u64 v[216:217], s[0:1], 0, v[158:159]
	s_add_i32 m0, s35, 0xc000
	ds_read_b128 v[184:187], v182
	ds_read_b128 v[188:191], v182 offset:1024
	ds_read_b128 v[192:195], v182 offset:2048
	ds_read_b128 v[196:199], v182 offset:3072
	ds_read_b128 v[200:203], v182 offset:4096
	ds_read_b128 v[204:207], v182 offset:5120
	ds_read_b128 v[208:211], v182 offset:6144
	ds_read_b128 v[212:215], v182 offset:7168
	global_load_lds_dwordx4 v[216:217], off
	v_lshl_add_u64 v[216:217], s[0:1], 0, v[160:161]
	s_add_i32 m0, s35, 0xe000
	s_nop 0
	global_load_lds_dwordx4 v[216:217], off
	s_waitcnt vmcnt(8)
	s_waitcnt lgkmcnt(0)
	s_barrier
	s_setprio 1
	s_waitcnt lgkmcnt(0)
	v_mfma_f32_16x16x32_bf16 v[126:129], v[130:133], v[184:187], v[126:129]
	v_mfma_f32_16x16x32_bf16 v[122:125], v[138:141], v[184:187], v[122:125]
	v_mfma_f32_16x16x32_bf16 v[110:113], v[130:133], v[192:195], v[110:113]
	v_mfma_f32_16x16x32_bf16 v[106:109], v[138:141], v[192:195], v[106:109]
	v_mfma_f32_16x16x32_bf16 v[94:97], v[130:133], v[200:203], v[94:97]
	v_mfma_f32_16x16x32_bf16 v[90:93], v[138:141], v[200:203], v[90:93]
	v_mfma_f32_16x16x32_bf16 v[78:81], v[130:133], v[208:211], v[78:81]
	v_mfma_f32_16x16x32_bf16 v[74:77], v[138:141], v[208:211], v[74:77]
	v_mfma_f32_16x16x32_bf16 v[126:129], v[134:137], v[188:191], v[126:129]
	v_mfma_f32_16x16x32_bf16 v[122:125], v[142:145], v[188:191], v[122:125]
	v_mfma_f32_16x16x32_bf16 v[110:113], v[134:137], v[196:199], v[110:113]
	v_mfma_f32_16x16x32_bf16 v[106:109], v[142:145], v[196:199], v[106:109]
	v_mfma_f32_16x16x32_bf16 v[94:97], v[134:137], v[204:207], v[94:97]
	v_mfma_f32_16x16x32_bf16 v[90:93], v[142:145], v[204:207], v[90:93]
	v_mfma_f32_16x16x32_bf16 v[78:81], v[134:137], v[212:215], v[78:81]
	v_mfma_f32_16x16x32_bf16 v[74:77], v[142:145], v[212:215], v[74:77]
	v_mfma_f32_16x16x32_bf16 v[118:121], v[146:149], v[184:187], v[118:121]
	v_mfma_f32_16x16x32_bf16 v[114:117], v[170:173], v[184:187], v[114:117]
	v_mfma_f32_16x16x32_bf16 v[102:105], v[146:149], v[192:195], v[102:105]
	v_mfma_f32_16x16x32_bf16 v[98:101], v[170:173], v[192:195], v[98:101]
	v_mfma_f32_16x16x32_bf16 v[86:89], v[146:149], v[200:203], v[86:89]
	v_mfma_f32_16x16x32_bf16 v[82:85], v[170:173], v[200:203], v[82:85]
	v_mfma_f32_16x16x32_bf16 v[70:73], v[146:149], v[208:211], v[70:73]
	v_mfma_f32_16x16x32_bf16 v[66:69], v[170:173], v[208:211], v[66:69]
	v_mfma_f32_16x16x32_bf16 v[118:121], v[166:169], v[188:191], v[118:121]
	v_mfma_f32_16x16x32_bf16 v[114:117], v[174:177], v[188:191], v[114:117]
	v_mfma_f32_16x16x32_bf16 v[102:105], v[166:169], v[196:199], v[102:105]
	v_mfma_f32_16x16x32_bf16 v[98:101], v[174:177], v[196:199], v[98:101]
	v_mfma_f32_16x16x32_bf16 v[86:89], v[166:169], v[204:207], v[86:89]
	v_mfma_f32_16x16x32_bf16 v[82:85], v[174:177], v[204:207], v[82:85]
	v_mfma_f32_16x16x32_bf16 v[70:73], v[166:169], v[212:215], v[70:73]
	v_mfma_f32_16x16x32_bf16 v[66:69], v[174:177], v[212:215], v[66:69]
	s_setprio 0
	s_barrier
	s_add_i32 s59, s51, s43
	v_lshl_add_u64 v[216:217], s[36:37], 0, v[152:153]
	s_mov_b32 m0, s59
	ds_read_b128 v[184:187], v182 offset:16384
	ds_read_b128 v[188:191], v182 offset:17408
	ds_read_b128 v[192:195], v182 offset:18432
	ds_read_b128 v[196:199], v182 offset:19456
	ds_read_b128 v[200:203], v182 offset:20480
	ds_read_b128 v[204:207], v182 offset:21504
	ds_read_b128 v[208:211], v182 offset:22528
	ds_read_b128 v[212:215], v182 offset:23552
	global_load_lds_dwordx4 v[216:217], off
	s_add_i32 m0, s59, 0x2000
	s_add_u32 s60, s36, 0x40000
	v_lshl_add_u64 v[218:219], s[36:37], 0, v[156:157]
	s_addc_u32 s61, s37, 0
	s_add_i32 s59, s52, s43
	global_load_lds_dwordx4 v[218:219], off
	v_lshl_add_u64 v[220:221], s[60:61], 0, v[152:153]
	s_mov_b32 m0, s59
	v_lshl_add_u64 v[222:223], s[38:39], 0, v[154:155]
	global_load_lds_dwordx4 v[220:221], off
	v_lshl_add_u64 v[220:221], s[60:61], 0, v[156:157]
	s_add_i32 m0, s59, 0x2000
	s_nop 0
	global_load_lds_dwordx4 v[220:221], off
	v_lshl_add_u64 v[220:221], s[38:39], 0, v[150:151]
	s_mov_b32 m0, s35
	s_nop 0
	global_load_lds_dwordx4 v[220:221], off
	s_mov_b32 m0, s44
	s_nop 0
	global_load_lds_dwordx4 v[222:223], off
	s_waitcnt vmcnt(8)
	s_waitcnt lgkmcnt(0)
	s_barrier
	s_setprio 1
	s_waitcnt lgkmcnt(0)
	v_mfma_f32_16x16x32_bf16 v[6:9], v[130:133], v[184:187], v[6:9]
	v_mfma_f32_16x16x32_bf16 v[2:5], v[138:141], v[184:187], v[2:5]
	v_mfma_f32_16x16x32_bf16 v[22:25], v[130:133], v[192:195], v[22:25]
	v_mfma_f32_16x16x32_bf16 v[18:21], v[138:141], v[192:195], v[18:21]
	v_mfma_f32_16x16x32_bf16 v[38:41], v[130:133], v[200:203], v[38:41]
	v_mfma_f32_16x16x32_bf16 v[34:37], v[138:141], v[200:203], v[34:37]
	v_mfma_f32_16x16x32_bf16 v[54:57], v[130:133], v[208:211], v[54:57]
	v_mfma_f32_16x16x32_bf16 v[50:53], v[138:141], v[208:211], v[50:53]
	v_mfma_f32_16x16x32_bf16 v[6:9], v[134:137], v[188:191], v[6:9]
	v_mfma_f32_16x16x32_bf16 v[2:5], v[142:145], v[188:191], v[2:5]
	v_mfma_f32_16x16x32_bf16 v[22:25], v[134:137], v[196:199], v[22:25]
	v_mfma_f32_16x16x32_bf16 v[18:21], v[142:145], v[196:199], v[18:21]
	v_mfma_f32_16x16x32_bf16 v[38:41], v[134:137], v[204:207], v[38:41]
	v_mfma_f32_16x16x32_bf16 v[34:37], v[142:145], v[204:207], v[34:37]
	v_mfma_f32_16x16x32_bf16 v[54:57], v[134:137], v[212:215], v[54:57]
	v_mfma_f32_16x16x32_bf16 v[50:53], v[142:145], v[212:215], v[50:53]
	v_mfma_f32_16x16x32_bf16 v[14:17], v[146:149], v[184:187], v[14:17]
	v_mfma_f32_16x16x32_bf16 v[10:13], v[170:173], v[184:187], v[10:13]
	v_mfma_f32_16x16x32_bf16 v[30:33], v[146:149], v[192:195], v[30:33]
	v_mfma_f32_16x16x32_bf16 v[26:29], v[170:173], v[192:195], v[26:29]
	v_mfma_f32_16x16x32_bf16 v[46:49], v[146:149], v[200:203], v[46:49]
	v_mfma_f32_16x16x32_bf16 v[42:45], v[170:173], v[200:203], v[42:45]
	v_mfma_f32_16x16x32_bf16 v[62:65], v[146:149], v[208:211], v[62:65]
	v_mfma_f32_16x16x32_bf16 v[58:61], v[170:173], v[208:211], v[58:61]
	v_mfma_f32_16x16x32_bf16 v[14:17], v[166:169], v[188:191], v[14:17]
	v_mfma_f32_16x16x32_bf16 v[10:13], v[174:177], v[188:191], v[10:13]
	v_mfma_f32_16x16x32_bf16 v[30:33], v[166:169], v[196:199], v[30:33]
	v_mfma_f32_16x16x32_bf16 v[26:29], v[174:177], v[196:199], v[26:29]
	v_mfma_f32_16x16x32_bf16 v[46:49], v[166:169], v[204:207], v[46:49]
	v_mfma_f32_16x16x32_bf16 v[42:45], v[174:177], v[204:207], v[42:45]
	v_mfma_f32_16x16x32_bf16 v[62:65], v[166:169], v[212:215], v[62:65]
	v_mfma_f32_16x16x32_bf16 v[58:61], v[174:177], v[212:215], v[58:61]
	s_setprio 0
	s_barrier
	s_cmp_lg_u32 s58, 12
	s_cbranch_scc1 .Lmy_p5_nox
	v_lshl_or_b32 v183, s53, 8, v179
	v_lshl_add_u32 v226, s34, 8, v1
	v_lshlrev_b32_e32 v183, 1, v183
	v_lshl_add_u32 v183, v226, 11, v183
	global_load_dwordx4 v[226:229], v183, s[12:13]
	global_load_dwordx4 v[230:233], v183, s[12:13] offset:256
	v_add_u32_e32 v183, 0x8000, v183
	global_load_dwordx4 v[234:237], v183, s[12:13]
	global_load_dwordx4 v[238:241], v183, s[12:13] offset:256
	v_add_u32_e32 v183, 0x8000, v183
	global_load_dwordx4 v[242:245], v183, s[12:13]
	global_load_dwordx4 v[246:249], v183, s[12:13] offset:256
	v_add_u32_e32 v183, 0x8000, v183
	global_load_dwordx4 v[250:253], v183, s[12:13]
	global_load_dwordx4 v[162:165], v183, s[12:13] offset:256

.Lmy_p5_wc_done:
	s_waitcnt lgkmcnt(0)
	s_barrier
	s_setprio 1
	s_waitcnt lgkmcnt(0)
	v_mfma_f32_16x16x32_bf16 v[126:129], v[130:133], v[184:187], v[126:129]
	v_mfma_f32_16x16x32_bf16 v[122:125], v[138:141], v[184:187], v[122:125]
	v_mfma_f32_16x16x32_bf16 v[110:113], v[130:133], v[192:195], v[110:113]
	v_mfma_f32_16x16x32_bf16 v[106:109], v[138:141], v[192:195], v[106:109]
	v_mfma_f32_16x16x32_bf16 v[94:97], v[130:133], v[200:203], v[94:97]
	v_mfma_f32_16x16x32_bf16 v[90:93], v[138:141], v[200:203], v[90:93]
	v_mfma_f32_16x16x32_bf16 v[78:81], v[130:133], v[208:211], v[78:81]
	v_mfma_f32_16x16x32_bf16 v[74:77], v[138:141], v[208:211], v[74:77]
	v_mfma_f32_16x16x32_bf16 v[126:129], v[134:137], v[188:191], v[126:129]
	v_mfma_f32_16x16x32_bf16 v[122:125], v[142:145], v[188:191], v[122:125]
	v_mfma_f32_16x16x32_bf16 v[110:113], v[134:137], v[196:199], v[110:113]
	v_mfma_f32_16x16x32_bf16 v[106:109], v[142:145], v[196:199], v[106:109]
	v_mfma_f32_16x16x32_bf16 v[94:97], v[134:137], v[204:207], v[94:97]
	v_mfma_f32_16x16x32_bf16 v[90:93], v[142:145], v[204:207], v[90:93]
	v_mfma_f32_16x16x32_bf16 v[78:81], v[134:137], v[212:215], v[78:81]
	v_mfma_f32_16x16x32_bf16 v[74:77], v[142:145], v[212:215], v[74:77]
	v_mfma_f32_16x16x32_bf16 v[118:121], v[146:149], v[184:187], v[118:121]
	v_mfma_f32_16x16x32_bf16 v[114:117], v[170:173], v[184:187], v[114:117]
	v_mfma_f32_16x16x32_bf16 v[102:105], v[146:149], v[192:195], v[102:105]
	v_mfma_f32_16x16x32_bf16 v[98:101], v[170:173], v[192:195], v[98:101]
	v_mfma_f32_16x16x32_bf16 v[86:89], v[146:149], v[200:203], v[86:89]
	v_mfma_f32_16x16x32_bf16 v[82:85], v[170:173], v[200:203], v[82:85]
	v_mfma_f32_16x16x32_bf16 v[70:73], v[146:149], v[208:211], v[70:73]
	v_mfma_f32_16x16x32_bf16 v[66:69], v[170:173], v[208:211], v[66:69]
	v_mfma_f32_16x16x32_bf16 v[118:121], v[166:169], v[188:191], v[118:121]
	v_mfma_f32_16x16x32_bf16 v[114:117], v[174:177], v[188:191], v[114:117]
	v_mfma_f32_16x16x32_bf16 v[102:105], v[166:169], v[196:199], v[102:105]
	v_mfma_f32_16x16x32_bf16 v[98:101], v[174:177], v[196:199], v[98:101]
	v_mfma_f32_16x16x32_bf16 v[86:89], v[166:169], v[204:207], v[86:89]
	v_mfma_f32_16x16x32_bf16 v[82:85], v[174:177], v[204:207], v[82:85]
	v_mfma_f32_16x16x32_bf16 v[70:73], v[166:169], v[212:215], v[70:73]
	v_mfma_f32_16x16x32_bf16 v[66:69], v[174:177], v[212:215], v[66:69]
	s_setprio 0
	s_barrier
	s_add_i32 s38, s59, s43
	v_lshl_add_u64 v[216:217], v[216:217], 0, s[14:15]
	s_mov_b32 m0, s38
	ds_read_b128 v[184:187], v182 offset:49152
	ds_read_b128 v[188:191], v182 offset:50176
	ds_read_b128 v[192:195], v182 offset:51200
	ds_read_b128 v[196:199], v182 offset:52224
	ds_read_b128 v[200:203], v182 offset:53248
	ds_read_b128 v[204:207], v182 offset:54272
	ds_read_b128 v[208:211], v182 offset:55296
	ds_read_b128 v[212:215], v182 offset:56320
	global_load_lds_dwordx4 v[216:217], off
	s_add_i32 m0, s38, 0x2000
	s_add_u32 s36, s36, 0x40080
	v_lshl_add_u64 v[216:217], v[218:219], 0, s[14:15]
	s_addc_u32 s37, s37, 0
	s_add_i32 s38, s60, s43
	global_load_lds_dwordx4 v[216:217], off
	v_lshl_add_u64 v[216:217], s[36:37], 0, v[152:153]
	s_mov_b32 m0, s38
	s_nop 0
	global_load_lds_dwordx4 v[216:217], off
	v_lshl_add_u64 v[216:217], s[36:37], 0, v[156:157]
	s_add_i32 m0, s38, 0x2000
	s_nop 0
	global_load_lds_dwordx4 v[216:217], off
	v_lshl_add_u64 v[216:217], v[220:221], 0, s[14:15]
	s_mov_b32 m0, s48
	s_nop 0
	global_load_lds_dwordx4 v[216:217], off
	v_lshl_add_u64 v[216:217], v[222:223], 0, s[14:15]
	s_mov_b32 m0, s49
	s_nop 0
	global_load_lds_dwordx4 v[216:217], off
	s_cmp_eq_u32 s58, 12
	s_cbranch_scc1 .Lmy_p5_wd_last
	s_waitcnt vmcnt(8)
	s_branch .Lmy_p5_wd_done

.Lmy_p5_wd_done:
	s_waitcnt lgkmcnt(0)
	s_barrier
	s_setprio 1
	s_waitcnt lgkmcnt(0)
	v_mfma_f32_16x16x32_bf16 v[6:9], v[130:133], v[184:187], v[6:9]
	v_mfma_f32_16x16x32_bf16 v[2:5], v[138:141], v[184:187], v[2:5]
	v_mfma_f32_16x16x32_bf16 v[22:25], v[130:133], v[192:195], v[22:25]
	v_mfma_f32_16x16x32_bf16 v[18:21], v[138:141], v[192:195], v[18:21]
	v_mfma_f32_16x16x32_bf16 v[38:41], v[130:133], v[200:203], v[38:41]
	v_mfma_f32_16x16x32_bf16 v[34:37], v[138:141], v[200:203], v[34:37]
	v_mfma_f32_16x16x32_bf16 v[54:57], v[130:133], v[208:211], v[54:57]
	v_mfma_f32_16x16x32_bf16 v[50:53], v[138:141], v[208:211], v[50:53]
	v_mfma_f32_16x16x32_bf16 v[6:9], v[134:137], v[188:191], v[6:9]
	v_mfma_f32_16x16x32_bf16 v[2:5], v[142:145], v[188:191], v[2:5]
	v_mfma_f32_16x16x32_bf16 v[22:25], v[134:137], v[196:199], v[22:25]
	v_mfma_f32_16x16x32_bf16 v[18:21], v[142:145], v[196:199], v[18:21]
	v_mfma_f32_16x16x32_bf16 v[38:41], v[134:137], v[204:207], v[38:41]
	v_mfma_f32_16x16x32_bf16 v[34:37], v[142:145], v[204:207], v[34:37]
	v_mfma_f32_16x16x32_bf16 v[54:57], v[134:137], v[212:215], v[54:57]
	v_mfma_f32_16x16x32_bf16 v[50:53], v[142:145], v[212:215], v[50:53]
	v_mfma_f32_16x16x32_bf16 v[14:17], v[146:149], v[184:187], v[14:17]
	v_mfma_f32_16x16x32_bf16 v[10:13], v[170:173], v[184:187], v[10:13]
	v_mfma_f32_16x16x32_bf16 v[30:33], v[146:149], v[192:195], v[30:33]
	v_mfma_f32_16x16x32_bf16 v[26:29], v[170:173], v[192:195], v[26:29]
	v_mfma_f32_16x16x32_bf16 v[46:49], v[146:149], v[200:203], v[46:49]
	v_mfma_f32_16x16x32_bf16 v[42:45], v[170:173], v[200:203], v[42:45]
	v_mfma_f32_16x16x32_bf16 v[62:65], v[146:149], v[208:211], v[62:65]
	v_mfma_f32_16x16x32_bf16 v[58:61], v[170:173], v[208:211], v[58:61]
	v_mfma_f32_16x16x32_bf16 v[14:17], v[166:169], v[188:191], v[14:17]
	v_mfma_f32_16x16x32_bf16 v[10:13], v[174:177], v[188:191], v[10:13]
	v_mfma_f32_16x16x32_bf16 v[30:33], v[166:169], v[196:199], v[30:33]
	v_mfma_f32_16x16x32_bf16 v[26:29], v[174:177], v[196:199], v[26:29]
	v_mfma_f32_16x16x32_bf16 v[46:49], v[166:169], v[204:207], v[46:49]
	v_mfma_f32_16x16x32_bf16 v[42:45], v[174:177], v[204:207], v[42:45]
	v_mfma_f32_16x16x32_bf16 v[62:65], v[166:169], v[212:215], v[62:65]
	v_mfma_f32_16x16x32_bf16 v[58:61], v[174:177], v[212:215], v[58:61]
	s_setprio 0
	s_barrier
	s_add_i32 s58, s58, 2
	s_add_u32 s0, s0, 0x100
	s_addc_u32 s1, s1, 0
	s_add_u32 s56, s56, 0x100
	s_addc_u32 s57, s57, 0
	s_cmp_gt_u32 s58, 13
	s_cbranch_scc0 .LBB0_771
	s_and_b64 vcc, exec, s[16:17]
	s_cbranch_vccz .LBB0_774
	s_barrier

.LBB0_796:
	ds_read_b128 v[130:133], v162
	ds_read_b128 v[134:137], v162 offset:1024
	ds_read_b128 v[154:157], v162 offset:2048
	ds_read_b128 v[166:169], v162 offset:3072
	ds_read_b128 v[170:173], v163
	ds_read_b128 v[174:177], v163 offset:1024
	ds_read_b128 v[178:181], v163 offset:2048
	ds_read_b128 v[182:185], v163 offset:3072
	s_add_u32 s28, s0, 0xfff80080
	s_addc_u32 s29, s1, -1
	s_cmp_eq_u32 s54, 28
	s_cselect_b32 s31, s21, s29
	s_cselect_b32 s30, s50, s28
	s_cselect_b32 s29, s19, s53
	s_cselect_b32 s28, s51, s52
	v_lshl_add_u64 v[158:159], s[0:1], 0, v[146:147]
	s_add_i32 m0, s27, 0xc000
	ds_read_b128 v[186:189], v164
	ds_read_b128 v[190:193], v164 offset:1024
	ds_read_b128 v[194:197], v164 offset:2048
	ds_read_b128 v[198:201], v164 offset:3072
	ds_read_b128 v[202:205], v164 offset:4096
	ds_read_b128 v[206:209], v164 offset:5120
	ds_read_b128 v[210:213], v164 offset:6144
	ds_read_b128 v[214:217], v164 offset:7168
	global_load_lds_dwordx4 v[158:159], off
	v_lshl_add_u64 v[158:159], s[0:1], 0, v[148:149]
	s_add_i32 m0, s27, 0xe000
	s_nop 0
	global_load_lds_dwordx4 v[158:159], off
	s_waitcnt vmcnt(8)
	s_waitcnt lgkmcnt(0)
	s_barrier
	s_setprio 1
	s_waitcnt lgkmcnt(0)
	v_mfma_f32_16x16x32_bf16 v[126:129], v[130:133], v[186:189], v[126:129]
	v_mfma_f32_16x16x32_bf16 v[122:125], v[154:157], v[186:189], v[122:125]
	v_mfma_f32_16x16x32_bf16 v[110:113], v[130:133], v[194:197], v[110:113]
	v_mfma_f32_16x16x32_bf16 v[106:109], v[154:157], v[194:197], v[106:109]
	v_mfma_f32_16x16x32_bf16 v[94:97], v[130:133], v[202:205], v[94:97]
	v_mfma_f32_16x16x32_bf16 v[90:93], v[154:157], v[202:205], v[90:93]
	v_mfma_f32_16x16x32_bf16 v[78:81], v[130:133], v[210:213], v[78:81]
	v_mfma_f32_16x16x32_bf16 v[74:77], v[154:157], v[210:213], v[74:77]
	v_mfma_f32_16x16x32_bf16 v[126:129], v[134:137], v[190:193], v[126:129]
	v_mfma_f32_16x16x32_bf16 v[122:125], v[166:169], v[190:193], v[122:125]
	v_mfma_f32_16x16x32_bf16 v[110:113], v[134:137], v[198:201], v[110:113]
	v_mfma_f32_16x16x32_bf16 v[106:109], v[166:169], v[198:201], v[106:109]
	v_mfma_f32_16x16x32_bf16 v[94:97], v[134:137], v[206:209], v[94:97]
	v_mfma_f32_16x16x32_bf16 v[90:93], v[166:169], v[206:209], v[90:93]
	v_mfma_f32_16x16x32_bf16 v[78:81], v[134:137], v[214:217], v[78:81]
	v_mfma_f32_16x16x32_bf16 v[74:77], v[166:169], v[214:217], v[74:77]
	v_mfma_f32_16x16x32_bf16 v[118:121], v[170:173], v[186:189], v[118:121]
	v_mfma_f32_16x16x32_bf16 v[114:117], v[178:181], v[186:189], v[114:117]
	v_mfma_f32_16x16x32_bf16 v[102:105], v[170:173], v[194:197], v[102:105]
	v_mfma_f32_16x16x32_bf16 v[98:101], v[178:181], v[194:197], v[98:101]
	v_mfma_f32_16x16x32_bf16 v[86:89], v[170:173], v[202:205], v[86:89]
	v_mfma_f32_16x16x32_bf16 v[82:85], v[178:181], v[202:205], v[82:85]
	v_mfma_f32_16x16x32_bf16 v[70:73], v[170:173], v[210:213], v[70:73]
	v_mfma_f32_16x16x32_bf16 v[66:69], v[178:181], v[210:213], v[66:69]
	v_mfma_f32_16x16x32_bf16 v[118:121], v[174:177], v[190:193], v[118:121]
	v_mfma_f32_16x16x32_bf16 v[114:117], v[182:185], v[190:193], v[114:117]
	v_mfma_f32_16x16x32_bf16 v[102:105], v[174:177], v[198:201], v[102:105]
	v_mfma_f32_16x16x32_bf16 v[98:101], v[182:185], v[198:201], v[98:101]
	v_mfma_f32_16x16x32_bf16 v[86:89], v[174:177], v[206:209], v[86:89]
	v_mfma_f32_16x16x32_bf16 v[82:85], v[182:185], v[206:209], v[82:85]
	v_mfma_f32_16x16x32_bf16 v[70:73], v[174:177], v[214:217], v[70:73]
	v_mfma_f32_16x16x32_bf16 v[66:69], v[182:185], v[214:217], v[66:69]
	s_setprio 0
	s_barrier
	s_add_i32 s55, s47, s39
	v_lshl_add_u64 v[158:159], s[28:29], 0, v[140:141]
	s_mov_b32 m0, s55
	ds_read_b128 v[186:189], v164 offset:16384
	ds_read_b128 v[190:193], v164 offset:17408
	ds_read_b128 v[194:197], v164 offset:18432
	ds_read_b128 v[198:201], v164 offset:19456
	ds_read_b128 v[202:205], v164 offset:20480
	ds_read_b128 v[206:209], v164 offset:21504
	ds_read_b128 v[210:213], v164 offset:22528
	ds_read_b128 v[214:217], v164 offset:23552
	global_load_lds_dwordx4 v[158:159], off
	s_add_i32 m0, s55, 0x2000
	s_add_u32 s56, s28, 0x80000
	v_lshl_add_u64 v[218:219], s[28:29], 0, v[144:145]
	s_addc_u32 s57, s29, 0
	s_add_i32 s55, s48, s39
	global_load_lds_dwordx4 v[218:219], off
	v_lshl_add_u64 v[220:221], s[56:57], 0, v[140:141]
	s_mov_b32 m0, s55
	v_lshl_add_u64 v[222:223], s[30:31], 0, v[142:143]
	global_load_lds_dwordx4 v[220:221], off
	v_lshl_add_u64 v[220:221], s[56:57], 0, v[144:145]
	s_add_i32 m0, s55, 0x2000
	s_nop 0
	global_load_lds_dwordx4 v[220:221], off
	v_lshl_add_u64 v[220:221], s[30:31], 0, v[138:139]
	s_mov_b32 m0, s27
	s_nop 0
	global_load_lds_dwordx4 v[220:221], off
	s_mov_b32 m0, s40
	s_nop 0
	global_load_lds_dwordx4 v[222:223], off
	s_waitcnt vmcnt(8)
	s_waitcnt lgkmcnt(0)
	s_barrier
	s_setprio 1
	s_waitcnt lgkmcnt(0)
	v_mfma_f32_16x16x32_bf16 v[62:65], v[130:133], v[186:189], v[62:65]
	v_mfma_f32_16x16x32_bf16 v[58:61], v[154:157], v[186:189], v[58:61]
	v_mfma_f32_16x16x32_bf16 v[46:49], v[130:133], v[194:197], v[46:49]
	v_mfma_f32_16x16x32_bf16 v[42:45], v[154:157], v[194:197], v[42:45]
	v_mfma_f32_16x16x32_bf16 v[6:9], v[130:133], v[202:205], v[6:9]
	v_mfma_f32_16x16x32_bf16 v[2:5], v[154:157], v[202:205], v[2:5]
	v_mfma_f32_16x16x32_bf16 v[22:25], v[130:133], v[210:213], v[22:25]
	v_mfma_f32_16x16x32_bf16 v[18:21], v[154:157], v[210:213], v[18:21]
	v_mfma_f32_16x16x32_bf16 v[62:65], v[134:137], v[190:193], v[62:65]
	v_mfma_f32_16x16x32_bf16 v[58:61], v[166:169], v[190:193], v[58:61]
	v_mfma_f32_16x16x32_bf16 v[46:49], v[134:137], v[198:201], v[46:49]
	v_mfma_f32_16x16x32_bf16 v[42:45], v[166:169], v[198:201], v[42:45]
	v_mfma_f32_16x16x32_bf16 v[6:9], v[134:137], v[206:209], v[6:9]
	v_mfma_f32_16x16x32_bf16 v[2:5], v[166:169], v[206:209], v[2:5]
	v_mfma_f32_16x16x32_bf16 v[22:25], v[134:137], v[214:217], v[22:25]
	v_mfma_f32_16x16x32_bf16 v[18:21], v[166:169], v[214:217], v[18:21]
	v_mfma_f32_16x16x32_bf16 v[54:57], v[170:173], v[186:189], v[54:57]
	v_mfma_f32_16x16x32_bf16 v[50:53], v[178:181], v[186:189], v[50:53]
	v_mfma_f32_16x16x32_bf16 v[38:41], v[170:173], v[194:197], v[38:41]
	v_mfma_f32_16x16x32_bf16 v[34:37], v[178:181], v[194:197], v[34:37]
	v_mfma_f32_16x16x32_bf16 v[14:17], v[170:173], v[202:205], v[14:17]
	v_mfma_f32_16x16x32_bf16 v[10:13], v[178:181], v[202:205], v[10:13]
	v_mfma_f32_16x16x32_bf16 v[30:33], v[170:173], v[210:213], v[30:33]
	v_mfma_f32_16x16x32_bf16 v[26:29], v[178:181], v[210:213], v[26:29]
	v_mfma_f32_16x16x32_bf16 v[54:57], v[174:177], v[190:193], v[54:57]
	v_mfma_f32_16x16x32_bf16 v[50:53], v[182:185], v[190:193], v[50:53]
	v_mfma_f32_16x16x32_bf16 v[38:41], v[174:177], v[198:201], v[38:41]
	v_mfma_f32_16x16x32_bf16 v[34:37], v[182:185], v[198:201], v[34:37]
	v_mfma_f32_16x16x32_bf16 v[14:17], v[174:177], v[206:209], v[14:17]
	v_mfma_f32_16x16x32_bf16 v[10:13], v[182:185], v[206:209], v[10:13]
	v_mfma_f32_16x16x32_bf16 v[30:33], v[174:177], v[214:217], v[30:33]
	v_mfma_f32_16x16x32_bf16 v[26:29], v[182:185], v[214:217], v[26:29]
	s_setprio 0
	s_barrier
	s_cmp_lg_u32 s54, 28
	s_cbranch_scc1 .Lmy_p6_nox
	v_lshl_add_u32 v152, s26, 8, v1
	v_lshl_or_b32 v153, s49, 8, v161
	v_lshl_add_u32 v152, v152, 10, v153
	v_lshlrev_b32_e32 v150, 1, v152
	v_add_u32_e32 v151, 0x8000, v150
	global_load_dwordx4 v[226:229], v150, s[8:9]
	global_load_dwordx4 v[230:233], v150, s[10:11]
	global_load_dwordx4 v[234:237], v150, s[8:9] offset:256
	global_load_dwordx4 v[238:241], v150, s[10:11] offset:256
	global_load_dwordx4 v[242:245], v151, s[8:9]
	global_load_dwordx4 v[246:249], v151, s[10:11]
	global_load_dwordx4 v[250:253], v151, s[8:9] offset:256
	global_load_dwordx4 v[150:153], v151, s[10:11] offset:256

.Lmy_p6_wc_done:
	s_waitcnt lgkmcnt(0)
	s_barrier
	s_setprio 1
	s_waitcnt lgkmcnt(0)
	v_mfma_f32_16x16x32_bf16 v[126:129], v[130:133], v[186:189], v[126:129]
	v_mfma_f32_16x16x32_bf16 v[122:125], v[154:157], v[186:189], v[122:125]
	v_mfma_f32_16x16x32_bf16 v[110:113], v[130:133], v[194:197], v[110:113]
	v_mfma_f32_16x16x32_bf16 v[106:109], v[154:157], v[194:197], v[106:109]
	v_mfma_f32_16x16x32_bf16 v[94:97], v[130:133], v[202:205], v[94:97]
	v_mfma_f32_16x16x32_bf16 v[90:93], v[154:157], v[202:205], v[90:93]
	v_mfma_f32_16x16x32_bf16 v[78:81], v[130:133], v[210:213], v[78:81]
	v_mfma_f32_16x16x32_bf16 v[74:77], v[154:157], v[210:213], v[74:77]
	v_mfma_f32_16x16x32_bf16 v[126:129], v[134:137], v[190:193], v[126:129]
	v_mfma_f32_16x16x32_bf16 v[122:125], v[166:169], v[190:193], v[122:125]
	v_mfma_f32_16x16x32_bf16 v[110:113], v[134:137], v[198:201], v[110:113]
	v_mfma_f32_16x16x32_bf16 v[106:109], v[166:169], v[198:201], v[106:109]
	v_mfma_f32_16x16x32_bf16 v[94:97], v[134:137], v[206:209], v[94:97]
	v_mfma_f32_16x16x32_bf16 v[90:93], v[166:169], v[206:209], v[90:93]
	v_mfma_f32_16x16x32_bf16 v[78:81], v[134:137], v[214:217], v[78:81]
	v_mfma_f32_16x16x32_bf16 v[74:77], v[166:169], v[214:217], v[74:77]
	v_mfma_f32_16x16x32_bf16 v[118:121], v[170:173], v[186:189], v[118:121]
	v_mfma_f32_16x16x32_bf16 v[114:117], v[178:181], v[186:189], v[114:117]
	v_mfma_f32_16x16x32_bf16 v[102:105], v[170:173], v[194:197], v[102:105]
	v_mfma_f32_16x16x32_bf16 v[98:101], v[178:181], v[194:197], v[98:101]
	v_mfma_f32_16x16x32_bf16 v[86:89], v[170:173], v[202:205], v[86:89]
	v_mfma_f32_16x16x32_bf16 v[82:85], v[178:181], v[202:205], v[82:85]
	v_mfma_f32_16x16x32_bf16 v[70:73], v[170:173], v[210:213], v[70:73]
	v_mfma_f32_16x16x32_bf16 v[66:69], v[178:181], v[210:213], v[66:69]
	v_mfma_f32_16x16x32_bf16 v[118:121], v[174:177], v[190:193], v[118:121]
	v_mfma_f32_16x16x32_bf16 v[114:117], v[182:185], v[190:193], v[114:117]
	v_mfma_f32_16x16x32_bf16 v[102:105], v[174:177], v[198:201], v[102:105]
	v_mfma_f32_16x16x32_bf16 v[98:101], v[182:185], v[198:201], v[98:101]
	v_mfma_f32_16x16x32_bf16 v[86:89], v[174:177], v[206:209], v[86:89]
	v_mfma_f32_16x16x32_bf16 v[82:85], v[182:185], v[206:209], v[82:85]
	v_mfma_f32_16x16x32_bf16 v[70:73], v[174:177], v[214:217], v[70:73]
	v_mfma_f32_16x16x32_bf16 v[66:69], v[182:185], v[214:217], v[66:69]
	s_setprio 0
	s_barrier
	s_add_i32 s30, s55, s39
	v_lshl_add_u64 v[158:159], v[158:159], 0, s[14:15]
	s_mov_b32 m0, s30
	ds_read_b128 v[186:189], v164 offset:49152
	ds_read_b128 v[190:193], v164 offset:50176
	ds_read_b128 v[194:197], v164 offset:51200
	ds_read_b128 v[198:201], v164 offset:52224
	ds_read_b128 v[202:205], v164 offset:53248
	ds_read_b128 v[206:209], v164 offset:54272
	ds_read_b128 v[210:213], v164 offset:55296
	ds_read_b128 v[214:217], v164 offset:56320
	global_load_lds_dwordx4 v[158:159], off
	s_add_i32 m0, s30, 0x2000
	s_add_u32 s28, s28, 0x80080
	v_lshl_add_u64 v[158:159], v[218:219], 0, s[14:15]
	s_addc_u32 s29, s29, 0
	s_add_i32 s30, s56, s39
	global_load_lds_dwordx4 v[158:159], off
	v_lshl_add_u64 v[158:159], s[28:29], 0, v[140:141]
	s_mov_b32 m0, s30
	s_nop 0
	global_load_lds_dwordx4 v[158:159], off
	v_lshl_add_u64 v[158:159], s[28:29], 0, v[144:145]
	s_add_i32 m0, s30, 0x2000
	s_nop 0
	global_load_lds_dwordx4 v[158:159], off
	v_lshl_add_u64 v[158:159], v[220:221], 0, s[14:15]
	s_mov_b32 m0, s44
	s_nop 0
	global_load_lds_dwordx4 v[158:159], off
	v_lshl_add_u64 v[158:159], v[222:223], 0, s[14:15]
	s_mov_b32 m0, s45
	s_nop 0
	global_load_lds_dwordx4 v[158:159], off
	s_cmp_eq_u32 s54, 28
	s_cbranch_scc1 .Lmy_p6_wd_last
	s_waitcnt vmcnt(8)
	s_branch .Lmy_p6_wd_done

.Lmy_p6_wd_done:
	s_waitcnt lgkmcnt(0)
	s_barrier
	s_setprio 1
	s_waitcnt lgkmcnt(0)
	v_mfma_f32_16x16x32_bf16 v[62:65], v[130:133], v[186:189], v[62:65]
	v_mfma_f32_16x16x32_bf16 v[58:61], v[154:157], v[186:189], v[58:61]
	v_mfma_f32_16x16x32_bf16 v[46:49], v[130:133], v[194:197], v[46:49]
	v_mfma_f32_16x16x32_bf16 v[42:45], v[154:157], v[194:197], v[42:45]
	v_mfma_f32_16x16x32_bf16 v[6:9], v[130:133], v[202:205], v[6:9]
	v_mfma_f32_16x16x32_bf16 v[2:5], v[154:157], v[202:205], v[2:5]
	v_mfma_f32_16x16x32_bf16 v[22:25], v[130:133], v[210:213], v[22:25]
	v_mfma_f32_16x16x32_bf16 v[18:21], v[154:157], v[210:213], v[18:21]
	v_mfma_f32_16x16x32_bf16 v[62:65], v[134:137], v[190:193], v[62:65]
	v_mfma_f32_16x16x32_bf16 v[58:61], v[166:169], v[190:193], v[58:61]
	v_mfma_f32_16x16x32_bf16 v[46:49], v[134:137], v[198:201], v[46:49]
	v_mfma_f32_16x16x32_bf16 v[42:45], v[166:169], v[198:201], v[42:45]
	v_mfma_f32_16x16x32_bf16 v[6:9], v[134:137], v[206:209], v[6:9]
	v_mfma_f32_16x16x32_bf16 v[2:5], v[166:169], v[206:209], v[2:5]
	v_mfma_f32_16x16x32_bf16 v[22:25], v[134:137], v[214:217], v[22:25]
	v_mfma_f32_16x16x32_bf16 v[18:21], v[166:169], v[214:217], v[18:21]
	v_mfma_f32_16x16x32_bf16 v[54:57], v[170:173], v[186:189], v[54:57]
	v_mfma_f32_16x16x32_bf16 v[50:53], v[178:181], v[186:189], v[50:53]
	v_mfma_f32_16x16x32_bf16 v[38:41], v[170:173], v[194:197], v[38:41]
	v_mfma_f32_16x16x32_bf16 v[34:37], v[178:181], v[194:197], v[34:37]
	v_mfma_f32_16x16x32_bf16 v[14:17], v[170:173], v[202:205], v[14:17]
	v_mfma_f32_16x16x32_bf16 v[10:13], v[178:181], v[202:205], v[10:13]
	v_mfma_f32_16x16x32_bf16 v[30:33], v[170:173], v[210:213], v[30:33]
	v_mfma_f32_16x16x32_bf16 v[26:29], v[178:181], v[210:213], v[26:29]
	v_mfma_f32_16x16x32_bf16 v[54:57], v[174:177], v[190:193], v[54:57]
	v_mfma_f32_16x16x32_bf16 v[50:53], v[182:185], v[190:193], v[50:53]
	v_mfma_f32_16x16x32_bf16 v[38:41], v[174:177], v[198:201], v[38:41]
	v_mfma_f32_16x16x32_bf16 v[34:37], v[182:185], v[198:201], v[34:37]
	v_mfma_f32_16x16x32_bf16 v[14:17], v[174:177], v[206:209], v[14:17]
	v_mfma_f32_16x16x32_bf16 v[10:13], v[182:185], v[206:209], v[10:13]
	v_mfma_f32_16x16x32_bf16 v[30:33], v[174:177], v[214:217], v[30:33]
	v_mfma_f32_16x16x32_bf16 v[26:29], v[182:185], v[214:217], v[26:29]
	s_setprio 0
	s_barrier
	s_add_i32 s54, s54, 2
	s_add_u32 s0, s0, 0x100
	s_addc_u32 s1, s1, 0
	s_add_u32 s52, s52, 0x100
	s_addc_u32 s53, s53, 0
	s_cmp_gt_u32 s54, 29
	s_cbranch_scc0 .LBB0_796
	s_and_b64 vcc, exec, s[16:17]
	s_cbranch_vccz .LBB0_799
	s_barrier

.LBB0_875:
	ds_read_b128 v[130:133], v192
	ds_read_b128 v[134:137], v192 offset:1024
	ds_read_b128 v[138:141], v192 offset:2048
	ds_read_b128 v[142:145], v192 offset:3072
	ds_read_b128 v[146:149], v193
	ds_read_b128 v[150:153], v193 offset:1024
	ds_read_b128 v[154:157], v193 offset:2048
	ds_read_b128 v[158:161], v193 offset:3072
	s_add_u32 s38, s0, 0xfffc0080
	s_addc_u32 s39, s1, -1
	s_cmp_eq_u32 s62, 12
	s_cselect_b32 s41, s29, s39
	s_cselect_b32 s40, s37, s38
	s_cselect_b32 s39, s27, s61
	s_cselect_b32 s38, s59, s60
	v_lshl_add_u64 v[216:217], s[0:1], 0, v[170:171]
	s_add_i32 m0, s47, 0xc000
	ds_read_b128 v[178:181], v194
	ds_read_b128 v[182:185], v194 offset:1024
	ds_read_b128 v[186:189], v194 offset:2048
	ds_read_b128 v[196:199], v194 offset:3072
	ds_read_b128 v[200:203], v194 offset:4096
	ds_read_b128 v[204:207], v194 offset:5120
	ds_read_b128 v[208:211], v194 offset:6144
	ds_read_b128 v[212:215], v194 offset:7168
	global_load_lds_dwordx4 v[216:217], off
	v_lshl_add_u64 v[216:217], s[0:1], 0, v[172:173]
	s_add_i32 m0, s47, 0xe000
	s_nop 0
	global_load_lds_dwordx4 v[216:217], off
	s_waitcnt vmcnt(8)
	s_waitcnt lgkmcnt(0)
	s_barrier
	s_setprio 1
	s_waitcnt lgkmcnt(0)
	v_mfma_f32_16x16x32_bf16 v[126:129], v[130:133], v[178:181], v[126:129]
	v_mfma_f32_16x16x32_bf16 v[122:125], v[138:141], v[178:181], v[122:125]
	v_mfma_f32_16x16x32_bf16 v[118:121], v[130:133], v[186:189], v[118:121]
	v_mfma_f32_16x16x32_bf16 v[110:113], v[138:141], v[186:189], v[110:113]
	v_mfma_f32_16x16x32_bf16 v[94:97], v[130:133], v[200:203], v[94:97]
	v_mfma_f32_16x16x32_bf16 v[90:93], v[138:141], v[200:203], v[90:93]
	v_mfma_f32_16x16x32_bf16 v[82:85], v[130:133], v[208:211], v[82:85]
	v_mfma_f32_16x16x32_bf16 v[74:77], v[138:141], v[208:211], v[74:77]
	v_mfma_f32_16x16x32_bf16 v[126:129], v[134:137], v[182:185], v[126:129]
	v_mfma_f32_16x16x32_bf16 v[122:125], v[142:145], v[182:185], v[122:125]
	v_mfma_f32_16x16x32_bf16 v[118:121], v[134:137], v[196:199], v[118:121]
	v_mfma_f32_16x16x32_bf16 v[110:113], v[142:145], v[196:199], v[110:113]
	v_mfma_f32_16x16x32_bf16 v[94:97], v[134:137], v[204:207], v[94:97]
	v_mfma_f32_16x16x32_bf16 v[90:93], v[142:145], v[204:207], v[90:93]
	v_mfma_f32_16x16x32_bf16 v[82:85], v[134:137], v[212:215], v[82:85]
	v_mfma_f32_16x16x32_bf16 v[74:77], v[142:145], v[212:215], v[74:77]
	v_mfma_f32_16x16x32_bf16 v[114:117], v[146:149], v[178:181], v[114:117]
	v_mfma_f32_16x16x32_bf16 v[106:109], v[154:157], v[178:181], v[106:109]
	v_mfma_f32_16x16x32_bf16 v[102:105], v[146:149], v[186:189], v[102:105]
	v_mfma_f32_16x16x32_bf16 v[98:101], v[154:157], v[186:189], v[98:101]
	v_mfma_f32_16x16x32_bf16 v[86:89], v[146:149], v[200:203], v[86:89]
	v_mfma_f32_16x16x32_bf16 v[78:81], v[154:157], v[200:203], v[78:81]
	v_mfma_f32_16x16x32_bf16 v[70:73], v[146:149], v[208:211], v[70:73]
	v_mfma_f32_16x16x32_bf16 v[66:69], v[154:157], v[208:211], v[66:69]
	v_mfma_f32_16x16x32_bf16 v[114:117], v[150:153], v[182:185], v[114:117]
	v_mfma_f32_16x16x32_bf16 v[106:109], v[158:161], v[182:185], v[106:109]
	v_mfma_f32_16x16x32_bf16 v[102:105], v[150:153], v[196:199], v[102:105]
	v_mfma_f32_16x16x32_bf16 v[98:101], v[158:161], v[196:199], v[98:101]
	v_mfma_f32_16x16x32_bf16 v[86:89], v[150:153], v[204:207], v[86:89]
	v_mfma_f32_16x16x32_bf16 v[78:81], v[158:161], v[204:207], v[78:81]
	v_mfma_f32_16x16x32_bf16 v[70:73], v[150:153], v[212:215], v[70:73]
	v_mfma_f32_16x16x32_bf16 v[66:69], v[158:161], v[212:215], v[66:69]
	s_setprio 0
	s_barrier
	s_add_i32 s63, s56, s46
	v_lshl_add_u64 v[216:217], s[38:39], 0, v[164:165]
	s_mov_b32 m0, s63
	ds_read_b128 v[178:181], v194 offset:16384
	ds_read_b128 v[182:185], v194 offset:17408
	ds_read_b128 v[186:189], v194 offset:18432
	ds_read_b128 v[196:199], v194 offset:19456
	ds_read_b128 v[200:203], v194 offset:20480
	ds_read_b128 v[204:207], v194 offset:21504
	ds_read_b128 v[208:211], v194 offset:22528
	ds_read_b128 v[212:215], v194 offset:23552
	global_load_lds_dwordx4 v[216:217], off
	s_add_i32 m0, s63, 0x2000
	s_add_u32 s64, s38, 0x40000
	v_lshl_add_u64 v[218:219], s[38:39], 0, v[168:169]
	s_addc_u32 s65, s39, 0
	s_add_i32 s63, s57, s46
	global_load_lds_dwordx4 v[218:219], off
	v_lshl_add_u64 v[220:221], s[64:65], 0, v[164:165]
	s_mov_b32 m0, s63
	v_lshl_add_u64 v[222:223], s[40:41], 0, v[166:167]
	global_load_lds_dwordx4 v[220:221], off
	v_lshl_add_u64 v[220:221], s[64:65], 0, v[168:169]
	s_add_i32 m0, s63, 0x2000
	s_nop 0
	global_load_lds_dwordx4 v[220:221], off
	v_lshl_add_u64 v[220:221], s[40:41], 0, v[162:163]
	s_mov_b32 m0, s47
	s_nop 0
	global_load_lds_dwordx4 v[220:221], off
	s_mov_b32 m0, s48
	s_nop 0
	global_load_lds_dwordx4 v[222:223], off
	s_waitcnt vmcnt(8)
	s_waitcnt lgkmcnt(0)
	s_barrier
	s_setprio 1
	s_waitcnt lgkmcnt(0)
	v_mfma_f32_16x16x32_bf16 v[62:65], v[130:133], v[178:181], v[62:65]
	v_mfma_f32_16x16x32_bf16 v[58:61], v[138:141], v[178:181], v[58:61]
	v_mfma_f32_16x16x32_bf16 v[50:53], v[130:133], v[186:189], v[50:53]
	v_mfma_f32_16x16x32_bf16 v[42:45], v[138:141], v[186:189], v[42:45]
	v_mfma_f32_16x16x32_bf16 v[30:33], v[130:133], v[200:203], v[30:33]
	v_mfma_f32_16x16x32_bf16 v[26:29], v[138:141], v[200:203], v[26:29]
	v_mfma_f32_16x16x32_bf16 v[14:17], v[130:133], v[208:211], v[14:17]
	v_mfma_f32_16x16x32_bf16 v[10:13], v[138:141], v[208:211], v[10:13]
	v_mfma_f32_16x16x32_bf16 v[62:65], v[134:137], v[182:185], v[62:65]
	v_mfma_f32_16x16x32_bf16 v[58:61], v[142:145], v[182:185], v[58:61]
	v_mfma_f32_16x16x32_bf16 v[50:53], v[134:137], v[196:199], v[50:53]
	v_mfma_f32_16x16x32_bf16 v[42:45], v[142:145], v[196:199], v[42:45]
	v_mfma_f32_16x16x32_bf16 v[30:33], v[134:137], v[204:207], v[30:33]
	v_mfma_f32_16x16x32_bf16 v[26:29], v[142:145], v[204:207], v[26:29]
	v_mfma_f32_16x16x32_bf16 v[14:17], v[134:137], v[212:215], v[14:17]
	v_mfma_f32_16x16x32_bf16 v[10:13], v[142:145], v[212:215], v[10:13]
	v_mfma_f32_16x16x32_bf16 v[54:57], v[146:149], v[178:181], v[54:57]
	v_mfma_f32_16x16x32_bf16 v[46:49], v[154:157], v[178:181], v[46:49]
	v_mfma_f32_16x16x32_bf16 v[38:41], v[146:149], v[186:189], v[38:41]
	v_mfma_f32_16x16x32_bf16 v[34:37], v[154:157], v[186:189], v[34:37]
	v_mfma_f32_16x16x32_bf16 v[22:25], v[146:149], v[200:203], v[22:25]
	v_mfma_f32_16x16x32_bf16 v[18:21], v[154:157], v[200:203], v[18:21]
	v_mfma_f32_16x16x32_bf16 v[6:9], v[146:149], v[208:211], v[6:9]
	v_mfma_f32_16x16x32_bf16 v[2:5], v[154:157], v[208:211], v[2:5]
	v_mfma_f32_16x16x32_bf16 v[54:57], v[150:153], v[182:185], v[54:57]
	v_mfma_f32_16x16x32_bf16 v[46:49], v[158:161], v[182:185], v[46:49]
	v_mfma_f32_16x16x32_bf16 v[38:41], v[150:153], v[196:199], v[38:41]
	v_mfma_f32_16x16x32_bf16 v[34:37], v[158:161], v[196:199], v[34:37]
	v_mfma_f32_16x16x32_bf16 v[22:25], v[150:153], v[204:207], v[22:25]
	v_mfma_f32_16x16x32_bf16 v[18:21], v[158:161], v[204:207], v[18:21]
	v_mfma_f32_16x16x32_bf16 v[6:9], v[150:153], v[212:215], v[6:9]
	v_mfma_f32_16x16x32_bf16 v[2:5], v[158:161], v[212:215], v[2:5]
	s_setprio 0
	s_barrier
	s_add_i32 s63, 0, 0x18000
	s_add_i32 s64, 0, 0x1c000
	v_add_u32_e32 v142, s63, v190
	v_add_u32_e32 v158, s64, v190
	ds_read_b128 v[130:133], v142
	ds_read_b128 v[134:137], v142 offset:1024
	ds_read_b128 v[138:141], v142 offset:2048
	ds_read_b128 v[142:145], v142 offset:3072
	ds_read_b128 v[146:149], v158
	ds_read_b128 v[150:153], v158 offset:1024
	ds_read_b128 v[154:157], v158 offset:2048
	ds_read_b128 v[158:161], v158 offset:3072
	s_add_u32 s40, s40, 0x40000
	s_addc_u32 s41, s41, 0
	s_mov_b32 m0, s49
	v_lshl_add_u64 v[224:225], s[40:41], 0, v[162:163]
	ds_read_b128 v[178:181], v194 offset:32768
	ds_read_b128 v[182:185], v194 offset:33792
	ds_read_b128 v[186:189], v194 offset:34816
	ds_read_b128 v[196:199], v194 offset:35840
	ds_read_b128 v[200:203], v194 offset:36864
	ds_read_b128 v[204:207], v194 offset:37888
	ds_read_b128 v[208:211], v194 offset:38912
	ds_read_b128 v[212:215], v194 offset:39936
	global_load_lds_dwordx4 v[224:225], off
	v_lshl_add_u64 v[224:225], s[40:41], 0, v[166:167]
	s_mov_b32 m0, s50
	s_nop 0
	global_load_lds_dwordx4 v[224:225], off
	s_waitcnt vmcnt(8)
	s_waitcnt lgkmcnt(0)
	s_barrier
	s_setprio 1
	s_waitcnt lgkmcnt(0)
	v_mfma_f32_16x16x32_bf16 v[126:129], v[130:133], v[178:181], v[126:129]
	v_mfma_f32_16x16x32_bf16 v[122:125], v[138:141], v[178:181], v[122:125]
	v_mfma_f32_16x16x32_bf16 v[118:121], v[130:133], v[186:189], v[118:121]
	v_mfma_f32_16x16x32_bf16 v[110:113], v[138:141], v[186:189], v[110:113]
	v_mfma_f32_16x16x32_bf16 v[94:97], v[130:133], v[200:203], v[94:97]
	v_mfma_f32_16x16x32_bf16 v[90:93], v[138:141], v[200:203], v[90:93]
	v_mfma_f32_16x16x32_bf16 v[82:85], v[130:133], v[208:211], v[82:85]
	v_mfma_f32_16x16x32_bf16 v[74:77], v[138:141], v[208:211], v[74:77]
	v_mfma_f32_16x16x32_bf16 v[126:129], v[134:137], v[182:185], v[126:129]
	v_mfma_f32_16x16x32_bf16 v[122:125], v[142:145], v[182:185], v[122:125]
	v_mfma_f32_16x16x32_bf16 v[118:121], v[134:137], v[196:199], v[118:121]
	v_mfma_f32_16x16x32_bf16 v[110:113], v[142:145], v[196:199], v[110:113]
	v_mfma_f32_16x16x32_bf16 v[94:97], v[134:137], v[204:207], v[94:97]
	v_mfma_f32_16x16x32_bf16 v[90:93], v[142:145], v[204:207], v[90:93]
	v_mfma_f32_16x16x32_bf16 v[82:85], v[134:137], v[212:215], v[82:85]
	v_mfma_f32_16x16x32_bf16 v[74:77], v[142:145], v[212:215], v[74:77]
	v_mfma_f32_16x16x32_bf16 v[114:117], v[146:149], v[178:181], v[114:117]
	v_mfma_f32_16x16x32_bf16 v[106:109], v[154:157], v[178:181], v[106:109]
	v_mfma_f32_16x16x32_bf16 v[102:105], v[146:149], v[186:189], v[102:105]
	v_mfma_f32_16x16x32_bf16 v[98:101], v[154:157], v[186:189], v[98:101]
	v_mfma_f32_16x16x32_bf16 v[86:89], v[146:149], v[200:203], v[86:89]
	v_mfma_f32_16x16x32_bf16 v[78:81], v[154:157], v[200:203], v[78:81]
	v_mfma_f32_16x16x32_bf16 v[70:73], v[146:149], v[208:211], v[70:73]
	v_mfma_f32_16x16x32_bf16 v[66:69], v[154:157], v[208:211], v[66:69]
	v_mfma_f32_16x16x32_bf16 v[114:117], v[150:153], v[182:185], v[114:117]
	v_mfma_f32_16x16x32_bf16 v[106:109], v[158:161], v[182:185], v[106:109]
	v_mfma_f32_16x16x32_bf16 v[102:105], v[150:153], v[196:199], v[102:105]
	v_mfma_f32_16x16x32_bf16 v[98:101], v[158:161], v[196:199], v[98:101]
	v_mfma_f32_16x16x32_bf16 v[86:89], v[150:153], v[204:207], v[86:89]
	v_mfma_f32_16x16x32_bf16 v[78:81], v[158:161], v[204:207], v[78:81]
	v_mfma_f32_16x16x32_bf16 v[70:73], v[150:153], v[212:215], v[70:73]
	v_mfma_f32_16x16x32_bf16 v[66:69], v[158:161], v[212:215], v[66:69]
	s_setprio 0
	s_barrier
	s_add_i32 s40, s63, s46
	v_lshl_add_u64 v[216:217], v[216:217], 0, s[18:19]
	s_mov_b32 m0, s40
	ds_read_b128 v[178:181], v194 offset:49152
	ds_read_b128 v[182:185], v194 offset:50176
	ds_read_b128 v[186:189], v194 offset:51200
	ds_read_b128 v[196:199], v194 offset:52224
	ds_read_b128 v[200:203], v194 offset:53248
	ds_read_b128 v[204:207], v194 offset:54272
	ds_read_b128 v[208:211], v194 offset:55296
	ds_read_b128 v[212:215], v194 offset:56320
	global_load_lds_dwordx4 v[216:217], off
	s_add_i32 m0, s40, 0x2000
	s_add_u32 s38, s38, 0x40080
	v_lshl_add_u64 v[216:217], v[218:219], 0, s[18:19]
	s_addc_u32 s39, s39, 0
	s_add_i32 s40, s64, s46
	global_load_lds_dwordx4 v[216:217], off
	v_lshl_add_u64 v[216:217], s[38:39], 0, v[164:165]
	s_mov_b32 m0, s40
	s_nop 0
	global_load_lds_dwordx4 v[216:217], off
	v_lshl_add_u64 v[216:217], s[38:39], 0, v[168:169]
	s_add_i32 m0, s40, 0x2000
	s_nop 0
	global_load_lds_dwordx4 v[216:217], off
	v_lshl_add_u64 v[216:217], v[220:221], 0, s[18:19]
	s_mov_b32 m0, s52
	s_nop 0
	global_load_lds_dwordx4 v[216:217], off
	v_lshl_add_u64 v[216:217], v[222:223], 0, s[18:19]
	s_mov_b32 m0, s53
	s_nop 0
	global_load_lds_dwordx4 v[216:217], off
	s_waitcnt vmcnt(8)
	s_waitcnt lgkmcnt(0)
	s_barrier
	s_setprio 1
	s_waitcnt lgkmcnt(0)
	v_mfma_f32_16x16x32_bf16 v[62:65], v[130:133], v[178:181], v[62:65]
	v_mfma_f32_16x16x32_bf16 v[58:61], v[138:141], v[178:181], v[58:61]
	v_mfma_f32_16x16x32_bf16 v[50:53], v[130:133], v[186:189], v[50:53]
	v_mfma_f32_16x16x32_bf16 v[42:45], v[138:141], v[186:189], v[42:45]
	v_mfma_f32_16x16x32_bf16 v[30:33], v[130:133], v[200:203], v[30:33]
	v_mfma_f32_16x16x32_bf16 v[26:29], v[138:141], v[200:203], v[26:29]
	v_mfma_f32_16x16x32_bf16 v[14:17], v[130:133], v[208:211], v[14:17]
	v_mfma_f32_16x16x32_bf16 v[10:13], v[138:141], v[208:211], v[10:13]
	v_mfma_f32_16x16x32_bf16 v[62:65], v[134:137], v[182:185], v[62:65]
	v_mfma_f32_16x16x32_bf16 v[58:61], v[142:145], v[182:185], v[58:61]
	v_mfma_f32_16x16x32_bf16 v[50:53], v[134:137], v[196:199], v[50:53]
	v_mfma_f32_16x16x32_bf16 v[42:45], v[142:145], v[196:199], v[42:45]
	v_mfma_f32_16x16x32_bf16 v[30:33], v[134:137], v[204:207], v[30:33]
	v_mfma_f32_16x16x32_bf16 v[26:29], v[142:145], v[204:207], v[26:29]
	v_mfma_f32_16x16x32_bf16 v[14:17], v[134:137], v[212:215], v[14:17]
	v_mfma_f32_16x16x32_bf16 v[10:13], v[142:145], v[212:215], v[10:13]
	v_mfma_f32_16x16x32_bf16 v[54:57], v[146:149], v[178:181], v[54:57]
	v_mfma_f32_16x16x32_bf16 v[46:49], v[154:157], v[178:181], v[46:49]
	v_mfma_f32_16x16x32_bf16 v[38:41], v[146:149], v[186:189], v[38:41]
	v_mfma_f32_16x16x32_bf16 v[34:37], v[154:157], v[186:189], v[34:37]
	v_mfma_f32_16x16x32_bf16 v[22:25], v[146:149], v[200:203], v[22:25]
	v_mfma_f32_16x16x32_bf16 v[18:21], v[154:157], v[200:203], v[18:21]
	v_mfma_f32_16x16x32_bf16 v[6:9], v[146:149], v[208:211], v[6:9]
	v_mfma_f32_16x16x32_bf16 v[2:5], v[154:157], v[208:211], v[2:5]
	v_mfma_f32_16x16x32_bf16 v[54:57], v[150:153], v[182:185], v[54:57]
	v_mfma_f32_16x16x32_bf16 v[46:49], v[158:161], v[182:185], v[46:49]
	v_mfma_f32_16x16x32_bf16 v[38:41], v[150:153], v[196:199], v[38:41]
	v_mfma_f32_16x16x32_bf16 v[34:37], v[158:161], v[196:199], v[34:37]
	v_mfma_f32_16x16x32_bf16 v[22:25], v[150:153], v[204:207], v[22:25]
	v_mfma_f32_16x16x32_bf16 v[18:21], v[158:161], v[204:207], v[18:21]
	v_mfma_f32_16x16x32_bf16 v[6:9], v[150:153], v[212:215], v[6:9]
	v_mfma_f32_16x16x32_bf16 v[2:5], v[158:161], v[212:215], v[2:5]
	s_setprio 0
	s_barrier
	s_add_i32 s62, s62, 2
	s_add_u32 s0, s0, 0x100
	s_addc_u32 s1, s1, 0
	s_add_u32 s60, s60, 0x100
	s_addc_u32 s61, s61, 0
	s_cmp_gt_u32 s62, 13
	s_cbranch_scc0 .LBB0_875
	s_and_b64 vcc, exec, s[20:21]
	s_cbranch_vccz .LBB0_878
	s_barrier

.LBB0_967:
	s_cmp_lg_u32 s12, 0
	v_mov_b32_e32 v133, v137
	v_mov_b32_e32 v135, v137
	v_mov_b32_e32 v131, v137
	s_cbranch_scc0 .LBB0_977
	ds_read_b128 v[2:5], v151
	ds_read_b128 v[6:9], v151 offset:1024
	ds_read_b128 v[10:13], v151 offset:2048
	ds_read_b128 v[14:17], v151 offset:3072
	ds_read_b128 v[18:21], v153
	ds_read_b128 v[22:25], v153 offset:1024
	ds_read_b128 v[26:29], v153 offset:2048
	ds_read_b128 v[30:33], v153 offset:3072
	ds_read_b128 v[34:37], v155
	ds_read_b128 v[38:41], v155 offset:1024
	ds_read_b128 v[42:45], v155 offset:2048
	ds_read_b128 v[46:49], v155 offset:3072
	ds_read_b128 v[50:53], v155 offset:4096
	ds_read_b128 v[54:57], v155 offset:5120
	ds_read_b128 v[58:61], v155 offset:6144
	ds_read_b128 v[62:65], v155 offset:7168
	s_waitcnt vmcnt(24)
	s_waitcnt lgkmcnt(0)
	s_barrier
	s_setprio 1
	s_waitcnt lgkmcnt(0)
	v_mfma_f32_16x16x32_bf16 v[90:93], v[2:5], v[58:61], 0
	v_mfma_f32_16x16x32_bf16 v[66:69], v[2:5], v[34:37], 0
	v_mfma_f32_16x16x32_bf16 v[70:73], v[10:13], v[34:37], 0
	v_mfma_f32_16x16x32_bf16 v[74:77], v[2:5], v[42:45], 0
	v_mfma_f32_16x16x32_bf16 v[78:81], v[10:13], v[42:45], 0
	v_mfma_f32_16x16x32_bf16 v[82:85], v[2:5], v[50:53], 0
	v_mfma_f32_16x16x32_bf16 v[86:89], v[10:13], v[50:53], 0
	v_mfma_f32_16x16x32_bf16 v[98:101], v[6:9], v[62:65], v[90:93]
	v_mfma_f32_16x16x32_bf16 v[90:93], v[10:13], v[58:61], 0
	v_mfma_f32_16x16x32_bf16 v[66:69], v[6:9], v[38:41], v[66:69]
	v_mfma_f32_16x16x32_bf16 v[70:73], v[14:17], v[38:41], v[70:73]
	v_mfma_f32_16x16x32_bf16 v[74:77], v[6:9], v[46:49], v[74:77]
	v_mfma_f32_16x16x32_bf16 v[78:81], v[14:17], v[46:49], v[78:81]
	v_mfma_f32_16x16x32_bf16 v[82:85], v[6:9], v[54:57], v[82:85]
	v_mfma_f32_16x16x32_bf16 v[86:89], v[14:17], v[54:57], v[86:89]
	v_mfma_f32_16x16x32_bf16 v[102:105], v[14:17], v[62:65], v[90:93]
	v_mfma_f32_16x16x32_bf16 v[90:93], v[18:21], v[34:37], 0
	v_mfma_f32_16x16x32_bf16 v[34:37], v[26:29], v[34:37], 0
	v_mfma_f32_16x16x32_bf16 v[114:117], v[22:25], v[38:41], v[90:93]
	v_mfma_f32_16x16x32_bf16 v[34:37], v[30:33], v[38:41], v[34:37]
	v_mfma_f32_16x16x32_bf16 v[38:41], v[18:21], v[42:45], 0
	v_mfma_f32_16x16x32_bf16 v[42:45], v[26:29], v[42:45], 0
	v_mfma_f32_16x16x32_bf16 v[38:41], v[22:25], v[46:49], v[38:41]
	v_mfma_f32_16x16x32_bf16 v[42:45], v[30:33], v[46:49], v[42:45]
	v_mfma_f32_16x16x32_bf16 v[46:49], v[18:21], v[50:53], 0
	v_mfma_f32_16x16x32_bf16 v[50:53], v[26:29], v[50:53], 0
	v_mfma_f32_16x16x32_bf16 v[46:49], v[22:25], v[54:57], v[46:49]
	v_mfma_f32_16x16x32_bf16 v[50:53], v[30:33], v[54:57], v[50:53]
	v_mfma_f32_16x16x32_bf16 v[54:57], v[18:21], v[58:61], 0
	v_mfma_f32_16x16x32_bf16 v[58:61], v[26:29], v[58:61], 0
	v_mfma_f32_16x16x32_bf16 v[54:57], v[22:25], v[62:65], v[54:57]
	v_mfma_f32_16x16x32_bf16 v[58:61], v[30:33], v[62:65], v[58:61]
	s_setprio 0
	s_barrier
	v_lshl_add_u64 v[248:249], s[0:1], 0, v[132:133]
	s_add_i32 s8, s57, s45
	v_lshl_add_u64 v[142:143], v[248:249], 0, s[24:25]
	s_mov_b32 m0, s8
	ds_read_b128 v[62:65], v155 offset:16384
	ds_read_b128 v[90:93], v155 offset:17408
	ds_read_b128 v[94:97], v155 offset:18432
	ds_read_b128 v[106:109], v155 offset:19456
	ds_read_b128 v[110:113], v155 offset:20480
	ds_read_b128 v[118:121], v155 offset:21504
	ds_read_b128 v[122:125], v155 offset:22528
	ds_read_b128 v[126:129], v155 offset:23552
	global_load_lds_dwordx4 v[142:143], off
	s_add_i32 m0, s8, 0x2000
	v_lshl_add_u64 v[250:251], s[0:1], 0, v[136:137]
	s_add_u32 s8, s0, 0x10100
	v_lshl_add_u64 v[142:143], v[250:251], 0, s[24:25]
	s_addc_u32 s9, s1, 0
	s_add_i32 s12, s58, s45
	global_load_lds_dwordx4 v[142:143], off
	s_mov_b32 m0, s12
	v_lshl_add_u64 v[252:253], s[6:7], 0, v[130:131]
	global_load_lds_dwordx4 v132, s[8:9]
	s_add_i32 m0, s12, 0x2000
	v_lshl_add_u64 v[142:143], v[252:253], 0, s[24:25]
	global_load_lds_dwordx4 v136, s[8:9]
	s_mov_b32 m0, s46
	v_lshl_add_u64 v[138:139], s[6:7], 0, v[134:135]
	global_load_lds_dwordx4 v[142:143], off
	v_lshl_add_u64 v[142:143], v[138:139], 0, s[24:25]
	s_mov_b32 m0, s47
	s_nop 0
	global_load_lds_dwordx4 v[142:143], off
	s_waitcnt vmcnt(24)
	s_waitcnt lgkmcnt(0)
	s_barrier
	s_setprio 1
	s_waitcnt lgkmcnt(0)
	v_mfma_f32_16x16x32_bf16 v[142:145], v[2:5], v[62:65], 0
	v_mfma_f32_16x16x32_bf16 v[160:163], v[2:5], v[94:97], 0
	v_mfma_f32_16x16x32_bf16 v[168:171], v[2:5], v[110:113], 0
	v_mfma_f32_16x16x32_bf16 v[2:5], v[2:5], v[122:125], 0
	v_mfma_f32_16x16x32_bf16 v[142:145], v[6:9], v[90:93], v[142:145]
	v_mfma_f32_16x16x32_bf16 v[160:163], v[6:9], v[106:109], v[160:163]
	v_mfma_f32_16x16x32_bf16 v[168:171], v[6:9], v[118:121], v[168:171]
	v_mfma_f32_16x16x32_bf16 v[2:5], v[6:9], v[126:129], v[2:5]
	v_mfma_f32_16x16x32_bf16 v[6:9], v[10:13], v[122:125], 0
	v_mfma_f32_16x16x32_bf16 v[156:159], v[10:13], v[62:65], 0
	v_mfma_f32_16x16x32_bf16 v[164:167], v[10:13], v[94:97], 0
	v_mfma_f32_16x16x32_bf16 v[172:175], v[10:13], v[110:113], 0
	v_mfma_f32_16x16x32_bf16 v[6:9], v[14:17], v[126:129], v[6:9]
	v_mfma_f32_16x16x32_bf16 v[156:159], v[14:17], v[90:93], v[156:159]
	v_mfma_f32_16x16x32_bf16 v[164:167], v[14:17], v[106:109], v[164:167]
	v_mfma_f32_16x16x32_bf16 v[172:175], v[14:17], v[118:121], v[172:175]
	v_mfma_f32_16x16x32_bf16 v[10:13], v[18:21], v[62:65], 0
	v_mfma_f32_16x16x32_bf16 v[176:179], v[22:25], v[90:93], v[10:13]
	v_mfma_f32_16x16x32_bf16 v[10:13], v[26:29], v[62:65], 0
	v_mfma_f32_16x16x32_bf16 v[180:183], v[30:33], v[90:93], v[10:13]
	v_mfma_f32_16x16x32_bf16 v[10:13], v[18:21], v[94:97], 0
	v_mfma_f32_16x16x32_bf16 v[184:187], v[22:25], v[106:109], v[10:13]
	v_mfma_f32_16x16x32_bf16 v[10:13], v[26:29], v[94:97], 0
	v_mfma_f32_16x16x32_bf16 v[188:191], v[30:33], v[106:109], v[10:13]
	v_mfma_f32_16x16x32_bf16 v[10:13], v[18:21], v[110:113], 0
	v_mfma_f32_16x16x32_bf16 v[192:195], v[22:25], v[118:121], v[10:13]
	v_mfma_f32_16x16x32_bf16 v[10:13], v[26:29], v[110:113], 0
	v_mfma_f32_16x16x32_bf16 v[196:199], v[30:33], v[118:121], v[10:13]
	v_mfma_f32_16x16x32_bf16 v[10:13], v[18:21], v[122:125], 0
	v_mfma_f32_16x16x32_bf16 v[200:203], v[22:25], v[126:129], v[10:13]
	v_mfma_f32_16x16x32_bf16 v[10:13], v[26:29], v[122:125], 0
	v_mfma_f32_16x16x32_bf16 v[204:207], v[30:33], v[126:129], v[10:13]
	s_setprio 0
	s_barrier
	s_add_i32 s12, 0, 0x18000
	s_add_i32 s35, 0, 0x1c000
	v_add_u32_e32 v22, s12, v149
	v_add_u32_e32 v26, s35, v149
	s_nop 0
	ds_read_b128 v[10:13], v22
	ds_read_b128 v[14:17], v22 offset:1024
	ds_read_b128 v[18:21], v22 offset:2048
	ds_read_b128 v[22:25], v22 offset:3072
	ds_read_b128 v[208:211], v26
	ds_read_b128 v[212:215], v26 offset:1024
	ds_read_b128 v[216:219], v26 offset:2048
	ds_read_b128 v[220:223], v26 offset:3072
	s_add_u32 s8, s6, 0x40100
	s_addc_u32 s9, s7, 0
	s_mov_b32 m0, s48
	ds_read_b128 v[26:29], v155 offset:32768
	ds_read_b128 v[30:33], v155 offset:33792
	ds_read_b128 v[62:65], v155 offset:34816
	ds_read_b128 v[224:227], v155 offset:35840
	ds_read_b128 v[228:231], v155 offset:36864
	ds_read_b128 v[232:235], v155 offset:37888
	ds_read_b128 v[236:239], v155 offset:38912
	ds_read_b128 v[240:243], v155 offset:39936
	global_load_lds_dwordx4 v130, s[8:9]
	s_mov_b32 m0, s49
	s_nop 0
	global_load_lds_dwordx4 v134, s[8:9]
	s_waitcnt vmcnt(24)
	s_waitcnt lgkmcnt(0)
	s_barrier
	s_setprio 1
	s_waitcnt lgkmcnt(0)
	v_mfma_f32_16x16x32_bf16 v[66:69], v[10:13], v[26:29], v[66:69]
	v_mfma_f32_16x16x32_bf16 v[126:129], v[14:17], v[30:33], v[66:69]
	v_mfma_f32_16x16x32_bf16 v[66:69], v[18:21], v[26:29], v[70:73]
	v_mfma_f32_16x16x32_bf16 v[122:125], v[22:25], v[30:33], v[66:69]
	v_mfma_f32_16x16x32_bf16 v[66:69], v[10:13], v[62:65], v[74:77]
	v_mfma_f32_16x16x32_bf16 v[110:113], v[14:17], v[224:227], v[66:69]
	v_mfma_f32_16x16x32_bf16 v[66:69], v[18:21], v[62:65], v[78:81]
	v_mfma_f32_16x16x32_bf16 v[106:109], v[22:25], v[224:227], v[66:69]
	v_mfma_f32_16x16x32_bf16 v[66:69], v[10:13], v[228:231], v[82:85]
	v_mfma_f32_16x16x32_bf16 v[94:97], v[14:17], v[232:235], v[66:69]
	v_mfma_f32_16x16x32_bf16 v[66:69], v[18:21], v[228:231], v[86:89]
	v_mfma_f32_16x16x32_bf16 v[90:93], v[22:25], v[232:235], v[66:69]
	v_mfma_f32_16x16x32_bf16 v[66:69], v[10:13], v[236:239], v[98:101]
	v_mfma_f32_16x16x32_bf16 v[78:81], v[14:17], v[240:243], v[66:69]
	v_mfma_f32_16x16x32_bf16 v[66:69], v[18:21], v[236:239], v[102:105]
	v_mfma_f32_16x16x32_bf16 v[74:77], v[22:25], v[240:243], v[66:69]
	v_mfma_f32_16x16x32_bf16 v[66:69], v[208:211], v[26:29], v[114:117]
	v_mfma_f32_16x16x32_bf16 v[26:29], v[216:219], v[26:29], v[34:37]
	v_mfma_f32_16x16x32_bf16 v[114:117], v[220:223], v[30:33], v[26:29]
	v_mfma_f32_16x16x32_bf16 v[26:29], v[208:211], v[62:65], v[38:41]
	v_mfma_f32_16x16x32_bf16 v[102:105], v[212:215], v[224:227], v[26:29]
	v_mfma_f32_16x16x32_bf16 v[26:29], v[216:219], v[62:65], v[42:45]
	v_mfma_f32_16x16x32_bf16 v[98:101], v[220:223], v[224:227], v[26:29]
	v_mfma_f32_16x16x32_bf16 v[26:29], v[208:211], v[228:231], v[46:49]
	v_mfma_f32_16x16x32_bf16 v[86:89], v[212:215], v[232:235], v[26:29]
	v_mfma_f32_16x16x32_bf16 v[26:29], v[216:219], v[228:231], v[50:53]
	v_mfma_f32_16x16x32_bf16 v[82:85], v[220:223], v[232:235], v[26:29]
	v_mfma_f32_16x16x32_bf16 v[26:29], v[208:211], v[236:239], v[54:57]
	v_mfma_f32_16x16x32_bf16 v[70:73], v[212:215], v[240:243], v[26:29]
	v_mfma_f32_16x16x32_bf16 v[26:29], v[216:219], v[236:239], v[58:61]
	v_mfma_f32_16x16x32_bf16 v[118:121], v[212:215], v[30:33], v[66:69]
	v_mfma_f32_16x16x32_bf16 v[66:69], v[220:223], v[240:243], v[26:29]
	s_setprio 0
	s_barrier
	s_add_i32 s8, s12, s45
	s_nop 2
	v_lshl_add_u64 v[26:27], v[248:249], 0, s[26:27]
	s_mov_b32 m0, s8
	ds_read_b128 v[34:37], v155 offset:49152
	ds_read_b128 v[38:41], v155 offset:50176
	ds_read_b128 v[224:227], v155 offset:51200
	ds_read_b128 v[228:231], v155 offset:52224
	ds_read_b128 v[232:235], v155 offset:53248
	ds_read_b128 v[236:239], v155 offset:54272
	ds_read_b128 v[240:243], v155 offset:55296
	ds_read_b128 v[244:247], v155 offset:56320
	global_load_lds_dwordx4 v[26:27], off
	s_add_i32 m0, s8, 0x2000
	s_add_u32 s8, s0, 0x10180
	v_lshl_add_u64 v[26:27], v[250:251], 0, s[26:27]
	s_addc_u32 s9, s1, 0
	s_add_i32 s12, s35, s45
	global_load_lds_dwordx4 v[26:27], off
	s_mov_b32 m0, s12
	v_lshl_add_u64 v[26:27], v[252:253], 0, s[26:27]
	global_load_lds_dwordx4 v132, s[8:9]
	s_add_i32 m0, s12, 0x2000
	s_nop 0
	global_load_lds_dwordx4 v136, s[8:9]
	s_mov_b32 m0, s53
	s_nop 0
	global_load_lds_dwordx4 v[26:27], off
	v_lshl_add_u64 v[26:27], v[138:139], 0, s[26:27]
	s_mov_b32 m0, s54
	s_nop 0
	global_load_lds_dwordx4 v[26:27], off
	s_waitcnt vmcnt(8)
	s_waitcnt lgkmcnt(0)
	s_barrier
	s_setprio 1
	s_waitcnt lgkmcnt(0)
	v_mfma_f32_16x16x32_bf16 v[26:29], v[10:13], v[34:37], v[142:145]
	v_mfma_f32_16x16x32_bf16 v[62:65], v[14:17], v[38:41], v[26:29]
	v_mfma_f32_16x16x32_bf16 v[26:29], v[18:21], v[34:37], v[156:159]
	v_mfma_f32_16x16x32_bf16 v[58:61], v[22:25], v[38:41], v[26:29]
	v_mfma_f32_16x16x32_bf16 v[26:29], v[10:13], v[224:227], v[160:163]
	v_mfma_f32_16x16x32_bf16 v[46:49], v[14:17], v[228:231], v[26:29]
	v_mfma_f32_16x16x32_bf16 v[26:29], v[18:21], v[224:227], v[164:167]
	v_mfma_f32_16x16x32_bf16 v[42:45], v[22:25], v[228:231], v[26:29]
	v_mfma_f32_16x16x32_bf16 v[26:29], v[10:13], v[232:235], v[168:171]
	v_mfma_f32_16x16x32_bf16 v[2:5], v[10:13], v[240:243], v[2:5]
	v_mfma_f32_16x16x32_bf16 v[30:33], v[14:17], v[236:239], v[26:29]
	v_mfma_f32_16x16x32_bf16 v[26:29], v[18:21], v[232:235], v[172:175]
	v_mfma_f32_16x16x32_bf16 v[14:17], v[14:17], v[244:247], v[2:5]
	v_mfma_f32_16x16x32_bf16 v[2:5], v[18:21], v[240:243], v[6:9]
	v_mfma_f32_16x16x32_bf16 v[26:29], v[22:25], v[236:239], v[26:29]
	v_mfma_f32_16x16x32_bf16 v[10:13], v[22:25], v[244:247], v[2:5]
	v_mfma_f32_16x16x32_bf16 v[2:5], v[208:211], v[34:37], v[176:179]
	v_mfma_f32_16x16x32_bf16 v[54:57], v[212:215], v[38:41], v[2:5]
	v_mfma_f32_16x16x32_bf16 v[2:5], v[216:219], v[34:37], v[180:183]
	v_mfma_f32_16x16x32_bf16 v[50:53], v[220:223], v[38:41], v[2:5]
	v_mfma_f32_16x16x32_bf16 v[2:5], v[208:211], v[224:227], v[184:187]
	v_mfma_f32_16x16x32_bf16 v[38:41], v[212:215], v[228:231], v[2:5]
	v_mfma_f32_16x16x32_bf16 v[2:5], v[216:219], v[224:227], v[188:191]
	v_mfma_f32_16x16x32_bf16 v[34:37], v[220:223], v[228:231], v[2:5]
	v_mfma_f32_16x16x32_bf16 v[2:5], v[208:211], v[232:235], v[192:195]
	v_mfma_f32_16x16x32_bf16 v[22:25], v[212:215], v[236:239], v[2:5]
	v_mfma_f32_16x16x32_bf16 v[2:5], v[216:219], v[232:235], v[196:199]
	v_mfma_f32_16x16x32_bf16 v[18:21], v[220:223], v[236:239], v[2:5]
	v_mfma_f32_16x16x32_bf16 v[2:5], v[208:211], v[240:243], v[200:203]
	v_mfma_f32_16x16x32_bf16 v[6:9], v[212:215], v[244:247], v[2:5]
	v_mfma_f32_16x16x32_bf16 v[2:5], v[216:219], v[240:243], v[204:207]
	v_mfma_f32_16x16x32_bf16 v[2:5], v[220:223], v[244:247], v[2:5]
	s_setprio 0
	s_barrier
	s_mov_b32 s8, 2
	s_cbranch_execnz .LBB0_970

.LBB0_971:
	ds_read_b128 v[156:159], v151
	ds_read_b128 v[160:163], v151 offset:1024
	ds_read_b128 v[164:167], v151 offset:2048
	ds_read_b128 v[168:171], v151 offset:3072
	ds_read_b128 v[172:175], v153
	ds_read_b128 v[176:179], v153 offset:1024
	ds_read_b128 v[180:183], v153 offset:2048
	ds_read_b128 v[184:187], v153 offset:3072
	s_add_u32 s6, s64, s12
	s_addc_u32 s7, s65, 0
	s_add_u32 s68, s66, s12
	s_addc_u32 s69, s67, 0
	s_cmp_eq_u32 s12, s0
	s_cselect_b32 s9, s37, s7
	s_cselect_b32 s8, s61, s6
	s_cselect_b32 s7, s35, s69
	s_cselect_b32 s6, s62, s68
	s_add_i32 s69, s46, 0xc000
	v_lshl_add_u64 v[138:139], v[142:143], 0, s[12:13]
	s_mov_b32 m0, s69
	s_add_i32 s68, s46, 0xe000
	ds_read_b128 v[188:191], v155
	ds_read_b128 v[192:195], v155 offset:1024
	ds_read_b128 v[196:199], v155 offset:2048
	ds_read_b128 v[200:203], v155 offset:3072
	ds_read_b128 v[204:207], v155 offset:4096
	ds_read_b128 v[208:211], v155 offset:5120
	ds_read_b128 v[212:215], v155 offset:6144
	ds_read_b128 v[216:219], v155 offset:7168
	global_load_lds_dwordx4 v[138:139], off
	v_lshl_add_u64 v[138:139], v[144:145], 0, s[12:13]
	s_mov_b32 m0, s68
	s_nop 0
	global_load_lds_dwordx4 v[138:139], off
	s_waitcnt vmcnt(8)
	s_waitcnt lgkmcnt(0)
	s_barrier
	s_setprio 1
	s_waitcnt lgkmcnt(0)
	v_mfma_f32_16x16x32_bf16 v[126:129], v[156:159], v[188:191], v[126:129]
	v_mfma_f32_16x16x32_bf16 v[122:125], v[164:167], v[188:191], v[122:125]
	v_mfma_f32_16x16x32_bf16 v[110:113], v[156:159], v[196:199], v[110:113]
	v_mfma_f32_16x16x32_bf16 v[106:109], v[164:167], v[196:199], v[106:109]
	v_mfma_f32_16x16x32_bf16 v[94:97], v[156:159], v[204:207], v[94:97]
	v_mfma_f32_16x16x32_bf16 v[90:93], v[164:167], v[204:207], v[90:93]
	v_mfma_f32_16x16x32_bf16 v[78:81], v[156:159], v[212:215], v[78:81]
	v_mfma_f32_16x16x32_bf16 v[74:77], v[164:167], v[212:215], v[74:77]
	v_mfma_f32_16x16x32_bf16 v[126:129], v[160:163], v[192:195], v[126:129]
	v_mfma_f32_16x16x32_bf16 v[122:125], v[168:171], v[192:195], v[122:125]
	v_mfma_f32_16x16x32_bf16 v[110:113], v[160:163], v[200:203], v[110:113]
	v_mfma_f32_16x16x32_bf16 v[106:109], v[168:171], v[200:203], v[106:109]
	v_mfma_f32_16x16x32_bf16 v[94:97], v[160:163], v[208:211], v[94:97]
	v_mfma_f32_16x16x32_bf16 v[90:93], v[168:171], v[208:211], v[90:93]
	v_mfma_f32_16x16x32_bf16 v[78:81], v[160:163], v[216:219], v[78:81]
	v_mfma_f32_16x16x32_bf16 v[74:77], v[168:171], v[216:219], v[74:77]
	v_mfma_f32_16x16x32_bf16 v[118:121], v[172:175], v[188:191], v[118:121]
	v_mfma_f32_16x16x32_bf16 v[114:117], v[180:183], v[188:191], v[114:117]
	v_mfma_f32_16x16x32_bf16 v[102:105], v[172:175], v[196:199], v[102:105]
	v_mfma_f32_16x16x32_bf16 v[98:101], v[180:183], v[196:199], v[98:101]
	v_mfma_f32_16x16x32_bf16 v[86:89], v[172:175], v[204:207], v[86:89]
	v_mfma_f32_16x16x32_bf16 v[82:85], v[180:183], v[204:207], v[82:85]
	v_mfma_f32_16x16x32_bf16 v[70:73], v[172:175], v[212:215], v[70:73]
	v_mfma_f32_16x16x32_bf16 v[66:69], v[180:183], v[212:215], v[66:69]
	v_mfma_f32_16x16x32_bf16 v[118:121], v[176:179], v[192:195], v[118:121]
	v_mfma_f32_16x16x32_bf16 v[114:117], v[184:187], v[192:195], v[114:117]
	v_mfma_f32_16x16x32_bf16 v[102:105], v[176:179], v[200:203], v[102:105]
	v_mfma_f32_16x16x32_bf16 v[98:101], v[184:187], v[200:203], v[98:101]
	v_mfma_f32_16x16x32_bf16 v[86:89], v[176:179], v[208:211], v[86:89]
	v_mfma_f32_16x16x32_bf16 v[82:85], v[184:187], v[208:211], v[82:85]
	v_mfma_f32_16x16x32_bf16 v[70:73], v[176:179], v[216:219], v[70:73]
	v_mfma_f32_16x16x32_bf16 v[66:69], v[184:187], v[216:219], v[66:69]
	s_setprio 0
	s_barrier
	s_cmp_lg_u32 s12, s0
	s_cbranch_scc1 .Lmy_p8_noload
	s_lshl_b32 s98, s4, 14
	v_lshl_add_u32 v252, v0, 5, s98
	global_load_dwordx4 v[228:231], v252, s[16:17]
	global_load_dwordx4 v[232:235], v252, s[16:17] offset:16
.Lmy_p8_noload:
	s_add_i32 s70, s57, s45
	v_lshl_add_u64 v[138:139], s[6:7], 0, v[132:133]
	s_mov_b32 m0, s70
	ds_read_b128 v[188:191], v155 offset:16384
	ds_read_b128 v[192:195], v155 offset:17408
	ds_read_b128 v[196:199], v155 offset:18432
	ds_read_b128 v[200:203], v155 offset:19456
	ds_read_b128 v[204:207], v155 offset:20480
	ds_read_b128 v[208:211], v155 offset:21504
	ds_read_b128 v[212:215], v155 offset:22528
	ds_read_b128 v[216:219], v155 offset:23552
	global_load_lds_dwordx4 v[138:139], off
	s_add_i32 m0, s70, 0x2000
	s_add_u32 s70, s6, 0x10000
	v_lshl_add_u64 v[220:221], s[6:7], 0, v[136:137]
	s_addc_u32 s71, s7, 0
	s_add_i32 s72, s58, s45
	global_load_lds_dwordx4 v[220:221], off
	v_lshl_add_u64 v[222:223], s[70:71], 0, v[132:133]
	s_mov_b32 m0, s72
	v_lshl_add_u64 v[224:225], s[8:9], 0, v[134:135]
	global_load_lds_dwordx4 v[222:223], off
	v_lshl_add_u64 v[222:223], s[70:71], 0, v[136:137]
	s_add_i32 m0, s72, 0x2000
	s_nop 0
	global_load_lds_dwordx4 v[222:223], off
	v_lshl_add_u64 v[222:223], s[8:9], 0, v[130:131]
	s_mov_b32 m0, s46
	s_nop 0
	global_load_lds_dwordx4 v[222:223], off
	s_mov_b32 m0, s47
	s_nop 0
	global_load_lds_dwordx4 v[224:225], off
	s_waitcnt vmcnt(8)
	s_waitcnt lgkmcnt(0)
	s_barrier
	s_setprio 1
	s_waitcnt lgkmcnt(0)
	v_mfma_f32_16x16x32_bf16 v[62:65], v[156:159], v[188:191], v[62:65]
	v_mfma_f32_16x16x32_bf16 v[58:61], v[164:167], v[188:191], v[58:61]
	v_mfma_f32_16x16x32_bf16 v[46:49], v[156:159], v[196:199], v[46:49]
	v_mfma_f32_16x16x32_bf16 v[42:45], v[164:167], v[196:199], v[42:45]
	v_mfma_f32_16x16x32_bf16 v[30:33], v[156:159], v[204:207], v[30:33]
	v_mfma_f32_16x16x32_bf16 v[26:29], v[164:167], v[204:207], v[26:29]
	v_mfma_f32_16x16x32_bf16 v[14:17], v[156:159], v[212:215], v[14:17]
	v_mfma_f32_16x16x32_bf16 v[10:13], v[164:167], v[212:215], v[10:13]
	v_mfma_f32_16x16x32_bf16 v[62:65], v[160:163], v[192:195], v[62:65]
	v_mfma_f32_16x16x32_bf16 v[58:61], v[168:171], v[192:195], v[58:61]
	v_mfma_f32_16x16x32_bf16 v[46:49], v[160:163], v[200:203], v[46:49]
	v_mfma_f32_16x16x32_bf16 v[42:45], v[168:171], v[200:203], v[42:45]
	v_mfma_f32_16x16x32_bf16 v[30:33], v[160:163], v[208:211], v[30:33]
	v_mfma_f32_16x16x32_bf16 v[26:29], v[168:171], v[208:211], v[26:29]
	v_mfma_f32_16x16x32_bf16 v[14:17], v[160:163], v[216:219], v[14:17]
	v_mfma_f32_16x16x32_bf16 v[10:13], v[168:171], v[216:219], v[10:13]
	v_mfma_f32_16x16x32_bf16 v[54:57], v[172:175], v[188:191], v[54:57]
	v_mfma_f32_16x16x32_bf16 v[50:53], v[180:183], v[188:191], v[50:53]
	v_mfma_f32_16x16x32_bf16 v[38:41], v[172:175], v[196:199], v[38:41]
	v_mfma_f32_16x16x32_bf16 v[34:37], v[180:183], v[196:199], v[34:37]
	v_mfma_f32_16x16x32_bf16 v[22:25], v[172:175], v[204:207], v[22:25]
	v_mfma_f32_16x16x32_bf16 v[18:21], v[180:183], v[204:207], v[18:21]
	v_mfma_f32_16x16x32_bf16 v[6:9], v[172:175], v[212:215], v[6:9]
	v_mfma_f32_16x16x32_bf16 v[2:5], v[180:183], v[212:215], v[2:5]
	v_mfma_f32_16x16x32_bf16 v[54:57], v[176:179], v[192:195], v[54:57]
	v_mfma_f32_16x16x32_bf16 v[50:53], v[184:187], v[192:195], v[50:53]
	v_mfma_f32_16x16x32_bf16 v[38:41], v[176:179], v[200:203], v[38:41]
	v_mfma_f32_16x16x32_bf16 v[34:37], v[184:187], v[200:203], v[34:37]
	v_mfma_f32_16x16x32_bf16 v[22:25], v[176:179], v[208:211], v[22:25]
	v_mfma_f32_16x16x32_bf16 v[18:21], v[184:187], v[208:211], v[18:21]
	v_mfma_f32_16x16x32_bf16 v[6:9], v[176:179], v[216:219], v[6:9]
	v_mfma_f32_16x16x32_bf16 v[2:5], v[184:187], v[216:219], v[2:5]
	s_setprio 0
	s_barrier
	s_add_i32 s70, 0, 0x18000
	v_add_u32_e32 v146, s70, v149
	s_add_i32 s71, 0, 0x1c000
	ds_read_b128 v[156:159], v146
	ds_read_b128 v[160:163], v146 offset:1024
	ds_read_b128 v[164:167], v146 offset:2048
	ds_read_b128 v[168:171], v146 offset:3072
	v_add_u32_e32 v146, s71, v149
	ds_read_b128 v[172:175], v146
	ds_read_b128 v[176:179], v146 offset:1024
	ds_read_b128 v[180:183], v146 offset:2048
	ds_read_b128 v[184:187], v146 offset:3072
	s_add_u32 s8, s8, 0x40000
	s_addc_u32 s9, s9, 0
	s_mov_b32 m0, s48
	v_lshl_add_u64 v[226:227], s[8:9], 0, v[130:131]
	ds_read_b128 v[188:191], v155 offset:32768
	ds_read_b128 v[192:195], v155 offset:33792
	ds_read_b128 v[196:199], v155 offset:34816
	ds_read_b128 v[200:203], v155 offset:35840
	ds_read_b128 v[204:207], v155 offset:36864
	ds_read_b128 v[208:211], v155 offset:37888
	ds_read_b128 v[212:215], v155 offset:38912
	ds_read_b128 v[216:219], v155 offset:39936
	global_load_lds_dwordx4 v[226:227], off
	v_lshl_add_u64 v[226:227], s[8:9], 0, v[134:135]
	s_mov_b32 m0, s49
	s_nop 0
	global_load_lds_dwordx4 v[226:227], off
	s_waitcnt vmcnt(8)
	s_waitcnt lgkmcnt(0)
	s_barrier
	s_setprio 1
	s_waitcnt lgkmcnt(0)
	v_mfma_f32_16x16x32_bf16 v[126:129], v[156:159], v[188:191], v[126:129]
	v_mfma_f32_16x16x32_bf16 v[122:125], v[164:167], v[188:191], v[122:125]
	v_mfma_f32_16x16x32_bf16 v[110:113], v[156:159], v[196:199], v[110:113]
	v_mfma_f32_16x16x32_bf16 v[106:109], v[164:167], v[196:199], v[106:109]
	v_mfma_f32_16x16x32_bf16 v[94:97], v[156:159], v[204:207], v[94:97]
	v_mfma_f32_16x16x32_bf16 v[90:93], v[164:167], v[204:207], v[90:93]
	v_mfma_f32_16x16x32_bf16 v[78:81], v[156:159], v[212:215], v[78:81]
	v_mfma_f32_16x16x32_bf16 v[74:77], v[164:167], v[212:215], v[74:77]
	v_mfma_f32_16x16x32_bf16 v[126:129], v[160:163], v[192:195], v[126:129]
	v_mfma_f32_16x16x32_bf16 v[122:125], v[168:171], v[192:195], v[122:125]
	v_mfma_f32_16x16x32_bf16 v[110:113], v[160:163], v[200:203], v[110:113]
	v_mfma_f32_16x16x32_bf16 v[106:109], v[168:171], v[200:203], v[106:109]
	v_mfma_f32_16x16x32_bf16 v[94:97], v[160:163], v[208:211], v[94:97]
	v_mfma_f32_16x16x32_bf16 v[90:93], v[168:171], v[208:211], v[90:93]
	v_mfma_f32_16x16x32_bf16 v[78:81], v[160:163], v[216:219], v[78:81]
	v_mfma_f32_16x16x32_bf16 v[74:77], v[168:171], v[216:219], v[74:77]
	v_mfma_f32_16x16x32_bf16 v[118:121], v[172:175], v[188:191], v[118:121]
	v_mfma_f32_16x16x32_bf16 v[114:117], v[180:183], v[188:191], v[114:117]
	v_mfma_f32_16x16x32_bf16 v[102:105], v[172:175], v[196:199], v[102:105]
	v_mfma_f32_16x16x32_bf16 v[98:101], v[180:183], v[196:199], v[98:101]
	v_mfma_f32_16x16x32_bf16 v[86:89], v[172:175], v[204:207], v[86:89]
	v_mfma_f32_16x16x32_bf16 v[82:85], v[180:183], v[204:207], v[82:85]
	v_mfma_f32_16x16x32_bf16 v[70:73], v[172:175], v[212:215], v[70:73]
	v_mfma_f32_16x16x32_bf16 v[66:69], v[180:183], v[212:215], v[66:69]
	v_mfma_f32_16x16x32_bf16 v[118:121], v[176:179], v[192:195], v[118:121]
	v_mfma_f32_16x16x32_bf16 v[114:117], v[184:187], v[192:195], v[114:117]
	v_mfma_f32_16x16x32_bf16 v[102:105], v[176:179], v[200:203], v[102:105]
	v_mfma_f32_16x16x32_bf16 v[98:101], v[184:187], v[200:203], v[98:101]
	v_mfma_f32_16x16x32_bf16 v[86:89], v[176:179], v[208:211], v[86:89]
	v_mfma_f32_16x16x32_bf16 v[82:85], v[184:187], v[208:211], v[82:85]
	v_mfma_f32_16x16x32_bf16 v[70:73], v[176:179], v[216:219], v[70:73]
	v_mfma_f32_16x16x32_bf16 v[66:69], v[184:187], v[216:219], v[66:69]
	s_setprio 0
	s_barrier
	s_cmp_lg_u32 s12, s0
	s_cbranch_scc1 .Lmy_p8_nostat
	v_add_f32_e32 v236, v228, v229
	v_add_f32_e32 v240, v230, v231
	v_add_f32_e32 v237, v232, v233
	v_add_f32_e32 v241, v234, v235
	v_add_f32_e32 v236, v236, v240
	v_add_f32_e32 v237, v237, v241
	v_mov_b32_e32 v240, 0x20800
	v_lshl_add_u32 v240, v0, 3, v240
	ds_write_b64 v240, v[236:237]
.Lmy_p8_nostat:
	s_add_i32 s8, s70, s45
	v_lshl_add_u64 v[138:139], v[138:139], 0, s[20:21]
	s_mov_b32 m0, s8
	ds_read_b128 v[188:191], v155 offset:49152
	ds_read_b128 v[192:195], v155 offset:50176
	ds_read_b128 v[196:199], v155 offset:51200
	ds_read_b128 v[200:203], v155 offset:52224
	ds_read_b128 v[204:207], v155 offset:53248
	ds_read_b128 v[208:211], v155 offset:54272
	ds_read_b128 v[212:215], v155 offset:55296
	ds_read_b128 v[216:219], v155 offset:56320
	global_load_lds_dwordx4 v[138:139], off
	s_add_i32 m0, s8, 0x2000
	s_add_u32 s6, s6, 0x10080
	v_lshl_add_u64 v[138:139], v[220:221], 0, s[20:21]
	s_addc_u32 s7, s7, 0
	s_add_i32 s8, s71, s45
	global_load_lds_dwordx4 v[138:139], off
	v_lshl_add_u64 v[138:139], s[6:7], 0, v[132:133]
	s_mov_b32 m0, s8
	s_nop 0
	global_load_lds_dwordx4 v[138:139], off
	v_lshl_add_u64 v[138:139], s[6:7], 0, v[136:137]
	s_add_i32 m0, s8, 0x2000
	s_nop 0
	global_load_lds_dwordx4 v[138:139], off
	v_lshl_add_u64 v[138:139], v[222:223], 0, s[20:21]
	s_mov_b32 m0, s53
	s_nop 0
	global_load_lds_dwordx4 v[138:139], off
	v_lshl_add_u64 v[138:139], v[224:225], 0, s[20:21]
	s_mov_b32 m0, s54
	s_nop 0
	global_load_lds_dwordx4 v[138:139], off
	s_waitcnt vmcnt(8)
	s_waitcnt lgkmcnt(0)
	s_barrier
	s_setprio 1
	s_waitcnt lgkmcnt(0)
	v_mfma_f32_16x16x32_bf16 v[62:65], v[156:159], v[188:191], v[62:65]
	v_mfma_f32_16x16x32_bf16 v[58:61], v[164:167], v[188:191], v[58:61]
	v_mfma_f32_16x16x32_bf16 v[46:49], v[156:159], v[196:199], v[46:49]
	v_mfma_f32_16x16x32_bf16 v[42:45], v[164:167], v[196:199], v[42:45]
	v_mfma_f32_16x16x32_bf16 v[30:33], v[156:159], v[204:207], v[30:33]
	v_mfma_f32_16x16x32_bf16 v[26:29], v[164:167], v[204:207], v[26:29]
	v_mfma_f32_16x16x32_bf16 v[14:17], v[156:159], v[212:215], v[14:17]
	v_mfma_f32_16x16x32_bf16 v[10:13], v[164:167], v[212:215], v[10:13]
	v_mfma_f32_16x16x32_bf16 v[62:65], v[160:163], v[192:195], v[62:65]
	v_mfma_f32_16x16x32_bf16 v[58:61], v[168:171], v[192:195], v[58:61]
	v_mfma_f32_16x16x32_bf16 v[46:49], v[160:163], v[200:203], v[46:49]
	v_mfma_f32_16x16x32_bf16 v[42:45], v[168:171], v[200:203], v[42:45]
	v_mfma_f32_16x16x32_bf16 v[30:33], v[160:163], v[208:211], v[30:33]
	v_mfma_f32_16x16x32_bf16 v[26:29], v[168:171], v[208:211], v[26:29]
	v_mfma_f32_16x16x32_bf16 v[14:17], v[160:163], v[216:219], v[14:17]
	v_mfma_f32_16x16x32_bf16 v[10:13], v[168:171], v[216:219], v[10:13]
	v_mfma_f32_16x16x32_bf16 v[54:57], v[172:175], v[188:191], v[54:57]
	v_mfma_f32_16x16x32_bf16 v[50:53], v[180:183], v[188:191], v[50:53]
	v_mfma_f32_16x16x32_bf16 v[38:41], v[172:175], v[196:199], v[38:41]
	v_mfma_f32_16x16x32_bf16 v[34:37], v[180:183], v[196:199], v[34:37]
	v_mfma_f32_16x16x32_bf16 v[22:25], v[172:175], v[204:207], v[22:25]
	v_mfma_f32_16x16x32_bf16 v[18:21], v[180:183], v[204:207], v[18:21]
	v_mfma_f32_16x16x32_bf16 v[6:9], v[172:175], v[212:215], v[6:9]
	v_mfma_f32_16x16x32_bf16 v[2:5], v[180:183], v[212:215], v[2:5]
	v_mfma_f32_16x16x32_bf16 v[54:57], v[176:179], v[192:195], v[54:57]
	v_mfma_f32_16x16x32_bf16 v[50:53], v[184:187], v[192:195], v[50:53]
	v_mfma_f32_16x16x32_bf16 v[38:41], v[176:179], v[200:203], v[38:41]
	v_mfma_f32_16x16x32_bf16 v[34:37], v[184:187], v[200:203], v[34:37]
	v_mfma_f32_16x16x32_bf16 v[22:25], v[176:179], v[208:211], v[22:25]
	v_mfma_f32_16x16x32_bf16 v[18:21], v[184:187], v[208:211], v[18:21]
	v_mfma_f32_16x16x32_bf16 v[6:9], v[176:179], v[216:219], v[6:9]
	v_mfma_f32_16x16x32_bf16 v[2:5], v[184:187], v[216:219], v[2:5]
	s_setprio 0
	s_barrier
	s_add_i32 s63, s63, 2
	s_add_u32 s64, s64, 0x100
	s_addc_u32 s65, s65, 0
	s_add_u32 s66, s66, 0x100
	s_addc_u32 s67, s67, 0
	s_add_u32 s0, s0, 0xffffff00
	s_addc_u32 s1, s1, -1
	v_lshl_add_u64 v[142:143], v[142:143], 0, s[24:25]
	s_cmp_gt_u32 s63, 13
	v_lshl_add_u64 v[144:145], v[144:145], 0, s[24:25]
	s_cbranch_scc0 .LBB0_971
	s_add_u32 s0, s61, 0x40080
	s_addc_u32 s1, s37, 0
	s_mov_b32 m0, s69
	v_lshl_add_u64 v[138:139], s[0:1], 0, v[130:131]
	global_load_lds_dwordx4 v[138:139], off
	v_lshl_add_u64 v[138:139], s[0:1], 0, v[134:135]
	s_mov_b32 m0, s68
	s_and_b64 vcc, exec, s[22:23]
	global_load_lds_dwordx4 v[138:139], off
	s_cbranch_vccz .LBB0_974
	s_barrier

.LBB0_1051:
	ds_read_b128 v[128:131], v213
	ds_read_b128 v[132:135], v213 offset:1024
	ds_read_b128 v[136:139], v213 offset:2048
	ds_read_b128 v[140:143], v213 offset:3072
	ds_read_b128 v[144:147], v214
	ds_read_b128 v[148:151], v214 offset:1024
	ds_read_b128 v[152:155], v214 offset:2048
	ds_read_b128 v[156:159], v214 offset:3072
	s_add_u32 s6, s2, 0xfff00080
	s_addc_u32 s7, s3, -1
	s_cmp_eq_u32 s58, 60
	s_cselect_b32 s55, s5, s7
	s_cselect_b32 s54, s47, s6
	s_cselect_b32 s7, s45, s57
	s_cselect_b32 s6, s53, s56
	v_lshl_add_u64 v[208:209], s[2:3], 0, v[194:195]
	s_add_i32 m0, s65, 0xc000
	ds_read_b128 v[160:163], v215
	ds_read_b128 v[164:167], v215 offset:1024
	ds_read_b128 v[168:171], v215 offset:2048
	ds_read_b128 v[172:175], v215 offset:3072
	ds_read_b128 v[176:179], v215 offset:4096
	ds_read_b128 v[180:183], v215 offset:5120
	ds_read_b128 v[204:207], v215 offset:6144
	ds_read_b128 v[220:223], v215 offset:7168
	global_load_lds_dwordx4 v[208:209], off
	v_lshl_add_u64 v[208:209], s[2:3], 0, v[196:197]
	s_add_i32 m0, s65, 0xe000
	s_nop 0
	global_load_lds_dwordx4 v[208:209], off
	s_waitcnt vmcnt(8)
	s_waitcnt lgkmcnt(0)
	s_barrier
	s_setprio 1
	s_waitcnt lgkmcnt(0)
	v_mfma_f32_16x16x32_bf16 v[124:127], v[128:131], v[160:163], v[124:127]
	v_mfma_f32_16x16x32_bf16 v[120:123], v[136:139], v[160:163], v[120:123]
	v_mfma_f32_16x16x32_bf16 v[108:111], v[128:131], v[168:171], v[108:111]
	v_mfma_f32_16x16x32_bf16 v[104:107], v[136:139], v[168:171], v[104:107]
	v_mfma_f32_16x16x32_bf16 v[92:95], v[128:131], v[176:179], v[92:95]
	v_mfma_f32_16x16x32_bf16 v[88:91], v[136:139], v[176:179], v[88:91]
	v_mfma_f32_16x16x32_bf16 v[76:79], v[128:131], v[204:207], v[76:79]
	v_mfma_f32_16x16x32_bf16 v[72:75], v[136:139], v[204:207], v[72:75]
	v_mfma_f32_16x16x32_bf16 v[124:127], v[132:135], v[164:167], v[124:127]
	v_mfma_f32_16x16x32_bf16 v[120:123], v[140:143], v[164:167], v[120:123]
	v_mfma_f32_16x16x32_bf16 v[108:111], v[132:135], v[172:175], v[108:111]
	v_mfma_f32_16x16x32_bf16 v[104:107], v[140:143], v[172:175], v[104:107]
	v_mfma_f32_16x16x32_bf16 v[92:95], v[132:135], v[180:183], v[92:95]
	v_mfma_f32_16x16x32_bf16 v[88:91], v[140:143], v[180:183], v[88:91]
	v_mfma_f32_16x16x32_bf16 v[76:79], v[132:135], v[220:223], v[76:79]
	v_mfma_f32_16x16x32_bf16 v[72:75], v[140:143], v[220:223], v[72:75]
	v_mfma_f32_16x16x32_bf16 v[116:119], v[144:147], v[160:163], v[116:119]
	v_mfma_f32_16x16x32_bf16 v[112:115], v[152:155], v[160:163], v[112:115]
	v_mfma_f32_16x16x32_bf16 v[100:103], v[144:147], v[168:171], v[100:103]
	v_mfma_f32_16x16x32_bf16 v[96:99], v[152:155], v[168:171], v[96:99]
	v_mfma_f32_16x16x32_bf16 v[84:87], v[144:147], v[176:179], v[84:87]
	v_mfma_f32_16x16x32_bf16 v[80:83], v[152:155], v[176:179], v[80:83]
	v_mfma_f32_16x16x32_bf16 v[68:71], v[144:147], v[204:207], v[68:71]
	v_mfma_f32_16x16x32_bf16 v[64:67], v[152:155], v[204:207], v[64:67]
	v_mfma_f32_16x16x32_bf16 v[116:119], v[148:151], v[164:167], v[116:119]
	v_mfma_f32_16x16x32_bf16 v[112:115], v[156:159], v[164:167], v[112:115]
	v_mfma_f32_16x16x32_bf16 v[100:103], v[148:151], v[172:175], v[100:103]
	v_mfma_f32_16x16x32_bf16 v[96:99], v[156:159], v[172:175], v[96:99]
	v_mfma_f32_16x16x32_bf16 v[84:87], v[148:151], v[180:183], v[84:87]
	v_mfma_f32_16x16x32_bf16 v[80:83], v[156:159], v[180:183], v[80:83]
	v_mfma_f32_16x16x32_bf16 v[68:71], v[148:151], v[220:223], v[68:71]
	v_mfma_f32_16x16x32_bf16 v[64:67], v[156:159], v[220:223], v[64:67]
	s_setprio 0
	s_barrier
	s_add_i32 s59, s82, s64
	v_lshl_add_u64 v[208:209], s[6:7], 0, v[186:187]
	s_mov_b32 m0, s59
	ds_read_b128 v[160:163], v215 offset:16384
	ds_read_b128 v[164:167], v215 offset:17408
	ds_read_b128 v[168:171], v215 offset:18432
	ds_read_b128 v[172:175], v215 offset:19456
	ds_read_b128 v[176:179], v215 offset:20480
	ds_read_b128 v[180:183], v215 offset:21504
	ds_read_b128 v[204:207], v215 offset:22528
	ds_read_b128 v[220:223], v215 offset:23552
	global_load_lds_dwordx4 v[208:209], off
	s_add_i32 m0, s59, 0x2000
	s_add_u32 vcc_lo, s6, 0x100000
	v_lshl_add_u64 v[224:225], s[6:7], 0, v[190:191]
	s_addc_u32 vcc_hi, s7, 0
	s_add_i32 s59, s83, s64
	global_load_lds_dwordx4 v[224:225], off
	v_lshl_add_u64 v[226:227], vcc, 0, v[186:187]
	s_mov_b32 m0, s59
	v_lshl_add_u64 v[228:229], s[54:55], 0, v[188:189]
	global_load_lds_dwordx4 v[226:227], off
	v_lshl_add_u64 v[226:227], vcc, 0, v[190:191]
	s_add_i32 m0, s59, 0x2000
	s_nop 0
	global_load_lds_dwordx4 v[226:227], off
	v_lshl_add_u64 v[226:227], s[54:55], 0, v[184:185]
	s_mov_b32 m0, s65
	s_nop 0
	global_load_lds_dwordx4 v[226:227], off
	s_mov_b32 m0, s66
	s_nop 0
	global_load_lds_dwordx4 v[228:229], off
	s_waitcnt vmcnt(8)
	s_waitcnt lgkmcnt(0)
	s_barrier
	s_setprio 1
	s_waitcnt lgkmcnt(0)
	v_mfma_f32_16x16x32_bf16 v[60:63], v[128:131], v[160:163], v[60:63]
	v_mfma_f32_16x16x32_bf16 v[56:59], v[136:139], v[160:163], v[56:59]
	v_mfma_f32_16x16x32_bf16 v[44:47], v[128:131], v[168:171], v[44:47]
	v_mfma_f32_16x16x32_bf16 v[40:43], v[136:139], v[168:171], v[40:43]
	v_mfma_f32_16x16x32_bf16 v[28:31], v[128:131], v[176:179], v[28:31]
	v_mfma_f32_16x16x32_bf16 v[24:27], v[136:139], v[176:179], v[24:27]
	v_mfma_f32_16x16x32_bf16 v[12:15], v[128:131], v[204:207], v[12:15]
	v_mfma_f32_16x16x32_bf16 v[8:11], v[136:139], v[204:207], v[8:11]
	v_mfma_f32_16x16x32_bf16 v[60:63], v[132:135], v[164:167], v[60:63]
	v_mfma_f32_16x16x32_bf16 v[56:59], v[140:143], v[164:167], v[56:59]
	v_mfma_f32_16x16x32_bf16 v[44:47], v[132:135], v[172:175], v[44:47]
	v_mfma_f32_16x16x32_bf16 v[40:43], v[140:143], v[172:175], v[40:43]
	v_mfma_f32_16x16x32_bf16 v[28:31], v[132:135], v[180:183], v[28:31]
	v_mfma_f32_16x16x32_bf16 v[24:27], v[140:143], v[180:183], v[24:27]
	v_mfma_f32_16x16x32_bf16 v[12:15], v[132:135], v[220:223], v[12:15]
	v_mfma_f32_16x16x32_bf16 v[8:11], v[140:143], v[220:223], v[8:11]
	v_mfma_f32_16x16x32_bf16 v[52:55], v[144:147], v[160:163], v[52:55]
	v_mfma_f32_16x16x32_bf16 v[48:51], v[152:155], v[160:163], v[48:51]
	v_mfma_f32_16x16x32_bf16 v[36:39], v[144:147], v[168:171], v[36:39]
	v_mfma_f32_16x16x32_bf16 v[32:35], v[152:155], v[168:171], v[32:35]
	v_mfma_f32_16x16x32_bf16 v[20:23], v[144:147], v[176:179], v[20:23]
	v_mfma_f32_16x16x32_bf16 v[16:19], v[152:155], v[176:179], v[16:19]
	v_mfma_f32_16x16x32_bf16 v[4:7], v[144:147], v[204:207], v[4:7]
	v_mfma_f32_16x16x32_bf16 v[0:3], v[152:155], v[204:207], v[0:3]
	v_mfma_f32_16x16x32_bf16 v[52:55], v[148:151], v[164:167], v[52:55]
	v_mfma_f32_16x16x32_bf16 v[48:51], v[156:159], v[164:167], v[48:51]
	v_mfma_f32_16x16x32_bf16 v[36:39], v[148:151], v[172:175], v[36:39]
	v_mfma_f32_16x16x32_bf16 v[32:35], v[156:159], v[172:175], v[32:35]
	v_mfma_f32_16x16x32_bf16 v[20:23], v[148:151], v[180:183], v[20:23]
	v_mfma_f32_16x16x32_bf16 v[16:19], v[156:159], v[180:183], v[16:19]
	v_mfma_f32_16x16x32_bf16 v[4:7], v[148:151], v[220:223], v[4:7]
	v_mfma_f32_16x16x32_bf16 v[0:3], v[156:159], v[220:223], v[0:3]
	s_setprio 0
	s_barrier
	s_add_i32 s59, 0, 0x18000
	s_add_i32 vcc_lo, 0, 0x1c000
	v_add_u32_e32 v140, s59, v212
	v_add_u32_e32 v156, vcc_lo, v212
	ds_read_b128 v[128:131], v140
	ds_read_b128 v[132:135], v140 offset:1024
	ds_read_b128 v[136:139], v140 offset:2048
	ds_read_b128 v[140:143], v140 offset:3072
	ds_read_b128 v[144:147], v156
	ds_read_b128 v[148:151], v156 offset:1024
	ds_read_b128 v[152:155], v156 offset:2048
	ds_read_b128 v[156:159], v156 offset:3072
	s_add_u32 s54, s54, 0x100000
	s_addc_u32 s55, s55, 0
	s_mov_b32 m0, s67
	v_lshl_add_u64 v[230:231], s[54:55], 0, v[184:185]
	ds_read_b128 v[160:163], v215 offset:32768
	ds_read_b128 v[164:167], v215 offset:33792
	ds_read_b128 v[168:171], v215 offset:34816
	ds_read_b128 v[172:175], v215 offset:35840
	ds_read_b128 v[176:179], v215 offset:36864
	ds_read_b128 v[180:183], v215 offset:37888
	ds_read_b128 v[204:207], v215 offset:38912
	ds_read_b128 v[220:223], v215 offset:39936
	global_load_lds_dwordx4 v[230:231], off
	v_lshl_add_u64 v[230:231], s[54:55], 0, v[188:189]
	s_mov_b32 m0, s68
	s_nop 0
	global_load_lds_dwordx4 v[230:231], off
	s_waitcnt vmcnt(8)
	s_waitcnt lgkmcnt(0)
	s_barrier
	s_setprio 1
	s_waitcnt lgkmcnt(0)
	v_mfma_f32_16x16x32_bf16 v[124:127], v[128:131], v[160:163], v[124:127]
	v_mfma_f32_16x16x32_bf16 v[120:123], v[136:139], v[160:163], v[120:123]
	v_mfma_f32_16x16x32_bf16 v[108:111], v[128:131], v[168:171], v[108:111]
	v_mfma_f32_16x16x32_bf16 v[104:107], v[136:139], v[168:171], v[104:107]
	v_mfma_f32_16x16x32_bf16 v[92:95], v[128:131], v[176:179], v[92:95]
	v_mfma_f32_16x16x32_bf16 v[88:91], v[136:139], v[176:179], v[88:91]
	v_mfma_f32_16x16x32_bf16 v[76:79], v[128:131], v[204:207], v[76:79]
	v_mfma_f32_16x16x32_bf16 v[72:75], v[136:139], v[204:207], v[72:75]
	v_mfma_f32_16x16x32_bf16 v[124:127], v[132:135], v[164:167], v[124:127]
	v_mfma_f32_16x16x32_bf16 v[120:123], v[140:143], v[164:167], v[120:123]
	v_mfma_f32_16x16x32_bf16 v[108:111], v[132:135], v[172:175], v[108:111]
	v_mfma_f32_16x16x32_bf16 v[104:107], v[140:143], v[172:175], v[104:107]
	v_mfma_f32_16x16x32_bf16 v[92:95], v[132:135], v[180:183], v[92:95]
	v_mfma_f32_16x16x32_bf16 v[88:91], v[140:143], v[180:183], v[88:91]
	v_mfma_f32_16x16x32_bf16 v[76:79], v[132:135], v[220:223], v[76:79]
	v_mfma_f32_16x16x32_bf16 v[72:75], v[140:143], v[220:223], v[72:75]
	v_mfma_f32_16x16x32_bf16 v[116:119], v[144:147], v[160:163], v[116:119]
	v_mfma_f32_16x16x32_bf16 v[112:115], v[152:155], v[160:163], v[112:115]
	v_mfma_f32_16x16x32_bf16 v[100:103], v[144:147], v[168:171], v[100:103]
	v_mfma_f32_16x16x32_bf16 v[96:99], v[152:155], v[168:171], v[96:99]
	v_mfma_f32_16x16x32_bf16 v[84:87], v[144:147], v[176:179], v[84:87]
	v_mfma_f32_16x16x32_bf16 v[80:83], v[152:155], v[176:179], v[80:83]
	v_mfma_f32_16x16x32_bf16 v[68:71], v[144:147], v[204:207], v[68:71]
	v_mfma_f32_16x16x32_bf16 v[64:67], v[152:155], v[204:207], v[64:67]
	v_mfma_f32_16x16x32_bf16 v[116:119], v[148:151], v[164:167], v[116:119]
	v_mfma_f32_16x16x32_bf16 v[112:115], v[156:159], v[164:167], v[112:115]
	v_mfma_f32_16x16x32_bf16 v[100:103], v[148:151], v[172:175], v[100:103]
	v_mfma_f32_16x16x32_bf16 v[96:99], v[156:159], v[172:175], v[96:99]
	v_mfma_f32_16x16x32_bf16 v[84:87], v[148:151], v[180:183], v[84:87]
	v_mfma_f32_16x16x32_bf16 v[80:83], v[156:159], v[180:183], v[80:83]
	v_mfma_f32_16x16x32_bf16 v[68:71], v[148:151], v[220:223], v[68:71]
	v_mfma_f32_16x16x32_bf16 v[64:67], v[156:159], v[220:223], v[64:67]
	s_setprio 0
	s_barrier
	s_add_i32 s54, s59, s64
	v_lshl_add_u64 v[208:209], v[208:209], 0, s[18:19]
	s_mov_b32 m0, s54
	ds_read_b128 v[160:163], v215 offset:49152
	ds_read_b128 v[164:167], v215 offset:50176
	ds_read_b128 v[168:171], v215 offset:51200
	ds_read_b128 v[172:175], v215 offset:52224
	ds_read_b128 v[176:179], v215 offset:53248
	ds_read_b128 v[180:183], v215 offset:54272
	ds_read_b128 v[204:207], v215 offset:55296
	ds_read_b128 v[220:223], v215 offset:56320
	global_load_lds_dwordx4 v[208:209], off
	s_add_i32 m0, s54, 0x2000
	s_add_u32 s6, s6, 0x100080
	v_lshl_add_u64 v[208:209], v[224:225], 0, s[18:19]
	s_addc_u32 s7, s7, 0
	s_add_i32 s54, vcc_lo, s64
	global_load_lds_dwordx4 v[208:209], off
	v_lshl_add_u64 v[208:209], s[6:7], 0, v[186:187]
	s_mov_b32 m0, s54
	s_nop 0
	global_load_lds_dwordx4 v[208:209], off
	v_lshl_add_u64 v[208:209], s[6:7], 0, v[190:191]
	s_add_i32 m0, s54, 0x2000
	s_nop 0
	global_load_lds_dwordx4 v[208:209], off
	v_lshl_add_u64 v[208:209], v[226:227], 0, s[18:19]
	s_mov_b32 m0, s74
	s_nop 0
	global_load_lds_dwordx4 v[208:209], off
	v_lshl_add_u64 v[208:209], v[228:229], 0, s[18:19]
	s_mov_b32 m0, s75
	s_nop 0
	global_load_lds_dwordx4 v[208:209], off
	s_waitcnt vmcnt(8)
	s_waitcnt lgkmcnt(0)
	s_barrier
	s_setprio 1
	s_waitcnt lgkmcnt(0)
	v_mfma_f32_16x16x32_bf16 v[60:63], v[128:131], v[160:163], v[60:63]
	v_mfma_f32_16x16x32_bf16 v[56:59], v[136:139], v[160:163], v[56:59]
	v_mfma_f32_16x16x32_bf16 v[44:47], v[128:131], v[168:171], v[44:47]
	v_mfma_f32_16x16x32_bf16 v[40:43], v[136:139], v[168:171], v[40:43]
	v_mfma_f32_16x16x32_bf16 v[28:31], v[128:131], v[176:179], v[28:31]
	v_mfma_f32_16x16x32_bf16 v[24:27], v[136:139], v[176:179], v[24:27]
	v_mfma_f32_16x16x32_bf16 v[12:15], v[128:131], v[204:207], v[12:15]
	v_mfma_f32_16x16x32_bf16 v[8:11], v[136:139], v[204:207], v[8:11]
	v_mfma_f32_16x16x32_bf16 v[60:63], v[132:135], v[164:167], v[60:63]
	v_mfma_f32_16x16x32_bf16 v[56:59], v[140:143], v[164:167], v[56:59]
	v_mfma_f32_16x16x32_bf16 v[44:47], v[132:135], v[172:175], v[44:47]
	v_mfma_f32_16x16x32_bf16 v[40:43], v[140:143], v[172:175], v[40:43]
	v_mfma_f32_16x16x32_bf16 v[28:31], v[132:135], v[180:183], v[28:31]
	v_mfma_f32_16x16x32_bf16 v[24:27], v[140:143], v[180:183], v[24:27]
	v_mfma_f32_16x16x32_bf16 v[12:15], v[132:135], v[220:223], v[12:15]
	v_mfma_f32_16x16x32_bf16 v[8:11], v[140:143], v[220:223], v[8:11]
	v_mfma_f32_16x16x32_bf16 v[52:55], v[144:147], v[160:163], v[52:55]
	v_mfma_f32_16x16x32_bf16 v[48:51], v[152:155], v[160:163], v[48:51]
	v_mfma_f32_16x16x32_bf16 v[36:39], v[144:147], v[168:171], v[36:39]
	v_mfma_f32_16x16x32_bf16 v[32:35], v[152:155], v[168:171], v[32:35]
	v_mfma_f32_16x16x32_bf16 v[20:23], v[144:147], v[176:179], v[20:23]
	v_mfma_f32_16x16x32_bf16 v[16:19], v[152:155], v[176:179], v[16:19]
	v_mfma_f32_16x16x32_bf16 v[4:7], v[144:147], v[204:207], v[4:7]
	v_mfma_f32_16x16x32_bf16 v[0:3], v[152:155], v[204:207], v[0:3]
	v_mfma_f32_16x16x32_bf16 v[52:55], v[148:151], v[164:167], v[52:55]
	v_mfma_f32_16x16x32_bf16 v[48:51], v[156:159], v[164:167], v[48:51]
	v_mfma_f32_16x16x32_bf16 v[36:39], v[148:151], v[172:175], v[36:39]
	v_mfma_f32_16x16x32_bf16 v[32:35], v[156:159], v[172:175], v[32:35]
	v_mfma_f32_16x16x32_bf16 v[20:23], v[148:151], v[180:183], v[20:23]
	v_mfma_f32_16x16x32_bf16 v[16:19], v[156:159], v[180:183], v[16:19]
	v_mfma_f32_16x16x32_bf16 v[4:7], v[148:151], v[220:223], v[4:7]
	v_mfma_f32_16x16x32_bf16 v[0:3], v[156:159], v[220:223], v[0:3]
	s_setprio 0
	s_barrier
	s_add_i32 s58, s58, 2
	s_add_u32 s2, s2, 0x100
	s_addc_u32 s3, s3, 0
	s_add_u32 s56, s56, 0x100
	s_addc_u32 s57, s57, 0
	s_cmp_gt_u32 s58, 61
	s_cbranch_scc0 .LBB0_1051
	s_and_b64 vcc, exec, s[20:21]
	s_cbranch_vccz .LBB0_1054
	s_barrier
